# E47: agent-scope write-through (sc1) on every 16-byte store so the barrier release write-back finds little dirty data in L2
# baseline (speedup 1.0000x reference)
; DI void transpose_item(const float* W, int ldw, int k0, int n, bf16_t* WT, int Kd, int dst_row, const float* kscale) {
;     float v[64];
; #pragma unroll
;     for (int i = 0; i < 64; ++i) v[i] = W[(size_t)(k0 + i) * ldw + n];
; DI void prologue(KArgs ap, int gw, int NGW, int lane) {
;     ...
;     for (int it = gw; it < 16 * 36; it += NGW) { const int kb = it / 36, hh = it % 36, bj = lane >> 5, x = lane & 31;
;         transpose_item(w_in, NIN, 64 * kb, 64 * hh + lane, (bf16_t*)(ws + WS_WIN), DM, 256 * (hh >> 2) + 128 * bj + 32 * (hh & 3) + x, nullptr); }
.LBB0_35:
	s_mul_hi_i32 s20, s24, 0x38e38e39
	s_lshr_b32 s21, s20, 31
	s_ashr_i32 s20, s20, 3
	s_add_i32 s21, s20, s21
	s_lshl_b32 s20, s21, 6
	s_mulk_i32 s21, 0xf700
	s_add_i32 s25, s5, s21
	v_add_u32_e32 v4, s25, v190
	v_ashrrev_i32_e32 v5, 31, v4
	s_or_b32 s21, s20, 1
	s_or_b32 s26, s20, 2
	s_or_b32 s27, s20, 3
	s_or_b32 s28, s20, 4
	s_or_b32 s29, s20, 5
	s_or_b32 s30, s20, 6
	s_or_b32 s31, s20, 7
	s_or_b32 s33, s20, 8
	s_or_b32 s34, s20, 9
	s_or_b32 s35, s20, 10
	s_or_b32 s42, s20, 11
	s_or_b32 s43, s20, 12
	s_or_b32 s44, s20, 13
	s_or_b32 s45, s20, 14
	s_or_b32 s47, s20, 16
	s_or_b32 s48, s20, 17
	s_or_b32 s49, s20, 18
	s_or_b32 s50, s20, 19
	s_or_b32 s51, s20, 20
	s_or_b32 s52, s20, 21
	s_or_b32 s53, s20, 22
	s_or_b32 s54, s20, 23
	s_or_b32 s55, s20, 24
	s_or_b32 s56, s20, 25
	s_or_b32 s57, s20, 26
	s_or_b32 s58, s20, 27
	s_or_b32 s59, s20, 28
	s_or_b32 s61, s20, 29
	s_or_b32 s62, s20, 30
	s_or_b32 s63, s20, 31
	s_or_b32 s64, s20, 32
	v_lshl_add_u64 v[4:5], v[4:5], 2, s[14:15]
	s_or_b32 s46, s20, 15
	s_or_b32 s65, s20, 33
	s_or_b32 s66, s20, 34
	s_or_b32 s67, s20, 35
	s_or_b32 s68, s20, 36
	s_or_b32 s69, s20, 37
	s_or_b32 s70, s20, 38
	s_or_b32 s71, s20, 39
	s_or_b32 s72, s20, 40
	s_or_b32 s73, s20, 41
	s_or_b32 s74, s20, 42
	s_or_b32 s75, s20, 43
	s_or_b32 s76, s20, 44
	s_or_b32 s77, s20, 45
	s_or_b32 s78, s20, 46
	s_or_b32 s79, s20, 47
	s_or_b32 s80, s20, 48
	s_or_b32 s81, s20, 49
	s_or_b32 s82, s20, 50
	s_or_b32 s83, s20, 51
	s_or_b32 s84, s20, 52
	s_or_b32 s85, s20, 53
	s_or_b32 s88, s20, 54
	s_or_b32 s89, s20, 55
	s_or_b32 s90, s20, 56
	s_or_b32 s91, s20, 57
	s_or_b32 s92, s20, 58
	s_or_b32 s93, s20, 59
	s_or_b32 s94, s20, 60
	s_or_b32 s95, s20, 61
	s_or_b32 s96, s20, 62
	s_or_b32 s97, s20, 63
	v_mad_i64_i32 v[6:7], s[86:87], s20, v2, v[4:5]
	v_mad_i64_i32 v[8:9], s[86:87], s21, v2, v[4:5]
	v_mad_i64_i32 v[10:11], s[86:87], s26, v2, v[4:5]
	v_mad_i64_i32 v[12:13], s[26:27], s27, v2, v[4:5]
	v_mad_i64_i32 v[14:15], s[26:27], s28, v2, v[4:5]
	v_mad_i64_i32 v[16:17], s[26:27], s29, v2, v[4:5]
	v_mad_i64_i32 v[18:19], s[26:27], s30, v2, v[4:5]
	v_mad_i64_i32 v[20:21], s[26:27], s31, v2, v[4:5]
	v_mad_i64_i32 v[22:23], s[26:27], s33, v2, v[4:5]
	v_mad_i64_i32 v[24:25], s[26:27], s34, v2, v[4:5]
	v_mad_i64_i32 v[26:27], s[26:27], s35, v2, v[4:5]
	v_mad_i64_i32 v[28:29], s[26:27], s42, v2, v[4:5]
	v_mad_i64_i32 v[30:31], s[26:27], s43, v2, v[4:5]
	v_mad_i64_i32 v[32:33], s[26:27], s44, v2, v[4:5]
	v_mad_i64_i32 v[34:35], s[26:27], s45, v2, v[4:5]
	v_mad_i64_i32 v[38:39], s[26:27], s47, v2, v[4:5]
	v_mad_i64_i32 v[40:41], s[26:27], s48, v2, v[4:5]
	v_mad_i64_i32 v[42:43], s[26:27], s49, v2, v[4:5]
	v_mad_i64_i32 v[44:45], s[26:27], s50, v2, v[4:5]
	v_mad_i64_i32 v[46:47], s[26:27], s51, v2, v[4:5]
	v_mad_i64_i32 v[48:49], s[26:27], s52, v2, v[4:5]
	v_mad_i64_i32 v[50:51], s[26:27], s53, v2, v[4:5]
	v_mad_i64_i32 v[52:53], s[26:27], s54, v2, v[4:5]
	v_mad_i64_i32 v[54:55], s[26:27], s55, v2, v[4:5]
	v_mad_i64_i32 v[56:57], s[26:27], s56, v2, v[4:5]
	v_mad_i64_i32 v[58:59], s[26:27], s57, v2, v[4:5]
	v_mad_i64_i32 v[60:61], s[26:27], s58, v2, v[4:5]
	v_mad_i64_i32 v[62:63], s[26:27], s59, v2, v[4:5]
	v_mad_i64_i32 v[64:65], s[26:27], s61, v2, v[4:5]
	v_mad_i64_i32 v[66:67], s[26:27], s62, v2, v[4:5]
	v_mad_i64_i32 v[68:69], s[26:27], s63, v2, v[4:5]
	v_mad_i64_i32 v[70:71], s[26:27], s64, v2, v[4:5]
	v_mad_i64_i32 v[36:37], s[26:27], s46, v2, v[4:5]
	v_mad_i64_i32 v[72:73], s[26:27], s65, v2, v[4:5]
	v_mad_i64_i32 v[74:75], s[26:27], s66, v2, v[4:5]
	v_mad_i64_i32 v[76:77], s[26:27], s67, v2, v[4:5]
	v_mad_i64_i32 v[78:79], s[26:27], s68, v2, v[4:5]
	v_mad_i64_i32 v[80:81], s[26:27], s69, v2, v[4:5]
	v_mad_i64_i32 v[82:83], s[26:27], s70, v2, v[4:5]
	v_mad_i64_i32 v[84:85], s[26:27], s71, v2, v[4:5]
	v_mad_i64_i32 v[86:87], s[26:27], s72, v2, v[4:5]
	v_mad_i64_i32 v[88:89], s[26:27], s73, v2, v[4:5]
	v_mad_i64_i32 v[90:91], s[26:27], s74, v2, v[4:5]
	v_mad_i64_i32 v[92:93], s[26:27], s75, v2, v[4:5]
	v_mad_i64_i32 v[94:95], s[26:27], s76, v2, v[4:5]
	v_mad_i64_i32 v[96:97], s[26:27], s77, v2, v[4:5]
	v_mad_i64_i32 v[98:99], s[26:27], s78, v2, v[4:5]
	v_mad_i64_i32 v[100:101], s[26:27], s79, v2, v[4:5]
	v_mad_i64_i32 v[102:103], s[26:27], s80, v2, v[4:5]
	v_mad_i64_i32 v[104:105], s[26:27], s81, v2, v[4:5]
	v_mad_i64_i32 v[106:107], s[26:27], s82, v2, v[4:5]
	v_mad_i64_i32 v[108:109], s[26:27], s83, v2, v[4:5]
	v_mad_i64_i32 v[110:111], s[26:27], s84, v2, v[4:5]
	v_mad_i64_i32 v[112:113], s[26:27], s85, v2, v[4:5]
	v_mad_i64_i32 v[114:115], s[26:27], s88, v2, v[4:5]
	v_mad_i64_i32 v[116:117], s[26:27], s89, v2, v[4:5]
	v_mad_i64_i32 v[118:119], s[26:27], s90, v2, v[4:5]
	v_mad_i64_i32 v[120:121], s[26:27], s91, v2, v[4:5]
	v_mad_i64_i32 v[122:123], s[26:27], s92, v2, v[4:5]
	v_mad_i64_i32 v[124:125], s[26:27], s93, v2, v[4:5]
	v_mad_i64_i32 v[126:127], s[26:27], s94, v2, v[4:5]
	v_mad_i64_i32 v[128:129], s[26:27], s95, v2, v[4:5]
	v_mad_i64_i32 v[130:131], s[26:27], s96, v2, v[4:5]
	v_mad_i64_i32 v[4:5], s[26:27], s97, v2, v[4:5]
	global_load_dword v3, v[6:7], off
; DI void transpose_item(const float* W, int ldw, int k0, int n, bf16_t* WT, int Kd, int dst_row, const float* kscale) {
;     float v[64];
; #pragma unroll
;     for (int i = 0; i < 64; ++i) v[i] = W[(size_t)(k0 + i) * ldw + n];
;     if (kscale) {
; #pragma unroll
;         for (int i = 0; i < 64; ++i) v[i] *= kscale[k0 + i];
;     }
;     bf16_t* d = WT + (size_t)dst_row * Kd + k0;
; #pragma unroll
;     for (int c = 0; c < 8; ++c) { u32x4 o; o.x = pk2(v[8 * c], v[8 * c + 1]); o.y = pk2(v[8 * c + 2], v[8 * c + 3]); o.z = pk2(v[8 * c + 4], v[8 * c + 5]); o.w = pk2(v[8 * c + 6], v[8 * c + 7]);
;         *(u32x4*)(d + 8 * c) = o; }
	s_nop 0
	global_load_dword v6, v[8:9], off
	global_load_dword v7, v[10:11], off
	s_nop 0
	global_load_dword v8, v[12:13], off
	global_load_dword v9, v[14:15], off
	global_load_dword v10, v[16:17], off
	global_load_dword v11, v[18:19], off
	s_nop 0
	global_load_dword v12, v[20:21], off
	global_load_dword v13, v[22:23], off
	global_load_dword v14, v[24:25], off
	global_load_dword v15, v[26:27], off
	global_load_dword v16, v[28:29], off
	global_load_dword v17, v[30:31], off
	global_load_dword v18, v[32:33], off
	global_load_dword v19, v[34:35], off
	global_load_dword v20, v[36:37], off
	global_load_dword v21, v[38:39], off
	global_load_dword v22, v[40:41], off
	global_load_dword v23, v[42:43], off
	global_load_dword v24, v[44:45], off
	global_load_dword v25, v[46:47], off
	global_load_dword v26, v[48:49], off
	global_load_dword v27, v[50:51], off
	global_load_dword v28, v[52:53], off
	global_load_dword v29, v[54:55], off
	global_load_dword v30, v[56:57], off
	global_load_dword v31, v[58:59], off
	global_load_dword v32, v[60:61], off
	global_load_dword v33, v[62:63], off
	global_load_dword v34, v[64:65], off
	global_load_dword v35, v[66:67], off
	global_load_dword v38, v[68:69], off
	global_load_dword v39, v[70:71], off
	global_load_dword v40, v[72:73], off
	global_load_dword v41, v[74:75], off
	global_load_dword v42, v[76:77], off
	global_load_dword v43, v[78:79], off
	global_load_dword v44, v[80:81], off
	global_load_dword v45, v[82:83], off
	global_load_dword v46, v[84:85], off
	global_load_dword v47, v[86:87], off
	global_load_dword v48, v[88:89], off
	global_load_dword v49, v[90:91], off
	global_load_dword v50, v[92:93], off
	global_load_dword v51, v[94:95], off
	global_load_dword v52, v[96:97], off
	global_load_dword v53, v[98:99], off
	global_load_dword v54, v[100:101], off
	global_load_dword v55, v[102:103], off
	global_load_dword v56, v[104:105], off
	global_load_dword v57, v[106:107], off
	global_load_dword v58, v[108:109], off
	global_load_dword v59, v[110:111], off
	global_load_dword v60, v[112:113], off
	global_load_dword v61, v[114:115], off
	global_load_dword v62, v[116:117], off
	global_load_dword v63, v[118:119], off
	global_load_dword v64, v[120:121], off
	global_load_dword v65, v[122:123], off
	global_load_dword v66, v[124:125], off
	global_load_dword v67, v[126:127], off
	global_load_dword v68, v[128:129], off
	global_load_dword v69, v[130:131], off
	global_load_dword v70, v[4:5], off
	s_and_b32 s25, s25, 0xffffff00
	s_and_b32 s26, s22, 0x60
	v_or_b32_e32 v4, s25, v0
	v_or3_b32 v4, v4, s26, v1
	v_ashrrev_i32_e32 v5, 31, v4
	v_lshlrev_b64 v[4:5], 11, v[4:5]
	s_add_i32 s24, s24, s4
	s_add_i32 s22, s22, s23
	s_ashr_i32 s21, s20, 31
	s_add_i32 s5, s5, s7
	v_lshl_add_u64 v[4:5], s[18:19], 0, v[4:5]
	s_cmpk_gt_i32 s24, 0x23f
	v_lshl_add_u64 v[36:37], s[20:21], 1, v[4:5]
	s_waitcnt vmcnt(62)
	v_cvt_pk_bf16_f32 v4, v3, v6
	s_waitcnt vmcnt(60)
	v_cvt_pk_bf16_f32 v5, v7, v8
	s_waitcnt vmcnt(58)
	v_cvt_pk_bf16_f32 v6, v9, v10
	s_waitcnt vmcnt(56)
	v_cvt_pk_bf16_f32 v7, v11, v12
	s_waitcnt vmcnt(54)
	v_cvt_pk_bf16_f32 v8, v13, v14
	s_waitcnt vmcnt(52)
	v_cvt_pk_bf16_f32 v9, v15, v16
	s_waitcnt vmcnt(50)
	v_cvt_pk_bf16_f32 v10, v17, v18
	s_waitcnt vmcnt(48)
	v_cvt_pk_bf16_f32 v11, v19, v20
	s_waitcnt vmcnt(46)
	v_cvt_pk_bf16_f32 v12, v21, v22
	s_waitcnt vmcnt(44)
	v_cvt_pk_bf16_f32 v13, v23, v24
	s_waitcnt vmcnt(42)
	v_cvt_pk_bf16_f32 v14, v25, v26
	s_waitcnt vmcnt(40)
	v_cvt_pk_bf16_f32 v15, v27, v28
	s_waitcnt vmcnt(38)
	v_cvt_pk_bf16_f32 v16, v29, v30
	s_waitcnt vmcnt(36)
	v_cvt_pk_bf16_f32 v17, v31, v32
	s_waitcnt vmcnt(34)
	v_cvt_pk_bf16_f32 v18, v33, v34
	s_waitcnt vmcnt(32)
	v_cvt_pk_bf16_f32 v19, v35, v38
	s_waitcnt vmcnt(30)
	v_cvt_pk_bf16_f32 v20, v39, v40
	s_waitcnt vmcnt(28)
	v_cvt_pk_bf16_f32 v21, v41, v42
	s_waitcnt vmcnt(26)
	v_cvt_pk_bf16_f32 v22, v43, v44
	s_waitcnt vmcnt(24)
	v_cvt_pk_bf16_f32 v23, v45, v46
	s_waitcnt vmcnt(22)
	v_cvt_pk_bf16_f32 v24, v47, v48
	s_waitcnt vmcnt(20)
	v_cvt_pk_bf16_f32 v25, v49, v50
	s_waitcnt vmcnt(18)
	v_cvt_pk_bf16_f32 v26, v51, v52
	s_waitcnt vmcnt(16)
	v_cvt_pk_bf16_f32 v27, v53, v54
	s_waitcnt vmcnt(14)
	v_cvt_pk_bf16_f32 v28, v55, v56
	s_waitcnt vmcnt(12)
	v_cvt_pk_bf16_f32 v29, v57, v58
	s_waitcnt vmcnt(10)
	v_cvt_pk_bf16_f32 v30, v59, v60
	s_waitcnt vmcnt(8)
	v_cvt_pk_bf16_f32 v31, v61, v62
	s_waitcnt vmcnt(6)
	v_cvt_pk_bf16_f32 v32, v63, v64
	s_waitcnt vmcnt(4)
	v_cvt_pk_bf16_f32 v33, v65, v66
	s_waitcnt vmcnt(2)
	v_cvt_pk_bf16_f32 v34, v67, v68
	s_waitcnt vmcnt(0)
	v_cvt_pk_bf16_f32 v35, v69, v70
	global_store_dwordx4 v[36:37], v[4:7], off sc1
	global_store_dwordx4 v[36:37], v[8:11], off offset:16 sc1
	global_store_dwordx4 v[36:37], v[12:15], off offset:32 sc1
	global_store_dwordx4 v[36:37], v[16:19], off offset:48 sc1
	global_store_dwordx4 v[36:37], v[20:23], off offset:64 sc1
	global_store_dwordx4 v[36:37], v[24:27], off offset:80 sc1
	global_store_dwordx4 v[36:37], v[28:31], off offset:96 sc1
	global_store_dwordx4 v[36:37], v[32:35], off offset:112 sc1
	s_cbranch_scc0 .LBB0_35

; DI size_t kf_off(int h, int nblk, int krow, int d) { return ((((size_t)h * nblk + (krow >> 5)) * 4 + (d >> 4)) * 64 + ((d >> 3) & 1) * 32 + (krow & 31)) * 8 + (d & 7); }
; DI u32x2 pk4(f32x4 v) { u32x2 r; r.x = pk2(v[0], v[1]); r.y = pk2(v[2], v[3]); return r; }
;     DI void operator()(const AccT& acc, const Unit& u, int wr, int wc, int fr, int fq, LAS unsigned char*) const {
;     ...
;                     const int krow = row < SEQ ? row : SEQ + (srow >> 6) * band + past + (srow & 63);
;                     const int krows = isA ? KA_ROWS : KB_ROWS;
;                     float* op = nullptr;
;                     size_t ooff = 0; bool has_o = false;
;                     if (row >= SEQ) { ooff = (isA ? (isK ? OFF_AKS : OFF_AVS) : (isK ? OFF_BKS : OFF_BVS)) + ((size_t)srow * nh + h) * 64; has_o = true; }
;                     else if (row >= SEQ - past) { ooff = (isA ? (isK ? OFF_AKP : OFF_AVP) : (isK ? OFF_BKP : OFF_BVP)) + ((size_t)(row - (SEQ - past)) * nh + h) * 64; has_o = true; }
;                     op = out + ooff;
;                     if (has_o) {
; #pragma unroll
;                         for (int bj = 0; bj < 2; ++bj)
; #pragma unroll
;                             for (int n = 0; n < 2; ++n) *(f32x4*)(op + 32 * bj + 16 * n + 4 * fq) = v[bj][n];
;                     }
;                     if (isK) {
;                         bf16_t* kp = (bf16_t*)(ws + (isA ? WS_KA : WS_KB));
; #pragma unroll
;                         for (int bj = 0; bj < 2; ++bj)
; #pragma unroll
;                             for (int n = 0; n < 2; ++n) *(u32x2*)(kp + kf_off(h, krows >> 5, krow, 32 * bj + 16 * n + 4 * fq)) = pk4(v[bj][n]);
;                     } else {
;                         bf16_t* vp = (bf16_t*)(ws + (isA ? WS_VTA : WS_VTB));
; #pragma unroll
;                         for (int bj = 0; bj < 2; ++bj)
; #pragma unroll
;                             for (int n = 0; n < 2; ++n)
; #pragma unroll
;                                 for (int j = 0; j < 4; ++j) {
;                                     const float mine = v[bj][n][j], oth = __shfl_xor(mine, 1);
;                                     if (!(fr & 1)) *(unsigned*)(vp + vf_off(h, krows >> 5, krow, 32 * bj + 16 * n + 4 * fq + j)) = pk2(mine, oth);
;                                 }
.LBB0_140:
	s_or_b64 exec, exec, s[10:11]
	s_and_saveexec_b64 s[10:11], s[54:55]
	s_cbranch_execz .LBB0_142
	v_lshlrev_b64 v[186:187], s92, v[150:151]
	v_lshl_add_u64 v[186:187], v[186:187], 0, s[44:45]
	v_lshlrev_b64 v[186:187], 8, v[186:187]
	v_lshl_add_u64 v[186:187], s[16:17], 0, v[186:187]
	v_lshlrev_b32_e32 v150, 2, v184
	v_lshl_add_u64 v[184:185], v[186:187], 0, v[150:151]
	v_lshlrev_b32_e32 v150, 2, v152
	v_lshl_add_u64 v[184:185], v[184:185], 0, v[150:151]
	global_store_dwordx4 v[184:185], v[140:143], off sc1
	global_store_dwordx4 v[184:185], v[136:139], off offset:64 sc1
	global_store_dwordx4 v[184:185], v[132:135], off offset:128 sc1
	global_store_dwordx4 v[184:185], v[128:131], off offset:192 sc1
.LBB0_142:
	s_or_b64 exec, exec, s[10:11]
	v_lshrrev_b32_e32 v183, 6, v183
	v_or_b32_e32 v150, s90, v167
	v_mad_u64_u32 v[184:185], s[10:11], s31, v183, v[150:151]
	v_cmp_gt_i32_e32 vcc, s68, v182
	s_mov_b64 s[10:11], -1
	s_nop 0
	v_cndmask_b32_e32 v183, v184, v182, vcc
	v_ashrrev_i32_e32 v184, 5, v183
	s_and_b64 vcc, exec, s[50:51]
	v_ashrrev_i32_e32 v185, 31, v184
	s_cbranch_vccz .LBB0_176
	v_readfirstlane_b32 s58, v183
	v_and_b32_e32 v150, 15, v198
	v_lshrrev_b32_e32 v186, 4, v198
	v_bfe_u32 v187, v150, 2, 1
	v_lshrrev_b32_e32 v188, 3, v150
	v_and_b32_e32 v150, 3, v150
	v_lshl_add_u32 v150, v188, 2, v150
	v_lshl_add_u32 v186, v187, 3, v186
	v_lshlrev_b32_e32 v186, 6, v186
	v_lshl_add_u32 v186, v150, 1, v186
	s_add_i32 s59, s64, 0xc000
	v_add_u32_e32 v186, s59, v186
	v_lshlrev_b32_e32 v188, 4, v198
	v_add_u32_e32 v187, s59, v188
	s_lshr_b32 s56, s58, 5
	s_add_u32 s56, s56, s46
	s_lshl_b32 s56, s56, 12
	s_and_b32 s57, s58, 16
	s_lshl_b32 s57, s57, 6
	s_add_u32 s56, s56, s57
	s_add_u32 s56, s56, s91
	s_add_u32 s56, s36, s56
	s_addc_u32 s57, s37, 0
	v_mov_b32_dpp v189, v140 quad_perm:[1,0,3,2] row_mask:0xf bank_mask:0xf
	v_mov_b32_dpp v199, v141 quad_perm:[1,0,3,2] row_mask:0xf bank_mask:0xf
	v_cvt_pk_bf16_f32 v140, v140, v189
	v_mov_b32_dpp v189, v142 quad_perm:[1,0,3,2] row_mask:0xf bank_mask:0xf
	v_cvt_pk_bf16_f32 v141, v141, v199
	v_mov_b32_dpp v199, v143 quad_perm:[1,0,3,2] row_mask:0xf bank_mask:0xf
	v_cvt_pk_bf16_f32 v142, v142, v189
	v_mov_b32_dpp v189, v136 quad_perm:[1,0,3,2] row_mask:0xf bank_mask:0xf
	v_cvt_pk_bf16_f32 v143, v143, v199
	v_mov_b32_dpp v199, v137 quad_perm:[1,0,3,2] row_mask:0xf bank_mask:0xf
	v_cvt_pk_bf16_f32 v136, v136, v189
	v_mov_b32_dpp v189, v138 quad_perm:[1,0,3,2] row_mask:0xf bank_mask:0xf
	v_cvt_pk_bf16_f32 v137, v137, v199
	v_mov_b32_dpp v199, v139 quad_perm:[1,0,3,2] row_mask:0xf bank_mask:0xf
	v_cvt_pk_bf16_f32 v138, v138, v189
	v_mov_b32_dpp v189, v132 quad_perm:[1,0,3,2] row_mask:0xf bank_mask:0xf
	v_cvt_pk_bf16_f32 v139, v139, v199
	v_mov_b32_dpp v199, v133 quad_perm:[1,0,3,2] row_mask:0xf bank_mask:0xf
	v_cvt_pk_bf16_f32 v132, v132, v189
	v_mov_b32_dpp v189, v134 quad_perm:[1,0,3,2] row_mask:0xf bank_mask:0xf
	v_cvt_pk_bf16_f32 v133, v133, v199
	v_mov_b32_dpp v199, v135 quad_perm:[1,0,3,2] row_mask:0xf bank_mask:0xf
	v_cvt_pk_bf16_f32 v134, v134, v189
	v_mov_b32_dpp v189, v128 quad_perm:[1,0,3,2] row_mask:0xf bank_mask:0xf
	v_cvt_pk_bf16_f32 v135, v135, v199
	v_mov_b32_dpp v199, v129 quad_perm:[1,0,3,2] row_mask:0xf bank_mask:0xf
	v_cvt_pk_bf16_f32 v128, v128, v189
	v_mov_b32_dpp v189, v130 quad_perm:[1,0,3,2] row_mask:0xf bank_mask:0xf
	v_cvt_pk_bf16_f32 v129, v129, v199
	v_mov_b32_dpp v199, v131 quad_perm:[1,0,3,2] row_mask:0xf bank_mask:0xf
	v_cvt_pk_bf16_f32 v130, v130, v189
	v_cvt_pk_bf16_f32 v131, v131, v199
	s_and_saveexec_b64 s[10:11], s[12:13]
	ds_write_b32 v186, v140
	ds_write_b32 v186, v141 offset:16
	ds_write_b32 v186, v142 offset:32
	ds_write_b32 v186, v143 offset:48
	ds_write_b32 v186, v136 offset:256
	ds_write_b32 v186, v137 offset:272
	ds_write_b32 v186, v138 offset:288
	ds_write_b32 v186, v139 offset:304
	ds_write_b32 v186, v132 offset:8192
	ds_write_b32 v186, v133 offset:8208
	ds_write_b32 v186, v134 offset:8224
	ds_write_b32 v186, v135 offset:8240
	ds_write_b32 v186, v128 offset:8448
	ds_write_b32 v186, v129 offset:8464
	ds_write_b32 v186, v130 offset:8480
	ds_write_b32 v186, v131 offset:8496
	s_mov_b64 exec, s[10:11]
	ds_read_b128 v[140:143], v187
	ds_read_b128 v[136:139], v187 offset:8192
	s_waitcnt lgkmcnt(0)
	global_store_dwordx4 v188, v[140:143], s[56:57] sc1
	global_store_dwordx4 v188, v[136:139], s[56:57] offset:2048 sc1

; DI u32x2 pk4(f32x4 v) { u32x2 r; r.x = pk2(v[0], v[1]); r.y = pk2(v[2], v[3]); return r; }
; DI size_t kf_off(int h, int nblk, int krow, int d) { return ((((size_t)h * nblk + (krow >> 5)) * 4 + (d >> 4)) * 64 + ((d >> 3) & 1) * 32 + (krow & 31)) * 8 + (d & 7); }
;     DI void operator()(const AccT& acc, const Unit& u, int wr, int wc, int fr, int fq, LAS unsigned char*) const {
;     ...
;                     if (isK) {
;                         bf16_t* kp = (bf16_t*)(ws + (isA ? WS_KA : WS_KB));
; #pragma unroll
;                         for (int bj = 0; bj < 2; ++bj)
; #pragma unroll
;                             for (int n = 0; n < 2; ++n) *(u32x2*)(kp + kf_off(h, krows >> 5, krow, 32 * bj + 16 * n + 4 * fq)) = pk4(v[bj][n]);
.LBB0_176:
	s_and_b64 vcc, exec, s[10:11]
	s_cbranch_vccz .LBB0_178
	v_lshl_add_u64 v[184:185], s[46:47], 0, v[184:185]
	v_lshlrev_b64 v[184:185], 8, v[184:185]
	v_and_or_b32 v150, v183, 15, v184
	v_lshl_add_u64 v[186:187], v[170:171], 0, s[48:49]
	v_or_b32_e32 v184, v150, v144
	v_lshl_add_u64 v[184:185], v[184:185], 4, v[186:187]
	s_waitcnt lgkmcnt(0)
	v_and_b32_e32 v186, 16, v226
	v_lshlrev_b32_e32 v187, 6, v186
	v_lshrrev_b32_e32 v186, 1, v186
	v_sub_u32_e32 v150, v187, v186
	v_lshl_add_u64 v[184:185], v[184:185], 0, v[150:151]
	v_cvt_pk_bf16_f32 v140, v140, v141
	v_cvt_pk_bf16_f32 v141, v142, v143
	v_cvt_pk_bf16_f32 v142, v136, v137
	v_cvt_pk_bf16_f32 v143, v138, v139
	v_cvt_pk_bf16_f32 v132, v132, v133
	v_cvt_pk_bf16_f32 v133, v134, v135
	v_cvt_pk_bf16_f32 v134, v128, v129
	v_cvt_pk_bf16_f32 v135, v130, v131
	s_nop 1
	v_permlane16_swap_b32_e32 v140, v142
	v_permlane16_swap_b32_e32 v141, v143
	v_permlane16_swap_b32_e32 v132, v134
	v_permlane16_swap_b32_e32 v133, v135
	global_store_dwordx4 v[184:185], v[140:143], off sc1
	global_store_dwordx4 v[184:185], v[132:135], off offset:2048 sc1

; DI u32x2 pk4(f32x4 v) { u32x2 r; r.x = pk2(v[0], v[1]); r.y = pk2(v[2], v[3]); return r; }
;     DI void operator()(const AccT& acc, const Unit& u, int wr, int wc, int fr, int fq, LAS unsigned char*) const {
;     ...
;                 if (kind == 0 || kind == 3) {
;                     bf16_t* q = (bf16_t*)(ws + (kind == 0 ? WS_QA : WS_QB)) + ((size_t)h * MTOK + row) * 64 + 4 * fq;
; #pragma unroll
;                     for (int bj = 0; bj < 2; ++bj)
; #pragma unroll
;                         for (int n = 0; n < 2; ++n) *(u32x2*)(q + 32 * bj + 16 * n) = pk4(v[bj][n] * QSCALE);
.LBB0_181:
	s_mul_hi_i32 s55, s44, 0x4800
	s_mul_i32 s54, s44, 0x4800
	s_and_b64 vcc, exec, s[10:11]
	s_cbranch_vccz .LBB0_179
	v_ashrrev_i32_e32 v183, 31, v182
	s_add_u32 s10, s36, s29
	v_lshl_add_u64 v[184:185], s[54:55], 0, v[182:183]
	s_addc_u32 s11, s37, 0
	v_lshlrev_b64 v[184:185], 7, v[184:185]
	v_lshl_add_u64 v[184:185], s[10:11], 0, v[184:185]
	v_lshlrev_b32_e32 v150, 1, v152
	v_pk_mul_f32 v[142:143], v[142:143], s[26:27] op_sel_hi:[1,0]
	v_pk_mul_f32 v[140:141], v[140:141], s[26:27] op_sel_hi:[1,0]
	v_pk_mul_f32 v[138:139], v[138:139], s[26:27] op_sel_hi:[1,0]
	v_pk_mul_f32 v[136:137], v[136:137], s[26:27] op_sel_hi:[1,0]
	v_pk_mul_f32 v[134:135], v[134:135], s[26:27] op_sel_hi:[1,0]
	v_pk_mul_f32 v[132:133], v[132:133], s[26:27] op_sel_hi:[1,0]
	v_pk_mul_f32 v[130:131], v[130:131], s[26:27] op_sel_hi:[1,0]
	v_pk_mul_f32 v[128:129], v[128:129], s[26:27] op_sel_hi:[1,0]
	v_lshl_add_u64 v[184:185], v[184:185], 0, v[150:151]
	v_and_b32_e32 v150, 8, v150
	v_mul_u32_u24_e32 v150, 3, v150
	v_lshl_add_u64 v[184:185], v[184:185], 0, v[150:151]
	v_cvt_pk_bf16_f32 v140, v140, v141
	v_cvt_pk_bf16_f32 v141, v142, v143
	v_cvt_pk_bf16_f32 v142, v136, v137
	v_cvt_pk_bf16_f32 v143, v138, v139
	v_cvt_pk_bf16_f32 v132, v132, v133
	v_cvt_pk_bf16_f32 v133, v134, v135
	v_cvt_pk_bf16_f32 v134, v128, v129
	v_cvt_pk_bf16_f32 v135, v130, v131
	s_nop 1
	v_permlane16_swap_b32_e32 v140, v142
	v_permlane16_swap_b32_e32 v141, v143
	v_permlane16_swap_b32_e32 v132, v134
	v_permlane16_swap_b32_e32 v133, v135
	global_store_dwordx4 v[184:185], v[140:143], off sc1
	global_store_dwordx4 v[184:185], v[132:135], off offset:64 sc1
	s_and_b64 vcc, exec, s[6:7]
	s_cbranch_vccz .LBB0_180

; DI size_t kf_off(int h, int nblk, int krow, int d) { return ((((size_t)h * nblk + (krow >> 5)) * 4 + (d >> 4)) * 64 + ((d >> 3) & 1) * 32 + (krow & 31)) * 8 + (d & 7); }
; DI u32x2 pk4(f32x4 v) { u32x2 r; r.x = pk2(v[0], v[1]); r.y = pk2(v[2], v[3]); return r; }
;     DI void operator()(const AccT& acc, const Unit& u, int wr, int wc, int fr, int fq, LAS unsigned char*) const {
;     ...
;                     const int krow = row < SEQ ? row : SEQ + (srow >> 6) * band + past + (srow & 63);
;                     const int krows = isA ? KA_ROWS : KB_ROWS;
;                     float* op = nullptr;
;                     size_t ooff = 0; bool has_o = false;
;                     if (row >= SEQ) { ooff = (isA ? (isK ? OFF_AKS : OFF_AVS) : (isK ? OFF_BKS : OFF_BVS)) + ((size_t)srow * nh + h) * 64; has_o = true; }
;                     else if (row >= SEQ - past) { ooff = (isA ? (isK ? OFF_AKP : OFF_AVP) : (isK ? OFF_BKP : OFF_BVP)) + ((size_t)(row - (SEQ - past)) * nh + h) * 64; has_o = true; }
;                     op = out + ooff;
;                     if (has_o) {
; #pragma unroll
;                         for (int bj = 0; bj < 2; ++bj)
; #pragma unroll
;                             for (int n = 0; n < 2; ++n) *(f32x4*)(op + 32 * bj + 16 * n + 4 * fq) = v[bj][n];
;                     }
;                     if (isK) {
;                         bf16_t* kp = (bf16_t*)(ws + (isA ? WS_KA : WS_KB));
; #pragma unroll
;                         for (int bj = 0; bj < 2; ++bj)
; #pragma unroll
;                             for (int n = 0; n < 2; ++n) *(u32x2*)(kp + kf_off(h, krows >> 5, krow, 32 * bj + 16 * n + 4 * fq)) = pk4(v[bj][n]);
;                     } else {
;                         bf16_t* vp = (bf16_t*)(ws + (isA ? WS_VTA : WS_VTB));
; #pragma unroll
;                         for (int bj = 0; bj < 2; ++bj)
; #pragma unroll
;                             for (int n = 0; n < 2; ++n)
; #pragma unroll
;                                 for (int j = 0; j < 4; ++j) {
;                                     const float mine = v[bj][n][j], oth = __shfl_xor(mine, 1);
;                                     if (!(fr & 1)) *(unsigned*)(vp + vf_off(h, krows >> 5, krow, 32 * bj + 16 * n + 4 * fq + j)) = pk2(mine, oth);
;                                 }
.LBB0_190:
	s_or_b64 exec, exec, s[0:1]
	s_and_saveexec_b64 s[0:1], s[56:57]
	s_cbranch_execz .LBB0_192
	v_lshlrev_b64 v[132:133], s92, v[150:151]
	v_lshl_add_u64 v[132:133], v[132:133], 0, s[44:45]
	v_lshlrev_b64 v[132:133], 8, v[132:133]
	v_lshl_add_u64 v[132:133], s[16:17], 0, v[132:133]
	v_lshlrev_b32_e32 v150, 2, v130
	v_lshl_add_u64 v[130:131], v[132:133], 0, v[150:151]
	v_lshlrev_b32_e32 v150, 2, v152
	v_lshl_add_u64 v[130:131], v[130:131], 0, v[150:151]
	global_store_dwordx4 v[130:131], v[124:127], off sc1
	global_store_dwordx4 v[130:131], v[120:123], off offset:64 sc1
	global_store_dwordx4 v[130:131], v[116:119], off offset:128 sc1
	global_store_dwordx4 v[130:131], v[112:115], off offset:192 sc1
.LBB0_192:
	s_or_b64 exec, exec, s[0:1]
	v_lshrrev_b32_e32 v129, 6, v129
	v_or_b32_e32 v130, s90, v191
	v_mad_u64_u32 v[130:131], s[0:1], s31, v129, v[130:131]
	v_cmp_gt_i32_e32 vcc, s68, v128
	s_mov_b64 s[0:1], -1
	s_nop 0
	v_cndmask_b32_e32 v129, v130, v128, vcc
	v_ashrrev_i32_e32 v130, 5, v129
	s_andn2_b64 vcc, exec, s[50:51]
	v_ashrrev_i32_e32 v131, 31, v130
	s_cbranch_vccnz .LBB0_226
	v_readfirstlane_b32 s58, v129
	v_and_b32_e32 v132, 15, v198
	v_lshrrev_b32_e32 v133, 4, v198
	v_bfe_u32 v134, v132, 2, 1
	v_lshrrev_b32_e32 v135, 3, v132
	v_and_b32_e32 v132, 3, v132
	v_lshl_add_u32 v132, v135, 2, v132
	v_lshl_add_u32 v133, v134, 3, v133
	v_lshlrev_b32_e32 v133, 6, v133
	v_lshl_add_u32 v133, v132, 1, v133
	s_add_i32 s59, s64, 0xc000
	v_add_u32_e32 v133, s59, v133
	v_lshlrev_b32_e32 v135, 4, v198
	v_add_u32_e32 v134, s59, v135
	s_lshr_b32 s56, s58, 5
	s_add_u32 s56, s56, s46
	s_lshl_b32 s56, s56, 12
	s_and_b32 s57, s58, 16
	s_lshl_b32 s57, s57, 6
	s_add_u32 s56, s56, s57
	s_add_u32 s56, s56, s91
	s_add_u32 s56, s36, s56
	s_addc_u32 s57, s37, 0
	v_mov_b32_dpp v136, v124 quad_perm:[1,0,3,2] row_mask:0xf bank_mask:0xf
	v_mov_b32_dpp v137, v125 quad_perm:[1,0,3,2] row_mask:0xf bank_mask:0xf
	v_cvt_pk_bf16_f32 v124, v124, v136
	v_mov_b32_dpp v136, v126 quad_perm:[1,0,3,2] row_mask:0xf bank_mask:0xf
	v_cvt_pk_bf16_f32 v125, v125, v137
	v_mov_b32_dpp v137, v127 quad_perm:[1,0,3,2] row_mask:0xf bank_mask:0xf
	v_cvt_pk_bf16_f32 v126, v126, v136
	v_mov_b32_dpp v136, v120 quad_perm:[1,0,3,2] row_mask:0xf bank_mask:0xf
	v_cvt_pk_bf16_f32 v127, v127, v137
	v_mov_b32_dpp v137, v121 quad_perm:[1,0,3,2] row_mask:0xf bank_mask:0xf
	v_cvt_pk_bf16_f32 v120, v120, v136
	v_mov_b32_dpp v136, v122 quad_perm:[1,0,3,2] row_mask:0xf bank_mask:0xf
	v_cvt_pk_bf16_f32 v121, v121, v137
	v_mov_b32_dpp v137, v123 quad_perm:[1,0,3,2] row_mask:0xf bank_mask:0xf
	v_cvt_pk_bf16_f32 v122, v122, v136
	v_mov_b32_dpp v136, v116 quad_perm:[1,0,3,2] row_mask:0xf bank_mask:0xf
	v_cvt_pk_bf16_f32 v123, v123, v137
	v_mov_b32_dpp v137, v117 quad_perm:[1,0,3,2] row_mask:0xf bank_mask:0xf
	v_cvt_pk_bf16_f32 v116, v116, v136
	v_mov_b32_dpp v136, v118 quad_perm:[1,0,3,2] row_mask:0xf bank_mask:0xf
	v_cvt_pk_bf16_f32 v117, v117, v137
	v_mov_b32_dpp v137, v119 quad_perm:[1,0,3,2] row_mask:0xf bank_mask:0xf
	v_cvt_pk_bf16_f32 v118, v118, v136
	v_mov_b32_dpp v136, v112 quad_perm:[1,0,3,2] row_mask:0xf bank_mask:0xf
	v_cvt_pk_bf16_f32 v119, v119, v137
	v_mov_b32_dpp v137, v113 quad_perm:[1,0,3,2] row_mask:0xf bank_mask:0xf
	v_cvt_pk_bf16_f32 v112, v112, v136
	v_mov_b32_dpp v136, v114 quad_perm:[1,0,3,2] row_mask:0xf bank_mask:0xf
	v_cvt_pk_bf16_f32 v113, v113, v137
	v_mov_b32_dpp v137, v115 quad_perm:[1,0,3,2] row_mask:0xf bank_mask:0xf
	v_cvt_pk_bf16_f32 v114, v114, v136
	v_cvt_pk_bf16_f32 v115, v115, v137
	s_and_saveexec_b64 s[0:1], s[12:13]
	ds_write_b32 v133, v124
	ds_write_b32 v133, v125 offset:16
	ds_write_b32 v133, v126 offset:32
	ds_write_b32 v133, v127 offset:48
	ds_write_b32 v133, v120 offset:256
	ds_write_b32 v133, v121 offset:272
	ds_write_b32 v133, v122 offset:288
	ds_write_b32 v133, v123 offset:304
	ds_write_b32 v133, v116 offset:8192
	ds_write_b32 v133, v117 offset:8208
	ds_write_b32 v133, v118 offset:8224
	ds_write_b32 v133, v119 offset:8240
	ds_write_b32 v133, v112 offset:8448
	ds_write_b32 v133, v113 offset:8464
	ds_write_b32 v133, v114 offset:8480
	ds_write_b32 v133, v115 offset:8496
	s_mov_b64 exec, s[0:1]
	ds_read_b128 v[124:127], v134
	ds_read_b128 v[120:123], v134 offset:8192
	s_waitcnt lgkmcnt(0)
	global_store_dwordx4 v135, v[124:127], s[56:57] sc1
	global_store_dwordx4 v135, v[120:123], s[56:57] offset:2048 sc1

; DI u32x2 pk4(f32x4 v) { u32x2 r; r.x = pk2(v[0], v[1]); r.y = pk2(v[2], v[3]); return r; }
; DI size_t kf_off(int h, int nblk, int krow, int d) { return ((((size_t)h * nblk + (krow >> 5)) * 4 + (d >> 4)) * 64 + ((d >> 3) & 1) * 32 + (krow & 31)) * 8 + (d & 7); }
;     DI void operator()(const AccT& acc, const Unit& u, int wr, int wc, int fr, int fq, LAS unsigned char*) const {
;     ...
;                     if (isK) {
;                         bf16_t* kp = (bf16_t*)(ws + (isA ? WS_KA : WS_KB));
; #pragma unroll
;                         for (int bj = 0; bj < 2; ++bj)
; #pragma unroll
;                             for (int n = 0; n < 2; ++n) *(u32x2*)(kp + kf_off(h, krows >> 5, krow, 32 * bj + 16 * n + 4 * fq)) = pk4(v[bj][n]);
.LBB0_226:
	s_and_b64 vcc, exec, s[0:1]
	s_cbranch_vccz .LBB0_228
	v_lshl_add_u64 v[130:131], s[46:47], 0, v[130:131]
	v_lshlrev_b64 v[130:131], 8, v[130:131]
	v_and_or_b32 v129, v129, 31, v130
	v_lshl_add_u64 v[132:133], v[170:171], 0, s[48:49]
	v_or_b32_e32 v130, v129, v144
	v_lshl_add_u64 v[130:131], v[130:131], 4, v[132:133]
	s_waitcnt lgkmcnt(0)
	v_and_b32_e32 v132, 16, v226
	v_lshlrev_b32_e32 v133, 6, v132
	v_lshrrev_b32_e32 v132, 1, v132
	v_sub_u32_e32 v150, v133, v132
	v_lshl_add_u64 v[130:131], v[130:131], 0, v[150:151]
	v_cvt_pk_bf16_f32 v124, v124, v125
	v_cvt_pk_bf16_f32 v125, v126, v127
	v_cvt_pk_bf16_f32 v126, v120, v121
	v_cvt_pk_bf16_f32 v127, v122, v123
	v_cvt_pk_bf16_f32 v116, v116, v117
	v_cvt_pk_bf16_f32 v117, v118, v119
	v_cvt_pk_bf16_f32 v118, v112, v113
	v_cvt_pk_bf16_f32 v119, v114, v115
	s_nop 1
	v_permlane16_swap_b32_e32 v124, v126
	v_permlane16_swap_b32_e32 v125, v127
	v_permlane16_swap_b32_e32 v116, v118
	v_permlane16_swap_b32_e32 v117, v119
	global_store_dwordx4 v[130:131], v[124:127], off sc1
	global_store_dwordx4 v[130:131], v[116:119], off offset:2048 sc1

; DI size_t kf_off(int h, int nblk, int krow, int d) { return ((((size_t)h * nblk + (krow >> 5)) * 4 + (d >> 4)) * 64 + ((d >> 3) & 1) * 32 + (krow & 31)) * 8 + (d & 7); }
; DI u32x2 pk4(f32x4 v) { u32x2 r; r.x = pk2(v[0], v[1]); r.y = pk2(v[2], v[3]); return r; }
;     DI void operator()(const AccT& acc, const Unit& u, int wr, int wc, int fr, int fq, LAS unsigned char*) const {
;     ...
;                     const int krow = row < SEQ ? row : SEQ + (srow >> 6) * band + past + (srow & 63);
;                     const int krows = isA ? KA_ROWS : KB_ROWS;
;                     float* op = nullptr;
;                     size_t ooff = 0; bool has_o = false;
;                     if (row >= SEQ) { ooff = (isA ? (isK ? OFF_AKS : OFF_AVS) : (isK ? OFF_BKS : OFF_BVS)) + ((size_t)srow * nh + h) * 64; has_o = true; }
;                     else if (row >= SEQ - past) { ooff = (isA ? (isK ? OFF_AKP : OFF_AVP) : (isK ? OFF_BKP : OFF_BVP)) + ((size_t)(row - (SEQ - past)) * nh + h) * 64; has_o = true; }
;                     op = out + ooff;
;                     if (has_o) {
; #pragma unroll
;                         for (int bj = 0; bj < 2; ++bj)
; #pragma unroll
;                             for (int n = 0; n < 2; ++n) *(f32x4*)(op + 32 * bj + 16 * n + 4 * fq) = v[bj][n];
;                     }
;                     if (isK) {
;                         bf16_t* kp = (bf16_t*)(ws + (isA ? WS_KA : WS_KB));
; #pragma unroll
;                         for (int bj = 0; bj < 2; ++bj)
; #pragma unroll
;                             for (int n = 0; n < 2; ++n) *(u32x2*)(kp + kf_off(h, krows >> 5, krow, 32 * bj + 16 * n + 4 * fq)) = pk4(v[bj][n]);
;                     } else {
;                         bf16_t* vp = (bf16_t*)(ws + (isA ? WS_VTA : WS_VTB));
; #pragma unroll
;                         for (int bj = 0; bj < 2; ++bj)
; #pragma unroll
;                             for (int n = 0; n < 2; ++n)
; #pragma unroll
;                                 for (int j = 0; j < 4; ++j) {
;                                     const float mine = v[bj][n][j], oth = __shfl_xor(mine, 1);
;                                     if (!(fr & 1)) *(unsigned*)(vp + vf_off(h, krows >> 5, krow, 32 * bj + 16 * n + 4 * fq + j)) = pk2(mine, oth);
;                                 }
.LBB0_236:
	s_or_b64 exec, exec, s[0:1]
	s_and_saveexec_b64 s[0:1], s[56:57]
	s_cbranch_execz .LBB0_238
	v_lshlrev_b64 v[116:117], s92, v[150:151]
	v_lshl_add_u64 v[116:117], v[116:117], 0, s[44:45]
	v_lshlrev_b64 v[116:117], 8, v[116:117]
	v_lshl_add_u64 v[116:117], s[16:17], 0, v[116:117]
	v_lshlrev_b32_e32 v150, 2, v114
	v_lshl_add_u64 v[114:115], v[116:117], 0, v[150:151]
	v_lshlrev_b32_e32 v150, 2, v152
	v_lshl_add_u64 v[114:115], v[114:115], 0, v[150:151]
	global_store_dwordx4 v[114:115], v[108:111], off sc1
	global_store_dwordx4 v[114:115], v[104:107], off offset:64 sc1
	global_store_dwordx4 v[114:115], v[100:103], off offset:128 sc1
	global_store_dwordx4 v[114:115], v[96:99], off offset:192 sc1
.LBB0_238:
	s_or_b64 exec, exec, s[0:1]
	v_lshrrev_b32_e32 v113, 6, v113
	v_or_b32_e32 v114, s90, v192
	v_mad_u64_u32 v[114:115], s[0:1], s31, v113, v[114:115]
	v_cmp_gt_i32_e32 vcc, s68, v112
	s_mov_b64 s[0:1], -1
	s_nop 0
	v_cndmask_b32_e32 v113, v114, v112, vcc
	v_ashrrev_i32_e32 v114, 5, v113
	s_andn2_b64 vcc, exec, s[50:51]
	v_ashrrev_i32_e32 v115, 31, v114
	s_cbranch_vccnz .LBB0_272
	v_readfirstlane_b32 s58, v113
	v_and_b32_e32 v116, 15, v198
	v_lshrrev_b32_e32 v117, 4, v198
	v_bfe_u32 v118, v116, 2, 1
	v_lshrrev_b32_e32 v119, 3, v116
	v_and_b32_e32 v116, 3, v116
	v_lshl_add_u32 v116, v119, 2, v116
	v_lshl_add_u32 v117, v118, 3, v117
	v_lshlrev_b32_e32 v117, 6, v117
	v_lshl_add_u32 v117, v116, 1, v117
	s_add_i32 s59, s64, 0xc000
	v_add_u32_e32 v117, s59, v117
	v_lshlrev_b32_e32 v119, 4, v198
	v_add_u32_e32 v118, s59, v119
	s_lshr_b32 s56, s58, 5
	s_add_u32 s56, s56, s46
	s_lshl_b32 s56, s56, 12
	s_and_b32 s57, s58, 16
	s_lshl_b32 s57, s57, 6
	s_add_u32 s56, s56, s57
	s_add_u32 s56, s56, s91
	s_add_u32 s56, s36, s56
	s_addc_u32 s57, s37, 0
	v_mov_b32_dpp v120, v108 quad_perm:[1,0,3,2] row_mask:0xf bank_mask:0xf
	v_mov_b32_dpp v121, v109 quad_perm:[1,0,3,2] row_mask:0xf bank_mask:0xf
	v_cvt_pk_bf16_f32 v108, v108, v120
	v_mov_b32_dpp v120, v110 quad_perm:[1,0,3,2] row_mask:0xf bank_mask:0xf
	v_cvt_pk_bf16_f32 v109, v109, v121
	v_mov_b32_dpp v121, v111 quad_perm:[1,0,3,2] row_mask:0xf bank_mask:0xf
	v_cvt_pk_bf16_f32 v110, v110, v120
	v_mov_b32_dpp v120, v104 quad_perm:[1,0,3,2] row_mask:0xf bank_mask:0xf
	v_cvt_pk_bf16_f32 v111, v111, v121
	v_mov_b32_dpp v121, v105 quad_perm:[1,0,3,2] row_mask:0xf bank_mask:0xf
	v_cvt_pk_bf16_f32 v104, v104, v120
	v_mov_b32_dpp v120, v106 quad_perm:[1,0,3,2] row_mask:0xf bank_mask:0xf
	v_cvt_pk_bf16_f32 v105, v105, v121
	v_mov_b32_dpp v121, v107 quad_perm:[1,0,3,2] row_mask:0xf bank_mask:0xf
	v_cvt_pk_bf16_f32 v106, v106, v120
	v_mov_b32_dpp v120, v100 quad_perm:[1,0,3,2] row_mask:0xf bank_mask:0xf
	v_cvt_pk_bf16_f32 v107, v107, v121
	v_mov_b32_dpp v121, v101 quad_perm:[1,0,3,2] row_mask:0xf bank_mask:0xf
	v_cvt_pk_bf16_f32 v100, v100, v120
	v_mov_b32_dpp v120, v102 quad_perm:[1,0,3,2] row_mask:0xf bank_mask:0xf
	v_cvt_pk_bf16_f32 v101, v101, v121
	v_mov_b32_dpp v121, v103 quad_perm:[1,0,3,2] row_mask:0xf bank_mask:0xf
	v_cvt_pk_bf16_f32 v102, v102, v120
	v_mov_b32_dpp v120, v96 quad_perm:[1,0,3,2] row_mask:0xf bank_mask:0xf
	v_cvt_pk_bf16_f32 v103, v103, v121
	v_mov_b32_dpp v121, v97 quad_perm:[1,0,3,2] row_mask:0xf bank_mask:0xf
	v_cvt_pk_bf16_f32 v96, v96, v120
	v_mov_b32_dpp v120, v98 quad_perm:[1,0,3,2] row_mask:0xf bank_mask:0xf
	v_cvt_pk_bf16_f32 v97, v97, v121
	v_mov_b32_dpp v121, v99 quad_perm:[1,0,3,2] row_mask:0xf bank_mask:0xf
	v_cvt_pk_bf16_f32 v98, v98, v120
	v_cvt_pk_bf16_f32 v99, v99, v121
	s_and_saveexec_b64 s[0:1], s[12:13]
	ds_write_b32 v117, v108
	ds_write_b32 v117, v109 offset:16
	ds_write_b32 v117, v110 offset:32
	ds_write_b32 v117, v111 offset:48
	ds_write_b32 v117, v104 offset:256
	ds_write_b32 v117, v105 offset:272
	ds_write_b32 v117, v106 offset:288
	ds_write_b32 v117, v107 offset:304
	ds_write_b32 v117, v100 offset:8192
	ds_write_b32 v117, v101 offset:8208
	ds_write_b32 v117, v102 offset:8224
	ds_write_b32 v117, v103 offset:8240
	ds_write_b32 v117, v96 offset:8448
	ds_write_b32 v117, v97 offset:8464
	ds_write_b32 v117, v98 offset:8480
	ds_write_b32 v117, v99 offset:8496
	s_mov_b64 exec, s[0:1]
	ds_read_b128 v[108:111], v118
	ds_read_b128 v[104:107], v118 offset:8192
	s_waitcnt lgkmcnt(0)
	global_store_dwordx4 v119, v[108:111], s[56:57] sc1
	global_store_dwordx4 v119, v[104:107], s[56:57] offset:2048 sc1

; DI u32x2 pk4(f32x4 v) { u32x2 r; r.x = pk2(v[0], v[1]); r.y = pk2(v[2], v[3]); return r; }
; DI size_t kf_off(int h, int nblk, int krow, int d) { return ((((size_t)h * nblk + (krow >> 5)) * 4 + (d >> 4)) * 64 + ((d >> 3) & 1) * 32 + (krow & 31)) * 8 + (d & 7); }
;     DI void operator()(const AccT& acc, const Unit& u, int wr, int wc, int fr, int fq, LAS unsigned char*) const {
;     ...
;                     if (isK) {
;                         bf16_t* kp = (bf16_t*)(ws + (isA ? WS_KA : WS_KB));
; #pragma unroll
;                         for (int bj = 0; bj < 2; ++bj)
; #pragma unroll
;                             for (int n = 0; n < 2; ++n) *(u32x2*)(kp + kf_off(h, krows >> 5, krow, 32 * bj + 16 * n + 4 * fq)) = pk4(v[bj][n]);
.LBB0_272:
	s_and_b64 vcc, exec, s[0:1]
	s_cbranch_vccz .LBB0_274
	v_lshl_add_u64 v[114:115], s[46:47], 0, v[114:115]
	v_lshlrev_b64 v[114:115], 8, v[114:115]
	v_and_or_b32 v113, v113, 15, v114
	v_lshl_add_u64 v[116:117], v[170:171], 0, s[48:49]
	v_or_b32_e32 v114, v113, v144
	v_lshl_add_u64 v[114:115], v[114:115], 4, v[116:117]
	s_waitcnt lgkmcnt(0)
	v_and_b32_e32 v116, 16, v226
	v_lshlrev_b32_e32 v117, 6, v116
	v_lshrrev_b32_e32 v116, 1, v116
	v_sub_u32_e32 v150, v117, v116
	v_lshl_add_u64 v[114:115], v[114:115], 0, v[150:151]
	v_cvt_pk_bf16_f32 v108, v108, v109
	v_cvt_pk_bf16_f32 v109, v110, v111
	v_cvt_pk_bf16_f32 v110, v104, v105
	v_cvt_pk_bf16_f32 v111, v106, v107
	v_cvt_pk_bf16_f32 v100, v100, v101
	v_cvt_pk_bf16_f32 v101, v102, v103
	v_cvt_pk_bf16_f32 v102, v96, v97
	v_cvt_pk_bf16_f32 v103, v98, v99
	s_nop 1
	v_permlane16_swap_b32_e32 v108, v110
	v_permlane16_swap_b32_e32 v109, v111
	v_permlane16_swap_b32_e32 v100, v102
	v_permlane16_swap_b32_e32 v101, v103
	global_store_dwordx4 v[114:115], v[108:111], off sc1
	global_store_dwordx4 v[114:115], v[100:103], off offset:2048 sc1

; DI size_t kf_off(int h, int nblk, int krow, int d) { return ((((size_t)h * nblk + (krow >> 5)) * 4 + (d >> 4)) * 64 + ((d >> 3) & 1) * 32 + (krow & 31)) * 8 + (d & 7); }
; DI u32x2 pk4(f32x4 v) { u32x2 r; r.x = pk2(v[0], v[1]); r.y = pk2(v[2], v[3]); return r; }
;     DI void operator()(const AccT& acc, const Unit& u, int wr, int wc, int fr, int fq, LAS unsigned char*) const {
;     ...
;                     const int krow = row < SEQ ? row : SEQ + (srow >> 6) * band + past + (srow & 63);
;                     const int krows = isA ? KA_ROWS : KB_ROWS;
;                     float* op = nullptr;
;                     size_t ooff = 0; bool has_o = false;
;                     if (row >= SEQ) { ooff = (isA ? (isK ? OFF_AKS : OFF_AVS) : (isK ? OFF_BKS : OFF_BVS)) + ((size_t)srow * nh + h) * 64; has_o = true; }
;                     else if (row >= SEQ - past) { ooff = (isA ? (isK ? OFF_AKP : OFF_AVP) : (isK ? OFF_BKP : OFF_BVP)) + ((size_t)(row - (SEQ - past)) * nh + h) * 64; has_o = true; }
;                     op = out + ooff;
;                     if (has_o) {
; #pragma unroll
;                         for (int bj = 0; bj < 2; ++bj)
; #pragma unroll
;                             for (int n = 0; n < 2; ++n) *(f32x4*)(op + 32 * bj + 16 * n + 4 * fq) = v[bj][n];
;                     }
;                     if (isK) {
;                         bf16_t* kp = (bf16_t*)(ws + (isA ? WS_KA : WS_KB));
; #pragma unroll
;                         for (int bj = 0; bj < 2; ++bj)
; #pragma unroll
;                             for (int n = 0; n < 2; ++n) *(u32x2*)(kp + kf_off(h, krows >> 5, krow, 32 * bj + 16 * n + 4 * fq)) = pk4(v[bj][n]);
;                     } else {
;                         bf16_t* vp = (bf16_t*)(ws + (isA ? WS_VTA : WS_VTB));
; #pragma unroll
;                         for (int bj = 0; bj < 2; ++bj)
; #pragma unroll
;                             for (int n = 0; n < 2; ++n)
; #pragma unroll
;                                 for (int j = 0; j < 4; ++j) {
;                                     const float mine = v[bj][n][j], oth = __shfl_xor(mine, 1);
;                                     if (!(fr & 1)) *(unsigned*)(vp + vf_off(h, krows >> 5, krow, 32 * bj + 16 * n + 4 * fq + j)) = pk2(mine, oth);
;                                 }
.LBB0_282:
	s_or_b64 exec, exec, s[0:1]
	s_and_saveexec_b64 s[0:1], s[56:57]
	s_cbranch_execz .LBB0_284
	v_lshlrev_b64 v[100:101], s92, v[150:151]
	v_lshl_add_u64 v[100:101], v[100:101], 0, s[44:45]
	v_lshlrev_b64 v[100:101], 8, v[100:101]
	v_lshl_add_u64 v[100:101], s[16:17], 0, v[100:101]
	v_lshlrev_b32_e32 v150, 2, v98
	v_lshl_add_u64 v[98:99], v[100:101], 0, v[150:151]
	v_lshlrev_b32_e32 v150, 2, v152
	v_lshl_add_u64 v[98:99], v[98:99], 0, v[150:151]
	global_store_dwordx4 v[98:99], v[92:95], off sc1
	global_store_dwordx4 v[98:99], v[88:91], off offset:64 sc1
	global_store_dwordx4 v[98:99], v[84:87], off offset:128 sc1
	global_store_dwordx4 v[98:99], v[80:83], off offset:192 sc1
.LBB0_284:
	s_or_b64 exec, exec, s[0:1]
	v_lshrrev_b32_e32 v97, 6, v97
	v_or_b32_e32 v98, s90, v193
	v_mad_u64_u32 v[98:99], s[0:1], s31, v97, v[98:99]
	v_cmp_gt_i32_e32 vcc, s68, v96
	s_mov_b64 s[0:1], -1
	s_nop 0
	v_cndmask_b32_e32 v97, v98, v96, vcc
	v_ashrrev_i32_e32 v98, 5, v97
	s_andn2_b64 vcc, exec, s[50:51]
	v_ashrrev_i32_e32 v99, 31, v98
	s_cbranch_vccnz .LBB0_318
	v_readfirstlane_b32 s58, v97
	v_and_b32_e32 v100, 15, v198
	v_lshrrev_b32_e32 v101, 4, v198
	v_bfe_u32 v102, v100, 2, 1
	v_lshrrev_b32_e32 v103, 3, v100
	v_and_b32_e32 v100, 3, v100
	v_lshl_add_u32 v100, v103, 2, v100
	v_lshl_add_u32 v101, v102, 3, v101
	v_lshlrev_b32_e32 v101, 6, v101
	v_lshl_add_u32 v101, v100, 1, v101
	s_add_i32 s59, s64, 0xc000
	v_add_u32_e32 v101, s59, v101
	v_lshlrev_b32_e32 v103, 4, v198
	v_add_u32_e32 v102, s59, v103
	s_lshr_b32 s56, s58, 5
	s_add_u32 s56, s56, s46
	s_lshl_b32 s56, s56, 12
	s_and_b32 s57, s58, 16
	s_lshl_b32 s57, s57, 6
	s_add_u32 s56, s56, s57
	s_add_u32 s56, s56, s91
	s_add_u32 s56, s36, s56
	s_addc_u32 s57, s37, 0
	v_mov_b32_dpp v104, v92 quad_perm:[1,0,3,2] row_mask:0xf bank_mask:0xf
	v_mov_b32_dpp v105, v93 quad_perm:[1,0,3,2] row_mask:0xf bank_mask:0xf
	v_cvt_pk_bf16_f32 v92, v92, v104
	v_mov_b32_dpp v104, v94 quad_perm:[1,0,3,2] row_mask:0xf bank_mask:0xf
	v_cvt_pk_bf16_f32 v93, v93, v105
	v_mov_b32_dpp v105, v95 quad_perm:[1,0,3,2] row_mask:0xf bank_mask:0xf
	v_cvt_pk_bf16_f32 v94, v94, v104
	v_mov_b32_dpp v104, v88 quad_perm:[1,0,3,2] row_mask:0xf bank_mask:0xf
	v_cvt_pk_bf16_f32 v95, v95, v105
	v_mov_b32_dpp v105, v89 quad_perm:[1,0,3,2] row_mask:0xf bank_mask:0xf
	v_cvt_pk_bf16_f32 v88, v88, v104
	v_mov_b32_dpp v104, v90 quad_perm:[1,0,3,2] row_mask:0xf bank_mask:0xf
	v_cvt_pk_bf16_f32 v89, v89, v105
	v_mov_b32_dpp v105, v91 quad_perm:[1,0,3,2] row_mask:0xf bank_mask:0xf
	v_cvt_pk_bf16_f32 v90, v90, v104
	v_mov_b32_dpp v104, v84 quad_perm:[1,0,3,2] row_mask:0xf bank_mask:0xf
	v_cvt_pk_bf16_f32 v91, v91, v105
	v_mov_b32_dpp v105, v85 quad_perm:[1,0,3,2] row_mask:0xf bank_mask:0xf
	v_cvt_pk_bf16_f32 v84, v84, v104
	v_mov_b32_dpp v104, v86 quad_perm:[1,0,3,2] row_mask:0xf bank_mask:0xf
	v_cvt_pk_bf16_f32 v85, v85, v105
	v_mov_b32_dpp v105, v87 quad_perm:[1,0,3,2] row_mask:0xf bank_mask:0xf
	v_cvt_pk_bf16_f32 v86, v86, v104
	v_mov_b32_dpp v104, v80 quad_perm:[1,0,3,2] row_mask:0xf bank_mask:0xf
	v_cvt_pk_bf16_f32 v87, v87, v105
	v_mov_b32_dpp v105, v81 quad_perm:[1,0,3,2] row_mask:0xf bank_mask:0xf
	v_cvt_pk_bf16_f32 v80, v80, v104
	v_mov_b32_dpp v104, v82 quad_perm:[1,0,3,2] row_mask:0xf bank_mask:0xf
	v_cvt_pk_bf16_f32 v81, v81, v105
	v_mov_b32_dpp v105, v83 quad_perm:[1,0,3,2] row_mask:0xf bank_mask:0xf
	v_cvt_pk_bf16_f32 v82, v82, v104
	v_cvt_pk_bf16_f32 v83, v83, v105
	s_and_saveexec_b64 s[0:1], s[12:13]
	ds_write_b32 v101, v92
	ds_write_b32 v101, v93 offset:16
	ds_write_b32 v101, v94 offset:32
	ds_write_b32 v101, v95 offset:48
	ds_write_b32 v101, v88 offset:256
	ds_write_b32 v101, v89 offset:272
	ds_write_b32 v101, v90 offset:288
	ds_write_b32 v101, v91 offset:304
	ds_write_b32 v101, v84 offset:8192
	ds_write_b32 v101, v85 offset:8208
	ds_write_b32 v101, v86 offset:8224
	ds_write_b32 v101, v87 offset:8240
	ds_write_b32 v101, v80 offset:8448
	ds_write_b32 v101, v81 offset:8464
	ds_write_b32 v101, v82 offset:8480
	ds_write_b32 v101, v83 offset:8496
	s_mov_b64 exec, s[0:1]
	ds_read_b128 v[92:95], v102
	ds_read_b128 v[88:91], v102 offset:8192
	s_waitcnt lgkmcnt(0)
	global_store_dwordx4 v103, v[92:95], s[56:57] sc1
	global_store_dwordx4 v103, v[88:91], s[56:57] offset:2048 sc1

; DI u32x2 pk4(f32x4 v) { u32x2 r; r.x = pk2(v[0], v[1]); r.y = pk2(v[2], v[3]); return r; }
; DI size_t kf_off(int h, int nblk, int krow, int d) { return ((((size_t)h * nblk + (krow >> 5)) * 4 + (d >> 4)) * 64 + ((d >> 3) & 1) * 32 + (krow & 31)) * 8 + (d & 7); }
;     DI void operator()(const AccT& acc, const Unit& u, int wr, int wc, int fr, int fq, LAS unsigned char*) const {
;     ...
;                     if (isK) {
;                         bf16_t* kp = (bf16_t*)(ws + (isA ? WS_KA : WS_KB));
; #pragma unroll
;                         for (int bj = 0; bj < 2; ++bj)
; #pragma unroll
;                             for (int n = 0; n < 2; ++n) *(u32x2*)(kp + kf_off(h, krows >> 5, krow, 32 * bj + 16 * n + 4 * fq)) = pk4(v[bj][n]);
.LBB0_318:
	s_and_b64 vcc, exec, s[0:1]
	s_cbranch_vccz .LBB0_320
	v_lshl_add_u64 v[98:99], s[46:47], 0, v[98:99]
	v_lshlrev_b64 v[98:99], 8, v[98:99]
	v_and_or_b32 v97, v97, 31, v98
	v_lshl_add_u64 v[100:101], v[170:171], 0, s[48:49]
	v_or_b32_e32 v98, v97, v144
	v_lshl_add_u64 v[98:99], v[98:99], 4, v[100:101]
	s_waitcnt lgkmcnt(0)
	v_and_b32_e32 v100, 16, v226
	v_lshlrev_b32_e32 v101, 6, v100
	v_lshrrev_b32_e32 v100, 1, v100
	v_sub_u32_e32 v150, v101, v100
	v_lshl_add_u64 v[98:99], v[98:99], 0, v[150:151]
	v_cvt_pk_bf16_f32 v92, v92, v93
	v_cvt_pk_bf16_f32 v93, v94, v95
	v_cvt_pk_bf16_f32 v94, v88, v89
	v_cvt_pk_bf16_f32 v95, v90, v91
	v_cvt_pk_bf16_f32 v84, v84, v85
	v_cvt_pk_bf16_f32 v85, v86, v87
	v_cvt_pk_bf16_f32 v86, v80, v81
	v_cvt_pk_bf16_f32 v87, v82, v83
	s_nop 1
	v_permlane16_swap_b32_e32 v92, v94
	v_permlane16_swap_b32_e32 v93, v95
	v_permlane16_swap_b32_e32 v84, v86
	v_permlane16_swap_b32_e32 v85, v87
	global_store_dwordx4 v[98:99], v[92:95], off sc1
	global_store_dwordx4 v[98:99], v[84:87], off offset:2048 sc1

; DI size_t kf_off(int h, int nblk, int krow, int d) { return ((((size_t)h * nblk + (krow >> 5)) * 4 + (d >> 4)) * 64 + ((d >> 3) & 1) * 32 + (krow & 31)) * 8 + (d & 7); }
; DI u32x2 pk4(f32x4 v) { u32x2 r; r.x = pk2(v[0], v[1]); r.y = pk2(v[2], v[3]); return r; }
;     DI void operator()(const AccT& acc, const Unit& u, int wr, int wc, int fr, int fq, LAS unsigned char*) const {
;     ...
;                     const int krow = row < SEQ ? row : SEQ + (srow >> 6) * band + past + (srow & 63);
;                     const int krows = isA ? KA_ROWS : KB_ROWS;
;                     float* op = nullptr;
;                     size_t ooff = 0; bool has_o = false;
;                     if (row >= SEQ) { ooff = (isA ? (isK ? OFF_AKS : OFF_AVS) : (isK ? OFF_BKS : OFF_BVS)) + ((size_t)srow * nh + h) * 64; has_o = true; }
;                     else if (row >= SEQ - past) { ooff = (isA ? (isK ? OFF_AKP : OFF_AVP) : (isK ? OFF_BKP : OFF_BVP)) + ((size_t)(row - (SEQ - past)) * nh + h) * 64; has_o = true; }
;                     op = out + ooff;
;                     if (has_o) {
; #pragma unroll
;                         for (int bj = 0; bj < 2; ++bj)
; #pragma unroll
;                             for (int n = 0; n < 2; ++n) *(f32x4*)(op + 32 * bj + 16 * n + 4 * fq) = v[bj][n];
;                     }
;                     if (isK) {
;                         bf16_t* kp = (bf16_t*)(ws + (isA ? WS_KA : WS_KB));
; #pragma unroll
;                         for (int bj = 0; bj < 2; ++bj)
; #pragma unroll
;                             for (int n = 0; n < 2; ++n) *(u32x2*)(kp + kf_off(h, krows >> 5, krow, 32 * bj + 16 * n + 4 * fq)) = pk4(v[bj][n]);
;                     } else {
;                         bf16_t* vp = (bf16_t*)(ws + (isA ? WS_VTA : WS_VTB));
; #pragma unroll
;                         for (int bj = 0; bj < 2; ++bj)
; #pragma unroll
;                             for (int n = 0; n < 2; ++n)
; #pragma unroll
;                                 for (int j = 0; j < 4; ++j) {
;                                     const float mine = v[bj][n][j], oth = __shfl_xor(mine, 1);
;                                     if (!(fr & 1)) *(unsigned*)(vp + vf_off(h, krows >> 5, krow, 32 * bj + 16 * n + 4 * fq + j)) = pk2(mine, oth);
;                                 }
.LBB0_328:
	s_or_b64 exec, exec, s[0:1]
	s_and_saveexec_b64 s[0:1], s[56:57]
	s_cbranch_execz .LBB0_330
	v_lshlrev_b64 v[84:85], s92, v[150:151]
	v_lshl_add_u64 v[84:85], v[84:85], 0, s[44:45]
	v_lshlrev_b64 v[84:85], 8, v[84:85]
	v_lshl_add_u64 v[84:85], s[16:17], 0, v[84:85]
	v_lshlrev_b32_e32 v150, 2, v82
	v_lshl_add_u64 v[82:83], v[84:85], 0, v[150:151]
	v_lshlrev_b32_e32 v150, 2, v152
	v_lshl_add_u64 v[82:83], v[82:83], 0, v[150:151]
	global_store_dwordx4 v[82:83], v[76:79], off sc1
	global_store_dwordx4 v[82:83], v[72:75], off offset:64 sc1
	global_store_dwordx4 v[82:83], v[68:71], off offset:128 sc1
	global_store_dwordx4 v[82:83], v[64:67], off offset:192 sc1
.LBB0_330:
	s_or_b64 exec, exec, s[0:1]
	v_lshrrev_b32_e32 v81, 6, v81
	v_or_b32_e32 v82, s90, v167
	v_mad_u64_u32 v[82:83], s[0:1], s31, v81, v[82:83]
	v_cmp_gt_i32_e32 vcc, s68, v80
	s_mov_b64 s[0:1], -1
	s_nop 0
	v_cndmask_b32_e32 v81, v82, v80, vcc
	v_ashrrev_i32_e32 v82, 5, v81
	s_andn2_b64 vcc, exec, s[50:51]
	v_ashrrev_i32_e32 v83, 31, v82
	s_cbranch_vccnz .LBB0_364
	v_readfirstlane_b32 s58, v81
	v_and_b32_e32 v84, 15, v198
	v_lshrrev_b32_e32 v85, 4, v198
	v_bfe_u32 v86, v84, 2, 1
	v_lshrrev_b32_e32 v87, 3, v84
	v_and_b32_e32 v84, 3, v84
	v_lshl_add_u32 v84, v87, 2, v84
	v_lshl_add_u32 v85, v86, 3, v85
	v_lshlrev_b32_e32 v85, 6, v85
	v_lshl_add_u32 v85, v84, 1, v85
	s_add_i32 s59, s64, 0xc000
	v_add_u32_e32 v85, s59, v85
	v_lshlrev_b32_e32 v87, 4, v198
	v_add_u32_e32 v86, s59, v87
	s_lshr_b32 s56, s58, 5
	s_add_u32 s56, s56, s46
	s_lshl_b32 s56, s56, 12
	s_and_b32 s57, s58, 16
	s_lshl_b32 s57, s57, 6
	s_add_u32 s56, s56, s57
	s_add_u32 s56, s56, s91
	s_add_u32 s56, s36, s56
	s_addc_u32 s57, s37, 0
	v_mov_b32_dpp v88, v76 quad_perm:[1,0,3,2] row_mask:0xf bank_mask:0xf
	v_mov_b32_dpp v89, v77 quad_perm:[1,0,3,2] row_mask:0xf bank_mask:0xf
	v_cvt_pk_bf16_f32 v76, v76, v88
	v_mov_b32_dpp v88, v78 quad_perm:[1,0,3,2] row_mask:0xf bank_mask:0xf
	v_cvt_pk_bf16_f32 v77, v77, v89
	v_mov_b32_dpp v89, v79 quad_perm:[1,0,3,2] row_mask:0xf bank_mask:0xf
	v_cvt_pk_bf16_f32 v78, v78, v88
	v_mov_b32_dpp v88, v72 quad_perm:[1,0,3,2] row_mask:0xf bank_mask:0xf
	v_cvt_pk_bf16_f32 v79, v79, v89
	v_mov_b32_dpp v89, v73 quad_perm:[1,0,3,2] row_mask:0xf bank_mask:0xf
	v_cvt_pk_bf16_f32 v72, v72, v88
	v_mov_b32_dpp v88, v74 quad_perm:[1,0,3,2] row_mask:0xf bank_mask:0xf
	v_cvt_pk_bf16_f32 v73, v73, v89
	v_mov_b32_dpp v89, v75 quad_perm:[1,0,3,2] row_mask:0xf bank_mask:0xf
	v_cvt_pk_bf16_f32 v74, v74, v88
	v_mov_b32_dpp v88, v68 quad_perm:[1,0,3,2] row_mask:0xf bank_mask:0xf
	v_cvt_pk_bf16_f32 v75, v75, v89
	v_mov_b32_dpp v89, v69 quad_perm:[1,0,3,2] row_mask:0xf bank_mask:0xf
	v_cvt_pk_bf16_f32 v68, v68, v88
	v_mov_b32_dpp v88, v70 quad_perm:[1,0,3,2] row_mask:0xf bank_mask:0xf
	v_cvt_pk_bf16_f32 v69, v69, v89
	v_mov_b32_dpp v89, v71 quad_perm:[1,0,3,2] row_mask:0xf bank_mask:0xf
	v_cvt_pk_bf16_f32 v70, v70, v88
	v_mov_b32_dpp v88, v64 quad_perm:[1,0,3,2] row_mask:0xf bank_mask:0xf
	v_cvt_pk_bf16_f32 v71, v71, v89
	v_mov_b32_dpp v89, v65 quad_perm:[1,0,3,2] row_mask:0xf bank_mask:0xf
	v_cvt_pk_bf16_f32 v64, v64, v88
	v_mov_b32_dpp v88, v66 quad_perm:[1,0,3,2] row_mask:0xf bank_mask:0xf
	v_cvt_pk_bf16_f32 v65, v65, v89
	v_mov_b32_dpp v89, v67 quad_perm:[1,0,3,2] row_mask:0xf bank_mask:0xf
	v_cvt_pk_bf16_f32 v66, v66, v88
	v_cvt_pk_bf16_f32 v67, v67, v89
	s_and_saveexec_b64 s[0:1], s[12:13]
	ds_write_b32 v85, v76
	ds_write_b32 v85, v77 offset:16
	ds_write_b32 v85, v78 offset:32
	ds_write_b32 v85, v79 offset:48
	ds_write_b32 v85, v72 offset:256
	ds_write_b32 v85, v73 offset:272
	ds_write_b32 v85, v74 offset:288
	ds_write_b32 v85, v75 offset:304
	ds_write_b32 v85, v68 offset:8192
	ds_write_b32 v85, v69 offset:8208
	ds_write_b32 v85, v70 offset:8224
	ds_write_b32 v85, v71 offset:8240
	ds_write_b32 v85, v64 offset:8448
	ds_write_b32 v85, v65 offset:8464
	ds_write_b32 v85, v66 offset:8480
	ds_write_b32 v85, v67 offset:8496
	s_mov_b64 exec, s[0:1]
	ds_read_b128 v[76:79], v86
	ds_read_b128 v[72:75], v86 offset:8192
	s_waitcnt lgkmcnt(0)
	global_store_dwordx4 v87, v[76:79], s[56:57] sc1
	global_store_dwordx4 v87, v[72:75], s[56:57] offset:2048 sc1

; DI u32x2 pk4(f32x4 v) { u32x2 r; r.x = pk2(v[0], v[1]); r.y = pk2(v[2], v[3]); return r; }
; DI size_t kf_off(int h, int nblk, int krow, int d) { return ((((size_t)h * nblk + (krow >> 5)) * 4 + (d >> 4)) * 64 + ((d >> 3) & 1) * 32 + (krow & 31)) * 8 + (d & 7); }
;     DI void operator()(const AccT& acc, const Unit& u, int wr, int wc, int fr, int fq, LAS unsigned char*) const {
;     ...
;                     if (isK) {
;                         bf16_t* kp = (bf16_t*)(ws + (isA ? WS_KA : WS_KB));
; #pragma unroll
;                         for (int bj = 0; bj < 2; ++bj)
; #pragma unroll
;                             for (int n = 0; n < 2; ++n) *(u32x2*)(kp + kf_off(h, krows >> 5, krow, 32 * bj + 16 * n + 4 * fq)) = pk4(v[bj][n]);
.LBB0_364:
	s_and_b64 vcc, exec, s[0:1]
	s_cbranch_vccz .LBB0_366
	v_lshl_add_u64 v[82:83], s[46:47], 0, v[82:83]
	v_lshlrev_b64 v[82:83], 8, v[82:83]
	v_and_or_b32 v81, v81, 15, v82
	v_lshl_add_u64 v[84:85], v[170:171], 0, s[48:49]
	v_or_b32_e32 v82, v81, v144
	v_lshl_add_u64 v[82:83], v[82:83], 4, v[84:85]
	s_waitcnt lgkmcnt(0)
	v_and_b32_e32 v84, 16, v226
	v_lshlrev_b32_e32 v85, 6, v84
	v_lshrrev_b32_e32 v84, 1, v84
	v_sub_u32_e32 v150, v85, v84
	v_lshl_add_u64 v[82:83], v[82:83], 0, v[150:151]
	v_cvt_pk_bf16_f32 v76, v76, v77
	v_cvt_pk_bf16_f32 v77, v78, v79
	v_cvt_pk_bf16_f32 v78, v72, v73
	v_cvt_pk_bf16_f32 v79, v74, v75
	v_cvt_pk_bf16_f32 v68, v68, v69
	v_cvt_pk_bf16_f32 v69, v70, v71
	v_cvt_pk_bf16_f32 v70, v64, v65
	v_cvt_pk_bf16_f32 v71, v66, v67
	s_nop 1
	v_permlane16_swap_b32_e32 v76, v78
	v_permlane16_swap_b32_e32 v77, v79
	v_permlane16_swap_b32_e32 v68, v70
	v_permlane16_swap_b32_e32 v69, v71
	global_store_dwordx4 v[82:83], v[76:79], off sc1
	global_store_dwordx4 v[82:83], v[68:71], off offset:2048 sc1

; DI size_t kf_off(int h, int nblk, int krow, int d) { return ((((size_t)h * nblk + (krow >> 5)) * 4 + (d >> 4)) * 64 + ((d >> 3) & 1) * 32 + (krow & 31)) * 8 + (d & 7); }
; DI u32x2 pk4(f32x4 v) { u32x2 r; r.x = pk2(v[0], v[1]); r.y = pk2(v[2], v[3]); return r; }
;     DI void operator()(const AccT& acc, const Unit& u, int wr, int wc, int fr, int fq, LAS unsigned char*) const {
;     ...
;                     const int krow = row < SEQ ? row : SEQ + (srow >> 6) * band + past + (srow & 63);
;                     const int krows = isA ? KA_ROWS : KB_ROWS;
;                     float* op = nullptr;
;                     size_t ooff = 0; bool has_o = false;
;                     if (row >= SEQ) { ooff = (isA ? (isK ? OFF_AKS : OFF_AVS) : (isK ? OFF_BKS : OFF_BVS)) + ((size_t)srow * nh + h) * 64; has_o = true; }
;                     else if (row >= SEQ - past) { ooff = (isA ? (isK ? OFF_AKP : OFF_AVP) : (isK ? OFF_BKP : OFF_BVP)) + ((size_t)(row - (SEQ - past)) * nh + h) * 64; has_o = true; }
;                     op = out + ooff;
;                     if (has_o) {
; #pragma unroll
;                         for (int bj = 0; bj < 2; ++bj)
; #pragma unroll
;                             for (int n = 0; n < 2; ++n) *(f32x4*)(op + 32 * bj + 16 * n + 4 * fq) = v[bj][n];
;                     }
;                     if (isK) {
;                         bf16_t* kp = (bf16_t*)(ws + (isA ? WS_KA : WS_KB));
; #pragma unroll
;                         for (int bj = 0; bj < 2; ++bj)
; #pragma unroll
;                             for (int n = 0; n < 2; ++n) *(u32x2*)(kp + kf_off(h, krows >> 5, krow, 32 * bj + 16 * n + 4 * fq)) = pk4(v[bj][n]);
;                     } else {
;                         bf16_t* vp = (bf16_t*)(ws + (isA ? WS_VTA : WS_VTB));
; #pragma unroll
;                         for (int bj = 0; bj < 2; ++bj)
; #pragma unroll
;                             for (int n = 0; n < 2; ++n)
; #pragma unroll
;                                 for (int j = 0; j < 4; ++j) {
;                                     const float mine = v[bj][n][j], oth = __shfl_xor(mine, 1);
;                                     if (!(fr & 1)) *(unsigned*)(vp + vf_off(h, krows >> 5, krow, 32 * bj + 16 * n + 4 * fq + j)) = pk2(mine, oth);
;                                 }
.LBB0_374:
	s_or_b64 exec, exec, s[0:1]
	s_and_saveexec_b64 s[0:1], s[56:57]
	s_cbranch_execz .LBB0_376
	v_lshlrev_b64 v[68:69], s92, v[150:151]
	v_lshl_add_u64 v[68:69], v[68:69], 0, s[44:45]
	v_lshlrev_b64 v[68:69], 8, v[68:69]
	v_lshl_add_u64 v[68:69], s[16:17], 0, v[68:69]
	v_lshlrev_b32_e32 v150, 2, v66
	v_lshl_add_u64 v[66:67], v[68:69], 0, v[150:151]
	v_lshlrev_b32_e32 v150, 2, v152
	v_lshl_add_u64 v[66:67], v[66:67], 0, v[150:151]
	global_store_dwordx4 v[66:67], v[44:47], off sc1
	global_store_dwordx4 v[66:67], v[40:43], off offset:64 sc1
	global_store_dwordx4 v[66:67], v[36:39], off offset:128 sc1
	global_store_dwordx4 v[66:67], v[32:35], off offset:192 sc1
.LBB0_376:
	s_or_b64 exec, exec, s[0:1]
	v_lshrrev_b32_e32 v65, 6, v65
	v_or_b32_e32 v66, s90, v191
	v_mad_u64_u32 v[66:67], s[0:1], s31, v65, v[66:67]
	v_cmp_gt_i32_e32 vcc, s68, v64
	s_mov_b64 s[0:1], -1
	s_nop 0
	v_cndmask_b32_e32 v65, v66, v64, vcc
	v_ashrrev_i32_e32 v66, 5, v65
	s_andn2_b64 vcc, exec, s[50:51]
	v_ashrrev_i32_e32 v67, 31, v66
	s_cbranch_vccnz .LBB0_410
	v_readfirstlane_b32 s58, v65
	v_and_b32_e32 v68, 15, v198
	v_lshrrev_b32_e32 v69, 4, v198
	v_bfe_u32 v70, v68, 2, 1
	v_lshrrev_b32_e32 v71, 3, v68
	v_and_b32_e32 v68, 3, v68
	v_lshl_add_u32 v68, v71, 2, v68
	v_lshl_add_u32 v69, v70, 3, v69
	v_lshlrev_b32_e32 v69, 6, v69
	v_lshl_add_u32 v69, v68, 1, v69
	s_add_i32 s59, s64, 0xc000
	v_add_u32_e32 v69, s59, v69
	v_lshlrev_b32_e32 v71, 4, v198
	v_add_u32_e32 v70, s59, v71
	s_lshr_b32 s56, s58, 5
	s_add_u32 s56, s56, s46
	s_lshl_b32 s56, s56, 12
	s_and_b32 s57, s58, 16
	s_lshl_b32 s57, s57, 6
	s_add_u32 s56, s56, s57
	s_add_u32 s56, s56, s91
	s_add_u32 s56, s36, s56
	s_addc_u32 s57, s37, 0
	v_mov_b32_dpp v72, v44 quad_perm:[1,0,3,2] row_mask:0xf bank_mask:0xf
	v_mov_b32_dpp v73, v45 quad_perm:[1,0,3,2] row_mask:0xf bank_mask:0xf
	v_cvt_pk_bf16_f32 v44, v44, v72
	v_mov_b32_dpp v72, v46 quad_perm:[1,0,3,2] row_mask:0xf bank_mask:0xf
	v_cvt_pk_bf16_f32 v45, v45, v73
	v_mov_b32_dpp v73, v47 quad_perm:[1,0,3,2] row_mask:0xf bank_mask:0xf
	v_cvt_pk_bf16_f32 v46, v46, v72
	v_mov_b32_dpp v72, v40 quad_perm:[1,0,3,2] row_mask:0xf bank_mask:0xf
	v_cvt_pk_bf16_f32 v47, v47, v73
	v_mov_b32_dpp v73, v41 quad_perm:[1,0,3,2] row_mask:0xf bank_mask:0xf
	v_cvt_pk_bf16_f32 v40, v40, v72
	v_mov_b32_dpp v72, v42 quad_perm:[1,0,3,2] row_mask:0xf bank_mask:0xf
	v_cvt_pk_bf16_f32 v41, v41, v73
	v_mov_b32_dpp v73, v43 quad_perm:[1,0,3,2] row_mask:0xf bank_mask:0xf
	v_cvt_pk_bf16_f32 v42, v42, v72
	v_mov_b32_dpp v72, v36 quad_perm:[1,0,3,2] row_mask:0xf bank_mask:0xf
	v_cvt_pk_bf16_f32 v43, v43, v73
	v_mov_b32_dpp v73, v37 quad_perm:[1,0,3,2] row_mask:0xf bank_mask:0xf
	v_cvt_pk_bf16_f32 v36, v36, v72
	v_mov_b32_dpp v72, v38 quad_perm:[1,0,3,2] row_mask:0xf bank_mask:0xf
	v_cvt_pk_bf16_f32 v37, v37, v73
	v_mov_b32_dpp v73, v39 quad_perm:[1,0,3,2] row_mask:0xf bank_mask:0xf
	v_cvt_pk_bf16_f32 v38, v38, v72
	v_mov_b32_dpp v72, v32 quad_perm:[1,0,3,2] row_mask:0xf bank_mask:0xf
	v_cvt_pk_bf16_f32 v39, v39, v73
	v_mov_b32_dpp v73, v33 quad_perm:[1,0,3,2] row_mask:0xf bank_mask:0xf
	v_cvt_pk_bf16_f32 v32, v32, v72
	v_mov_b32_dpp v72, v34 quad_perm:[1,0,3,2] row_mask:0xf bank_mask:0xf
	v_cvt_pk_bf16_f32 v33, v33, v73
	v_mov_b32_dpp v73, v35 quad_perm:[1,0,3,2] row_mask:0xf bank_mask:0xf
	v_cvt_pk_bf16_f32 v34, v34, v72
	v_cvt_pk_bf16_f32 v35, v35, v73
	s_and_saveexec_b64 s[0:1], s[12:13]
	ds_write_b32 v69, v44
	ds_write_b32 v69, v45 offset:16
	ds_write_b32 v69, v46 offset:32
	ds_write_b32 v69, v47 offset:48
	ds_write_b32 v69, v40 offset:256
	ds_write_b32 v69, v41 offset:272
	ds_write_b32 v69, v42 offset:288
	ds_write_b32 v69, v43 offset:304
	ds_write_b32 v69, v36 offset:8192
	ds_write_b32 v69, v37 offset:8208
	ds_write_b32 v69, v38 offset:8224
	ds_write_b32 v69, v39 offset:8240
	ds_write_b32 v69, v32 offset:8448
	ds_write_b32 v69, v33 offset:8464
	ds_write_b32 v69, v34 offset:8480
	ds_write_b32 v69, v35 offset:8496
	s_mov_b64 exec, s[0:1]
	ds_read_b128 v[44:47], v70
	ds_read_b128 v[40:43], v70 offset:8192
	s_waitcnt lgkmcnt(0)
	global_store_dwordx4 v71, v[44:47], s[56:57] sc1
	global_store_dwordx4 v71, v[40:43], s[56:57] offset:2048 sc1

; DI u32x2 pk4(f32x4 v) { u32x2 r; r.x = pk2(v[0], v[1]); r.y = pk2(v[2], v[3]); return r; }
; DI size_t kf_off(int h, int nblk, int krow, int d) { return ((((size_t)h * nblk + (krow >> 5)) * 4 + (d >> 4)) * 64 + ((d >> 3) & 1) * 32 + (krow & 31)) * 8 + (d & 7); }
;     DI void operator()(const AccT& acc, const Unit& u, int wr, int wc, int fr, int fq, LAS unsigned char*) const {
;     ...
;                     if (isK) {
;                         bf16_t* kp = (bf16_t*)(ws + (isA ? WS_KA : WS_KB));
; #pragma unroll
;                         for (int bj = 0; bj < 2; ++bj)
; #pragma unroll
;                             for (int n = 0; n < 2; ++n) *(u32x2*)(kp + kf_off(h, krows >> 5, krow, 32 * bj + 16 * n + 4 * fq)) = pk4(v[bj][n]);
.LBB0_410:
	s_and_b64 vcc, exec, s[0:1]
	s_cbranch_vccz .LBB0_412
	v_lshl_add_u64 v[66:67], s[46:47], 0, v[66:67]
	v_lshlrev_b64 v[66:67], 8, v[66:67]
	v_and_or_b32 v65, v65, 31, v66
	v_lshl_add_u64 v[68:69], v[170:171], 0, s[48:49]
	v_or_b32_e32 v66, v65, v144
	v_lshl_add_u64 v[66:67], v[66:67], 4, v[68:69]
	s_waitcnt lgkmcnt(0)
	v_and_b32_e32 v68, 16, v226
	v_lshlrev_b32_e32 v69, 6, v68
	v_lshrrev_b32_e32 v68, 1, v68
	v_sub_u32_e32 v150, v69, v68
	v_lshl_add_u64 v[66:67], v[66:67], 0, v[150:151]
	v_cvt_pk_bf16_f32 v44, v44, v45
	v_cvt_pk_bf16_f32 v45, v46, v47
	v_cvt_pk_bf16_f32 v46, v40, v41
	v_cvt_pk_bf16_f32 v47, v42, v43
	v_cvt_pk_bf16_f32 v36, v36, v37
	v_cvt_pk_bf16_f32 v37, v38, v39
	v_cvt_pk_bf16_f32 v38, v32, v33
	v_cvt_pk_bf16_f32 v39, v34, v35
	s_nop 1
	v_permlane16_swap_b32_e32 v44, v46
	v_permlane16_swap_b32_e32 v45, v47
	v_permlane16_swap_b32_e32 v36, v38
	v_permlane16_swap_b32_e32 v37, v39
	global_store_dwordx4 v[66:67], v[44:47], off sc1
	global_store_dwordx4 v[66:67], v[36:39], off offset:2048 sc1

; DI size_t kf_off(int h, int nblk, int krow, int d) { return ((((size_t)h * nblk + (krow >> 5)) * 4 + (d >> 4)) * 64 + ((d >> 3) & 1) * 32 + (krow & 31)) * 8 + (d & 7); }
; DI u32x2 pk4(f32x4 v) { u32x2 r; r.x = pk2(v[0], v[1]); r.y = pk2(v[2], v[3]); return r; }
;     DI void operator()(const AccT& acc, const Unit& u, int wr, int wc, int fr, int fq, LAS unsigned char*) const {
;     ...
;                     const int krow = row < SEQ ? row : SEQ + (srow >> 6) * band + past + (srow & 63);
;                     const int krows = isA ? KA_ROWS : KB_ROWS;
;                     float* op = nullptr;
;                     size_t ooff = 0; bool has_o = false;
;                     if (row >= SEQ) { ooff = (isA ? (isK ? OFF_AKS : OFF_AVS) : (isK ? OFF_BKS : OFF_BVS)) + ((size_t)srow * nh + h) * 64; has_o = true; }
;                     else if (row >= SEQ - past) { ooff = (isA ? (isK ? OFF_AKP : OFF_AVP) : (isK ? OFF_BKP : OFF_BVP)) + ((size_t)(row - (SEQ - past)) * nh + h) * 64; has_o = true; }
;                     op = out + ooff;
;                     if (has_o) {
; #pragma unroll
;                         for (int bj = 0; bj < 2; ++bj)
; #pragma unroll
;                             for (int n = 0; n < 2; ++n) *(f32x4*)(op + 32 * bj + 16 * n + 4 * fq) = v[bj][n];
;                     }
;                     if (isK) {
;                         bf16_t* kp = (bf16_t*)(ws + (isA ? WS_KA : WS_KB));
; #pragma unroll
;                         for (int bj = 0; bj < 2; ++bj)
; #pragma unroll
;                             for (int n = 0; n < 2; ++n) *(u32x2*)(kp + kf_off(h, krows >> 5, krow, 32 * bj + 16 * n + 4 * fq)) = pk4(v[bj][n]);
;                     } else {
;                         bf16_t* vp = (bf16_t*)(ws + (isA ? WS_VTA : WS_VTB));
; #pragma unroll
;                         for (int bj = 0; bj < 2; ++bj)
; #pragma unroll
;                             for (int n = 0; n < 2; ++n)
; #pragma unroll
;                                 for (int j = 0; j < 4; ++j) {
;                                     const float mine = v[bj][n][j], oth = __shfl_xor(mine, 1);
;                                     if (!(fr & 1)) *(unsigned*)(vp + vf_off(h, krows >> 5, krow, 32 * bj + 16 * n + 4 * fq + j)) = pk2(mine, oth);
;                                 }
.LBB0_420:
	s_or_b64 exec, exec, s[0:1]
	s_and_saveexec_b64 s[0:1], s[56:57]
	s_cbranch_execz .LBB0_422
	v_lshlrev_b64 v[36:37], s92, v[150:151]
	v_lshl_add_u64 v[36:37], v[36:37], 0, s[44:45]
	v_lshlrev_b64 v[36:37], 8, v[36:37]
	v_lshl_add_u64 v[36:37], s[16:17], 0, v[36:37]
	v_lshlrev_b32_e32 v150, 2, v34
	v_lshl_add_u64 v[34:35], v[36:37], 0, v[150:151]
	v_lshlrev_b32_e32 v150, 2, v152
	v_lshl_add_u64 v[34:35], v[34:35], 0, v[150:151]
	global_store_dwordx4 v[34:35], v[28:31], off sc1
	global_store_dwordx4 v[34:35], v[24:27], off offset:64 sc1
	global_store_dwordx4 v[34:35], v[20:23], off offset:128 sc1
	global_store_dwordx4 v[34:35], v[16:19], off offset:192 sc1
.LBB0_422:
	s_or_b64 exec, exec, s[0:1]
	v_lshrrev_b32_e32 v33, 6, v33
	v_or_b32_e32 v34, s90, v192
	v_mad_u64_u32 v[34:35], s[0:1], s31, v33, v[34:35]
	v_cmp_gt_i32_e32 vcc, s68, v32
	s_mov_b64 s[0:1], -1
	s_nop 0
	v_cndmask_b32_e32 v33, v34, v32, vcc
	v_ashrrev_i32_e32 v34, 5, v33
	s_andn2_b64 vcc, exec, s[50:51]
	v_ashrrev_i32_e32 v35, 31, v34
	s_cbranch_vccnz .LBB0_456
	v_readfirstlane_b32 s58, v33
	v_and_b32_e32 v36, 15, v198
	v_lshrrev_b32_e32 v37, 4, v198
	v_bfe_u32 v38, v36, 2, 1
	v_lshrrev_b32_e32 v39, 3, v36
	v_and_b32_e32 v36, 3, v36
	v_lshl_add_u32 v36, v39, 2, v36
	v_lshl_add_u32 v37, v38, 3, v37
	v_lshlrev_b32_e32 v37, 6, v37
	v_lshl_add_u32 v37, v36, 1, v37
	s_add_i32 s59, s64, 0xc000
	v_add_u32_e32 v37, s59, v37
	v_lshlrev_b32_e32 v39, 4, v198
	v_add_u32_e32 v38, s59, v39
	s_lshr_b32 s56, s58, 5
	s_add_u32 s56, s56, s46
	s_lshl_b32 s56, s56, 12
	s_and_b32 s57, s58, 16
	s_lshl_b32 s57, s57, 6
	s_add_u32 s56, s56, s57
	s_add_u32 s56, s56, s91
	s_add_u32 s56, s36, s56
	s_addc_u32 s57, s37, 0
	v_mov_b32_dpp v40, v28 quad_perm:[1,0,3,2] row_mask:0xf bank_mask:0xf
	v_mov_b32_dpp v41, v29 quad_perm:[1,0,3,2] row_mask:0xf bank_mask:0xf
	v_cvt_pk_bf16_f32 v28, v28, v40
	v_mov_b32_dpp v40, v30 quad_perm:[1,0,3,2] row_mask:0xf bank_mask:0xf
	v_cvt_pk_bf16_f32 v29, v29, v41
	v_mov_b32_dpp v41, v31 quad_perm:[1,0,3,2] row_mask:0xf bank_mask:0xf
	v_cvt_pk_bf16_f32 v30, v30, v40
	v_mov_b32_dpp v40, v24 quad_perm:[1,0,3,2] row_mask:0xf bank_mask:0xf
	v_cvt_pk_bf16_f32 v31, v31, v41
	v_mov_b32_dpp v41, v25 quad_perm:[1,0,3,2] row_mask:0xf bank_mask:0xf
	v_cvt_pk_bf16_f32 v24, v24, v40
	v_mov_b32_dpp v40, v26 quad_perm:[1,0,3,2] row_mask:0xf bank_mask:0xf
	v_cvt_pk_bf16_f32 v25, v25, v41
	v_mov_b32_dpp v41, v27 quad_perm:[1,0,3,2] row_mask:0xf bank_mask:0xf
	v_cvt_pk_bf16_f32 v26, v26, v40
	v_mov_b32_dpp v40, v20 quad_perm:[1,0,3,2] row_mask:0xf bank_mask:0xf
	v_cvt_pk_bf16_f32 v27, v27, v41
	v_mov_b32_dpp v41, v21 quad_perm:[1,0,3,2] row_mask:0xf bank_mask:0xf
	v_cvt_pk_bf16_f32 v20, v20, v40
	v_mov_b32_dpp v40, v22 quad_perm:[1,0,3,2] row_mask:0xf bank_mask:0xf
	v_cvt_pk_bf16_f32 v21, v21, v41
	v_mov_b32_dpp v41, v23 quad_perm:[1,0,3,2] row_mask:0xf bank_mask:0xf
	v_cvt_pk_bf16_f32 v22, v22, v40
	v_mov_b32_dpp v40, v16 quad_perm:[1,0,3,2] row_mask:0xf bank_mask:0xf
	v_cvt_pk_bf16_f32 v23, v23, v41
	v_mov_b32_dpp v41, v17 quad_perm:[1,0,3,2] row_mask:0xf bank_mask:0xf
	v_cvt_pk_bf16_f32 v16, v16, v40
	v_mov_b32_dpp v40, v18 quad_perm:[1,0,3,2] row_mask:0xf bank_mask:0xf
	v_cvt_pk_bf16_f32 v17, v17, v41
	v_mov_b32_dpp v41, v19 quad_perm:[1,0,3,2] row_mask:0xf bank_mask:0xf
	v_cvt_pk_bf16_f32 v18, v18, v40
	v_cvt_pk_bf16_f32 v19, v19, v41
	s_and_saveexec_b64 s[0:1], s[12:13]
	ds_write_b32 v37, v28
	ds_write_b32 v37, v29 offset:16
	ds_write_b32 v37, v30 offset:32
	ds_write_b32 v37, v31 offset:48
	ds_write_b32 v37, v24 offset:256
	ds_write_b32 v37, v25 offset:272
	ds_write_b32 v37, v26 offset:288
	ds_write_b32 v37, v27 offset:304
	ds_write_b32 v37, v20 offset:8192
	ds_write_b32 v37, v21 offset:8208
	ds_write_b32 v37, v22 offset:8224
	ds_write_b32 v37, v23 offset:8240
	ds_write_b32 v37, v16 offset:8448
	ds_write_b32 v37, v17 offset:8464
	ds_write_b32 v37, v18 offset:8480
	ds_write_b32 v37, v19 offset:8496
	s_mov_b64 exec, s[0:1]
	ds_read_b128 v[28:31], v38
	ds_read_b128 v[24:27], v38 offset:8192
	s_waitcnt lgkmcnt(0)
	global_store_dwordx4 v39, v[28:31], s[56:57] sc1
	global_store_dwordx4 v39, v[24:27], s[56:57] offset:2048 sc1

; DI u32x2 pk4(f32x4 v) { u32x2 r; r.x = pk2(v[0], v[1]); r.y = pk2(v[2], v[3]); return r; }
; DI size_t kf_off(int h, int nblk, int krow, int d) { return ((((size_t)h * nblk + (krow >> 5)) * 4 + (d >> 4)) * 64 + ((d >> 3) & 1) * 32 + (krow & 31)) * 8 + (d & 7); }
;     DI void operator()(const AccT& acc, const Unit& u, int wr, int wc, int fr, int fq, LAS unsigned char*) const {
;     ...
;                     if (isK) {
;                         bf16_t* kp = (bf16_t*)(ws + (isA ? WS_KA : WS_KB));
; #pragma unroll
;                         for (int bj = 0; bj < 2; ++bj)
; #pragma unroll
;                             for (int n = 0; n < 2; ++n) *(u32x2*)(kp + kf_off(h, krows >> 5, krow, 32 * bj + 16 * n + 4 * fq)) = pk4(v[bj][n]);
.LBB0_456:
	s_and_b64 vcc, exec, s[0:1]
	s_cbranch_vccz .LBB0_458
	v_lshl_add_u64 v[34:35], s[46:47], 0, v[34:35]
	v_lshlrev_b64 v[34:35], 8, v[34:35]
	v_and_or_b32 v33, v33, 15, v34
	v_lshl_add_u64 v[36:37], v[170:171], 0, s[48:49]
	v_or_b32_e32 v34, v33, v144
	v_lshl_add_u64 v[34:35], v[34:35], 4, v[36:37]
	s_waitcnt lgkmcnt(0)
	v_and_b32_e32 v36, 16, v226
	v_lshlrev_b32_e32 v37, 6, v36
	v_lshrrev_b32_e32 v36, 1, v36
	v_sub_u32_e32 v150, v37, v36
	v_lshl_add_u64 v[34:35], v[34:35], 0, v[150:151]
	v_cvt_pk_bf16_f32 v28, v28, v29
	v_cvt_pk_bf16_f32 v29, v30, v31
	v_cvt_pk_bf16_f32 v30, v24, v25
	v_cvt_pk_bf16_f32 v31, v26, v27
	v_cvt_pk_bf16_f32 v20, v20, v21
	v_cvt_pk_bf16_f32 v21, v22, v23
	v_cvt_pk_bf16_f32 v22, v16, v17
	v_cvt_pk_bf16_f32 v23, v18, v19
	s_nop 1
	v_permlane16_swap_b32_e32 v28, v30
	v_permlane16_swap_b32_e32 v29, v31
	v_permlane16_swap_b32_e32 v20, v22
	v_permlane16_swap_b32_e32 v21, v23
	global_store_dwordx4 v[34:35], v[28:31], off sc1
	global_store_dwordx4 v[34:35], v[20:23], off offset:2048 sc1

; DI size_t kf_off(int h, int nblk, int krow, int d) { return ((((size_t)h * nblk + (krow >> 5)) * 4 + (d >> 4)) * 64 + ((d >> 3) & 1) * 32 + (krow & 31)) * 8 + (d & 7); }
; DI u32x2 pk4(f32x4 v) { u32x2 r; r.x = pk2(v[0], v[1]); r.y = pk2(v[2], v[3]); return r; }
;     DI void operator()(const AccT& acc, const Unit& u, int wr, int wc, int fr, int fq, LAS unsigned char*) const {
;     ...
;                     const int krow = row < SEQ ? row : SEQ + (srow >> 6) * band + past + (srow & 63);
;                     const int krows = isA ? KA_ROWS : KB_ROWS;
;                     float* op = nullptr;
;                     size_t ooff = 0; bool has_o = false;
;                     if (row >= SEQ) { ooff = (isA ? (isK ? OFF_AKS : OFF_AVS) : (isK ? OFF_BKS : OFF_BVS)) + ((size_t)srow * nh + h) * 64; has_o = true; }
;                     else if (row >= SEQ - past) { ooff = (isA ? (isK ? OFF_AKP : OFF_AVP) : (isK ? OFF_BKP : OFF_BVP)) + ((size_t)(row - (SEQ - past)) * nh + h) * 64; has_o = true; }
;                     op = out + ooff;
;                     if (has_o) {
; #pragma unroll
;                         for (int bj = 0; bj < 2; ++bj)
; #pragma unroll
;                             for (int n = 0; n < 2; ++n) *(f32x4*)(op + 32 * bj + 16 * n + 4 * fq) = v[bj][n];
;                     }
;                     if (isK) {
;                         bf16_t* kp = (bf16_t*)(ws + (isA ? WS_KA : WS_KB));
; #pragma unroll
;                         for (int bj = 0; bj < 2; ++bj)
; #pragma unroll
;                             for (int n = 0; n < 2; ++n) *(u32x2*)(kp + kf_off(h, krows >> 5, krow, 32 * bj + 16 * n + 4 * fq)) = pk4(v[bj][n]);
;                     } else {
;                         bf16_t* vp = (bf16_t*)(ws + (isA ? WS_VTA : WS_VTB));
; #pragma unroll
;                         for (int bj = 0; bj < 2; ++bj)
; #pragma unroll
;                             for (int n = 0; n < 2; ++n)
; #pragma unroll
;                                 for (int j = 0; j < 4; ++j) {
;                                     const float mine = v[bj][n][j], oth = __shfl_xor(mine, 1);
;                                     if (!(fr & 1)) *(unsigned*)(vp + vf_off(h, krows >> 5, krow, 32 * bj + 16 * n + 4 * fq + j)) = pk2(mine, oth);
;                                 }
.LBB0_466:
	s_or_b64 exec, exec, s[0:1]
	s_and_saveexec_b64 s[0:1], s[6:7]
	s_cbranch_execz .LBB0_468
	v_lshlrev_b64 v[20:21], s92, v[150:151]
	v_lshl_add_u64 v[20:21], v[20:21], 0, s[44:45]
	v_lshlrev_b64 v[20:21], 8, v[20:21]
	v_lshl_add_u64 v[20:21], s[16:17], 0, v[20:21]
	v_lshlrev_b32_e32 v150, 2, v18
	v_lshl_add_u64 v[18:19], v[20:21], 0, v[150:151]
	v_lshlrev_b32_e32 v150, 2, v152
	v_lshl_add_u64 v[18:19], v[18:19], 0, v[150:151]
	global_store_dwordx4 v[18:19], v[12:15], off sc1
	global_store_dwordx4 v[18:19], v[8:11], off offset:64 sc1
	global_store_dwordx4 v[18:19], v[4:7], off offset:128 sc1
	global_store_dwordx4 v[18:19], v[0:3], off offset:192 sc1
.LBB0_468:
	s_or_b64 exec, exec, s[0:1]
	v_lshrrev_b32_e32 v17, 6, v17
	v_or_b32_e32 v18, s90, v193
	v_mad_u64_u32 v[18:19], s[0:1], s31, v17, v[18:19]
	v_cmp_gt_i32_e32 vcc, s68, v16
	s_mov_b64 s[0:1], -1
	s_nop 0
	v_cndmask_b32_e32 v17, v18, v16, vcc
	v_ashrrev_i32_e32 v18, 5, v17
	s_andn2_b64 vcc, exec, s[50:51]
	v_ashrrev_i32_e32 v19, 31, v18
	s_cbranch_vccnz .LBB0_502
	v_readfirstlane_b32 s58, v17
	v_and_b32_e32 v20, 15, v198
	v_lshrrev_b32_e32 v21, 4, v198
	v_bfe_u32 v22, v20, 2, 1
	v_lshrrev_b32_e32 v23, 3, v20
	v_and_b32_e32 v20, 3, v20
	v_lshl_add_u32 v20, v23, 2, v20
	v_lshl_add_u32 v21, v22, 3, v21
	v_lshlrev_b32_e32 v21, 6, v21
	v_lshl_add_u32 v21, v20, 1, v21
	s_add_i32 s59, s64, 0xc000
	v_add_u32_e32 v21, s59, v21
	v_lshlrev_b32_e32 v23, 4, v198
	v_add_u32_e32 v22, s59, v23
	s_lshr_b32 s56, s58, 5
	s_add_u32 s56, s56, s46
	s_lshl_b32 s56, s56, 12
	s_and_b32 s57, s58, 16
	s_lshl_b32 s57, s57, 6
	s_add_u32 s56, s56, s57
	s_add_u32 s56, s56, s91
	s_add_u32 s56, s36, s56
	s_addc_u32 s57, s37, 0
	v_mov_b32_dpp v24, v12 quad_perm:[1,0,3,2] row_mask:0xf bank_mask:0xf
	v_mov_b32_dpp v25, v13 quad_perm:[1,0,3,2] row_mask:0xf bank_mask:0xf
	v_cvt_pk_bf16_f32 v12, v12, v24
	v_mov_b32_dpp v24, v14 quad_perm:[1,0,3,2] row_mask:0xf bank_mask:0xf
	v_cvt_pk_bf16_f32 v13, v13, v25
	v_mov_b32_dpp v25, v15 quad_perm:[1,0,3,2] row_mask:0xf bank_mask:0xf
	v_cvt_pk_bf16_f32 v14, v14, v24
	v_mov_b32_dpp v24, v8 quad_perm:[1,0,3,2] row_mask:0xf bank_mask:0xf
	v_cvt_pk_bf16_f32 v15, v15, v25
	v_mov_b32_dpp v25, v9 quad_perm:[1,0,3,2] row_mask:0xf bank_mask:0xf
	v_cvt_pk_bf16_f32 v8, v8, v24
	v_mov_b32_dpp v24, v10 quad_perm:[1,0,3,2] row_mask:0xf bank_mask:0xf
	v_cvt_pk_bf16_f32 v9, v9, v25
	v_mov_b32_dpp v25, v11 quad_perm:[1,0,3,2] row_mask:0xf bank_mask:0xf
	v_cvt_pk_bf16_f32 v10, v10, v24
	v_mov_b32_dpp v24, v4 quad_perm:[1,0,3,2] row_mask:0xf bank_mask:0xf
	v_cvt_pk_bf16_f32 v11, v11, v25
	v_mov_b32_dpp v25, v5 quad_perm:[1,0,3,2] row_mask:0xf bank_mask:0xf
	v_cvt_pk_bf16_f32 v4, v4, v24
	v_mov_b32_dpp v24, v6 quad_perm:[1,0,3,2] row_mask:0xf bank_mask:0xf
	v_cvt_pk_bf16_f32 v5, v5, v25
	v_mov_b32_dpp v25, v7 quad_perm:[1,0,3,2] row_mask:0xf bank_mask:0xf
	v_cvt_pk_bf16_f32 v6, v6, v24
	v_mov_b32_dpp v24, v0 quad_perm:[1,0,3,2] row_mask:0xf bank_mask:0xf
	v_cvt_pk_bf16_f32 v7, v7, v25
	v_mov_b32_dpp v25, v1 quad_perm:[1,0,3,2] row_mask:0xf bank_mask:0xf
	v_cvt_pk_bf16_f32 v0, v0, v24
	v_mov_b32_dpp v24, v2 quad_perm:[1,0,3,2] row_mask:0xf bank_mask:0xf
	v_cvt_pk_bf16_f32 v1, v1, v25
	v_mov_b32_dpp v25, v3 quad_perm:[1,0,3,2] row_mask:0xf bank_mask:0xf
	v_cvt_pk_bf16_f32 v2, v2, v24
	v_cvt_pk_bf16_f32 v3, v3, v25
	s_and_saveexec_b64 s[0:1], s[12:13]
	ds_write_b32 v21, v12
	ds_write_b32 v21, v13 offset:16
	ds_write_b32 v21, v14 offset:32
	ds_write_b32 v21, v15 offset:48
	ds_write_b32 v21, v8 offset:256
	ds_write_b32 v21, v9 offset:272
	ds_write_b32 v21, v10 offset:288
	ds_write_b32 v21, v11 offset:304
	ds_write_b32 v21, v4 offset:8192
	ds_write_b32 v21, v5 offset:8208
	ds_write_b32 v21, v6 offset:8224
	ds_write_b32 v21, v7 offset:8240
	ds_write_b32 v21, v0 offset:8448
	ds_write_b32 v21, v1 offset:8464
	ds_write_b32 v21, v2 offset:8480
	ds_write_b32 v21, v3 offset:8496
	s_mov_b64 exec, s[0:1]
	ds_read_b128 v[12:15], v22
	ds_read_b128 v[8:11], v22 offset:8192
	s_waitcnt lgkmcnt(0)
	global_store_dwordx4 v23, v[12:15], s[56:57] sc1
	global_store_dwordx4 v23, v[8:11], s[56:57] offset:2048 sc1

; DI u32x2 pk4(f32x4 v) { u32x2 r; r.x = pk2(v[0], v[1]); r.y = pk2(v[2], v[3]); return r; }
; DI size_t kf_off(int h, int nblk, int krow, int d) { return ((((size_t)h * nblk + (krow >> 5)) * 4 + (d >> 4)) * 64 + ((d >> 3) & 1) * 32 + (krow & 31)) * 8 + (d & 7); }
;     DI void operator()(const AccT& acc, const Unit& u, int wr, int wc, int fr, int fq, LAS unsigned char*) const {
;     ...
;                     if (isK) {
;                         bf16_t* kp = (bf16_t*)(ws + (isA ? WS_KA : WS_KB));
; #pragma unroll
;                         for (int bj = 0; bj < 2; ++bj)
; #pragma unroll
;                             for (int n = 0; n < 2; ++n) *(u32x2*)(kp + kf_off(h, krows >> 5, krow, 32 * bj + 16 * n + 4 * fq)) = pk4(v[bj][n]);
.LBB0_502:
	s_and_b64 vcc, exec, s[0:1]
	s_cbranch_vccz .LBB0_504
	v_lshl_add_u64 v[18:19], s[46:47], 0, v[18:19]
	v_lshlrev_b64 v[18:19], 8, v[18:19]
	v_and_or_b32 v17, v17, 31, v18
	v_lshl_add_u64 v[20:21], v[170:171], 0, s[48:49]
	v_or_b32_e32 v18, v17, v144
	v_lshl_add_u64 v[18:19], v[18:19], 4, v[20:21]
	s_waitcnt lgkmcnt(0)
	v_and_b32_e32 v20, 16, v226
	v_lshlrev_b32_e32 v21, 6, v20
	v_lshrrev_b32_e32 v20, 1, v20
	v_sub_u32_e32 v150, v21, v20
	v_lshl_add_u64 v[18:19], v[18:19], 0, v[150:151]
	v_cvt_pk_bf16_f32 v12, v12, v13
	v_cvt_pk_bf16_f32 v13, v14, v15
	v_cvt_pk_bf16_f32 v14, v8, v9
	v_cvt_pk_bf16_f32 v15, v10, v11
	v_cvt_pk_bf16_f32 v4, v4, v5
	v_cvt_pk_bf16_f32 v5, v6, v7
	v_cvt_pk_bf16_f32 v6, v0, v1
	v_cvt_pk_bf16_f32 v7, v2, v3
	s_nop 1
	v_permlane16_swap_b32_e32 v12, v14
	v_permlane16_swap_b32_e32 v13, v15
	v_permlane16_swap_b32_e32 v4, v6
	v_permlane16_swap_b32_e32 v5, v7
	global_store_dwordx4 v[18:19], v[12:15], off sc1
	global_store_dwordx4 v[18:19], v[4:7], off offset:2048 sc1

; DI u32x2 pk4(f32x4 v) { u32x2 r; r.x = pk2(v[0], v[1]); r.y = pk2(v[2], v[3]); return r; }
;     DI void operator()(const AccT& acc, const Unit& u, int wr, int wc, int fr, int fq, LAS unsigned char*) const {
;     ...
;                 if (kind == 0 || kind == 3) {
;                     bf16_t* q = (bf16_t*)(ws + (kind == 0 ? WS_QA : WS_QB)) + ((size_t)h * MTOK + row) * 64 + 4 * fq;
; #pragma unroll
;                     for (int bj = 0; bj < 2; ++bj)
; #pragma unroll
;                         for (int n = 0; n < 2; ++n) *(u32x2*)(q + 32 * bj + 16 * n) = pk4(v[bj][n] * QSCALE);
.LBB0_506:
	s_and_b64 vcc, exec, s[0:1]
	s_cbranch_vccz .LBB0_229
	v_ashrrev_i32_e32 v129, 31, v128
	s_add_u32 s0, s36, s29
	v_lshl_add_u64 v[128:129], s[54:55], 0, v[128:129]
	s_addc_u32 s1, s37, 0
	v_lshlrev_b64 v[128:129], 7, v[128:129]
	v_lshl_add_u64 v[128:129], s[0:1], 0, v[128:129]
	v_lshlrev_b32_e32 v150, 1, v152
	v_pk_mul_f32 v[126:127], v[126:127], s[26:27] op_sel_hi:[1,0]
	v_pk_mul_f32 v[124:125], v[124:125], s[26:27] op_sel_hi:[1,0]
	v_pk_mul_f32 v[122:123], v[122:123], s[26:27] op_sel_hi:[1,0]
	v_pk_mul_f32 v[120:121], v[120:121], s[26:27] op_sel_hi:[1,0]
	v_pk_mul_f32 v[118:119], v[118:119], s[26:27] op_sel_hi:[1,0]
	v_pk_mul_f32 v[116:117], v[116:117], s[26:27] op_sel_hi:[1,0]
	v_pk_mul_f32 v[114:115], v[114:115], s[26:27] op_sel_hi:[1,0]
	v_pk_mul_f32 v[112:113], v[112:113], s[26:27] op_sel_hi:[1,0]
	v_lshl_add_u64 v[128:129], v[128:129], 0, v[150:151]
	v_and_b32_e32 v150, 8, v150
	v_mul_u32_u24_e32 v150, 3, v150
	v_lshl_add_u64 v[128:129], v[128:129], 0, v[150:151]
	v_cvt_pk_bf16_f32 v124, v124, v125
	v_cvt_pk_bf16_f32 v125, v126, v127
	v_cvt_pk_bf16_f32 v126, v120, v121
	v_cvt_pk_bf16_f32 v127, v122, v123
	v_cvt_pk_bf16_f32 v116, v116, v117
	v_cvt_pk_bf16_f32 v117, v118, v119
	v_cvt_pk_bf16_f32 v118, v112, v113
	v_cvt_pk_bf16_f32 v119, v114, v115
	s_nop 1
	v_permlane16_swap_b32_e32 v124, v126
	v_permlane16_swap_b32_e32 v125, v127
	v_permlane16_swap_b32_e32 v116, v118
	v_permlane16_swap_b32_e32 v117, v119
	global_store_dwordx4 v[128:129], v[124:127], off sc1
	global_store_dwordx4 v[128:129], v[116:119], off offset:64 sc1
	s_and_b64 vcc, exec, s[6:7]
	s_cbranch_vccz .LBB0_230

; DI u32x2 pk4(f32x4 v) { u32x2 r; r.x = pk2(v[0], v[1]); r.y = pk2(v[2], v[3]); return r; }
;     DI void operator()(const AccT& acc, const Unit& u, int wr, int wc, int fr, int fq, LAS unsigned char*) const {
;     ...
;                 if (kind == 0 || kind == 3) {
;                     bf16_t* q = (bf16_t*)(ws + (kind == 0 ? WS_QA : WS_QB)) + ((size_t)h * MTOK + row) * 64 + 4 * fq;
; #pragma unroll
;                     for (int bj = 0; bj < 2; ++bj)
; #pragma unroll
;                         for (int n = 0; n < 2; ++n) *(u32x2*)(q + 32 * bj + 16 * n) = pk4(v[bj][n] * QSCALE);
.LBB0_510:
	s_and_b64 vcc, exec, s[0:1]
	s_cbranch_vccz .LBB0_275
	v_ashrrev_i32_e32 v113, 31, v112
	s_add_u32 s0, s36, s29
	v_lshl_add_u64 v[112:113], s[54:55], 0, v[112:113]
	s_addc_u32 s1, s37, 0
	v_lshlrev_b64 v[112:113], 7, v[112:113]
	v_lshl_add_u64 v[112:113], s[0:1], 0, v[112:113]
	v_lshlrev_b32_e32 v150, 1, v152
	v_pk_mul_f32 v[110:111], v[110:111], s[26:27] op_sel_hi:[1,0]
	v_pk_mul_f32 v[108:109], v[108:109], s[26:27] op_sel_hi:[1,0]
	v_pk_mul_f32 v[106:107], v[106:107], s[26:27] op_sel_hi:[1,0]
	v_pk_mul_f32 v[104:105], v[104:105], s[26:27] op_sel_hi:[1,0]
	v_pk_mul_f32 v[102:103], v[102:103], s[26:27] op_sel_hi:[1,0]
	v_pk_mul_f32 v[100:101], v[100:101], s[26:27] op_sel_hi:[1,0]
	v_pk_mul_f32 v[98:99], v[98:99], s[26:27] op_sel_hi:[1,0]
	v_pk_mul_f32 v[96:97], v[96:97], s[26:27] op_sel_hi:[1,0]
	v_lshl_add_u64 v[112:113], v[112:113], 0, v[150:151]
	v_and_b32_e32 v150, 8, v150
	v_mul_u32_u24_e32 v150, 3, v150
	v_lshl_add_u64 v[112:113], v[112:113], 0, v[150:151]
	v_cvt_pk_bf16_f32 v108, v108, v109
	v_cvt_pk_bf16_f32 v109, v110, v111
	v_cvt_pk_bf16_f32 v110, v104, v105
	v_cvt_pk_bf16_f32 v111, v106, v107
	v_cvt_pk_bf16_f32 v100, v100, v101
	v_cvt_pk_bf16_f32 v101, v102, v103
	v_cvt_pk_bf16_f32 v102, v96, v97
	v_cvt_pk_bf16_f32 v103, v98, v99
	s_nop 1
	v_permlane16_swap_b32_e32 v108, v110
	v_permlane16_swap_b32_e32 v109, v111
	v_permlane16_swap_b32_e32 v100, v102
	v_permlane16_swap_b32_e32 v101, v103
	global_store_dwordx4 v[112:113], v[108:111], off sc1
	global_store_dwordx4 v[112:113], v[100:103], off offset:64 sc1
	s_and_b64 vcc, exec, s[6:7]
	s_cbranch_vccz .LBB0_276

; DI u32x2 pk4(f32x4 v) { u32x2 r; r.x = pk2(v[0], v[1]); r.y = pk2(v[2], v[3]); return r; }
;     DI void operator()(const AccT& acc, const Unit& u, int wr, int wc, int fr, int fq, LAS unsigned char*) const {
;     ...
;                 if (kind == 0 || kind == 3) {
;                     bf16_t* q = (bf16_t*)(ws + (kind == 0 ? WS_QA : WS_QB)) + ((size_t)h * MTOK + row) * 64 + 4 * fq;
; #pragma unroll
;                     for (int bj = 0; bj < 2; ++bj)
; #pragma unroll
;                         for (int n = 0; n < 2; ++n) *(u32x2*)(q + 32 * bj + 16 * n) = pk4(v[bj][n] * QSCALE);
.LBB0_514:
	s_and_b64 vcc, exec, s[0:1]
	s_cbranch_vccz .LBB0_321
	v_ashrrev_i32_e32 v97, 31, v96
	s_add_u32 s0, s36, s29
	v_lshl_add_u64 v[96:97], s[54:55], 0, v[96:97]
	s_addc_u32 s1, s37, 0
	v_lshlrev_b64 v[96:97], 7, v[96:97]
	v_lshl_add_u64 v[96:97], s[0:1], 0, v[96:97]
	v_lshlrev_b32_e32 v150, 1, v152
	v_pk_mul_f32 v[94:95], v[94:95], s[26:27] op_sel_hi:[1,0]
	v_pk_mul_f32 v[92:93], v[92:93], s[26:27] op_sel_hi:[1,0]
	v_pk_mul_f32 v[90:91], v[90:91], s[26:27] op_sel_hi:[1,0]
	v_pk_mul_f32 v[88:89], v[88:89], s[26:27] op_sel_hi:[1,0]
	v_pk_mul_f32 v[86:87], v[86:87], s[26:27] op_sel_hi:[1,0]
	v_pk_mul_f32 v[84:85], v[84:85], s[26:27] op_sel_hi:[1,0]
	v_pk_mul_f32 v[82:83], v[82:83], s[26:27] op_sel_hi:[1,0]
	v_pk_mul_f32 v[80:81], v[80:81], s[26:27] op_sel_hi:[1,0]
	v_lshl_add_u64 v[96:97], v[96:97], 0, v[150:151]
	v_and_b32_e32 v150, 8, v150
	v_mul_u32_u24_e32 v150, 3, v150
	v_lshl_add_u64 v[96:97], v[96:97], 0, v[150:151]
	v_cvt_pk_bf16_f32 v92, v92, v93
	v_cvt_pk_bf16_f32 v93, v94, v95
	v_cvt_pk_bf16_f32 v94, v88, v89
	v_cvt_pk_bf16_f32 v95, v90, v91
	v_cvt_pk_bf16_f32 v84, v84, v85
	v_cvt_pk_bf16_f32 v85, v86, v87
	v_cvt_pk_bf16_f32 v86, v80, v81
	v_cvt_pk_bf16_f32 v87, v82, v83
	s_nop 1
	v_permlane16_swap_b32_e32 v92, v94
	v_permlane16_swap_b32_e32 v93, v95
	v_permlane16_swap_b32_e32 v84, v86
	v_permlane16_swap_b32_e32 v85, v87
	global_store_dwordx4 v[96:97], v[92:95], off sc1
	global_store_dwordx4 v[96:97], v[84:87], off offset:64 sc1
	s_and_b64 vcc, exec, s[6:7]
	s_cbranch_vccz .LBB0_322

; DI u32x2 pk4(f32x4 v) { u32x2 r; r.x = pk2(v[0], v[1]); r.y = pk2(v[2], v[3]); return r; }
;     DI void operator()(const AccT& acc, const Unit& u, int wr, int wc, int fr, int fq, LAS unsigned char*) const {
;     ...
;                 if (kind == 0 || kind == 3) {
;                     bf16_t* q = (bf16_t*)(ws + (kind == 0 ? WS_QA : WS_QB)) + ((size_t)h * MTOK + row) * 64 + 4 * fq;
; #pragma unroll
;                     for (int bj = 0; bj < 2; ++bj)
; #pragma unroll
;                         for (int n = 0; n < 2; ++n) *(u32x2*)(q + 32 * bj + 16 * n) = pk4(v[bj][n] * QSCALE);
.LBB0_518:
	s_and_b64 vcc, exec, s[0:1]
	s_cbranch_vccz .LBB0_367
	v_ashrrev_i32_e32 v81, 31, v80
	s_add_u32 s0, s36, s29
	v_lshl_add_u64 v[80:81], s[54:55], 0, v[80:81]
	s_addc_u32 s1, s37, 0
	v_lshlrev_b64 v[80:81], 7, v[80:81]
	v_lshl_add_u64 v[80:81], s[0:1], 0, v[80:81]
	v_lshlrev_b32_e32 v150, 1, v152
	v_pk_mul_f32 v[78:79], v[78:79], s[26:27] op_sel_hi:[1,0]
	v_pk_mul_f32 v[76:77], v[76:77], s[26:27] op_sel_hi:[1,0]
	v_pk_mul_f32 v[74:75], v[74:75], s[26:27] op_sel_hi:[1,0]
	v_pk_mul_f32 v[72:73], v[72:73], s[26:27] op_sel_hi:[1,0]
	v_pk_mul_f32 v[70:71], v[70:71], s[26:27] op_sel_hi:[1,0]
	v_pk_mul_f32 v[68:69], v[68:69], s[26:27] op_sel_hi:[1,0]
	v_pk_mul_f32 v[66:67], v[66:67], s[26:27] op_sel_hi:[1,0]
	v_pk_mul_f32 v[64:65], v[64:65], s[26:27] op_sel_hi:[1,0]
	v_lshl_add_u64 v[80:81], v[80:81], 0, v[150:151]
	v_and_b32_e32 v150, 8, v150
	v_mul_u32_u24_e32 v150, 3, v150
	v_lshl_add_u64 v[80:81], v[80:81], 0, v[150:151]
	v_cvt_pk_bf16_f32 v76, v76, v77
	v_cvt_pk_bf16_f32 v77, v78, v79
	v_cvt_pk_bf16_f32 v78, v72, v73
	v_cvt_pk_bf16_f32 v79, v74, v75
	v_cvt_pk_bf16_f32 v68, v68, v69
	v_cvt_pk_bf16_f32 v69, v70, v71
	v_cvt_pk_bf16_f32 v70, v64, v65
	v_cvt_pk_bf16_f32 v71, v66, v67
	s_nop 1
	v_permlane16_swap_b32_e32 v76, v78
	v_permlane16_swap_b32_e32 v77, v79
	v_permlane16_swap_b32_e32 v68, v70
	v_permlane16_swap_b32_e32 v69, v71
	global_store_dwordx4 v[80:81], v[76:79], off sc1
	global_store_dwordx4 v[80:81], v[68:71], off offset:64 sc1
	s_and_b64 vcc, exec, s[6:7]
	s_cbranch_vccz .LBB0_368

; DI u32x2 pk4(f32x4 v) { u32x2 r; r.x = pk2(v[0], v[1]); r.y = pk2(v[2], v[3]); return r; }
;     DI void operator()(const AccT& acc, const Unit& u, int wr, int wc, int fr, int fq, LAS unsigned char*) const {
;     ...
;                 if (kind == 0 || kind == 3) {
;                     bf16_t* q = (bf16_t*)(ws + (kind == 0 ? WS_QA : WS_QB)) + ((size_t)h * MTOK + row) * 64 + 4 * fq;
; #pragma unroll
;                     for (int bj = 0; bj < 2; ++bj)
; #pragma unroll
;                         for (int n = 0; n < 2; ++n) *(u32x2*)(q + 32 * bj + 16 * n) = pk4(v[bj][n] * QSCALE);
.LBB0_522:
	s_and_b64 vcc, exec, s[0:1]
	s_cbranch_vccz .LBB0_413
	v_ashrrev_i32_e32 v65, 31, v64
	s_add_u32 s0, s36, s29
	v_lshl_add_u64 v[64:65], s[54:55], 0, v[64:65]
	s_addc_u32 s1, s37, 0
	v_lshlrev_b64 v[64:65], 7, v[64:65]
	v_lshl_add_u64 v[64:65], s[0:1], 0, v[64:65]
	v_lshlrev_b32_e32 v150, 1, v152
	v_pk_mul_f32 v[46:47], v[46:47], s[26:27] op_sel_hi:[1,0]
	v_pk_mul_f32 v[44:45], v[44:45], s[26:27] op_sel_hi:[1,0]
	v_pk_mul_f32 v[42:43], v[42:43], s[26:27] op_sel_hi:[1,0]
	v_pk_mul_f32 v[40:41], v[40:41], s[26:27] op_sel_hi:[1,0]
	v_pk_mul_f32 v[38:39], v[38:39], s[26:27] op_sel_hi:[1,0]
	v_pk_mul_f32 v[36:37], v[36:37], s[26:27] op_sel_hi:[1,0]
	v_pk_mul_f32 v[34:35], v[34:35], s[26:27] op_sel_hi:[1,0]
	v_pk_mul_f32 v[32:33], v[32:33], s[26:27] op_sel_hi:[1,0]
	v_lshl_add_u64 v[64:65], v[64:65], 0, v[150:151]
	v_and_b32_e32 v150, 8, v150
	v_mul_u32_u24_e32 v150, 3, v150
	v_lshl_add_u64 v[64:65], v[64:65], 0, v[150:151]
	v_cvt_pk_bf16_f32 v44, v44, v45
	v_cvt_pk_bf16_f32 v45, v46, v47
	v_cvt_pk_bf16_f32 v46, v40, v41
	v_cvt_pk_bf16_f32 v47, v42, v43
	v_cvt_pk_bf16_f32 v36, v36, v37
	v_cvt_pk_bf16_f32 v37, v38, v39
	v_cvt_pk_bf16_f32 v38, v32, v33
	v_cvt_pk_bf16_f32 v39, v34, v35
	s_nop 1
	v_permlane16_swap_b32_e32 v44, v46
	v_permlane16_swap_b32_e32 v45, v47
	v_permlane16_swap_b32_e32 v36, v38
	v_permlane16_swap_b32_e32 v37, v39
	global_store_dwordx4 v[64:65], v[44:47], off sc1
	global_store_dwordx4 v[64:65], v[36:39], off offset:64 sc1
	s_and_b64 vcc, exec, s[6:7]
	s_cbranch_vccz .LBB0_414

; DI u32x2 pk4(f32x4 v) { u32x2 r; r.x = pk2(v[0], v[1]); r.y = pk2(v[2], v[3]); return r; }
;     DI void operator()(const AccT& acc, const Unit& u, int wr, int wc, int fr, int fq, LAS unsigned char*) const {
;     ...
;                 if (kind == 0 || kind == 3) {
;                     bf16_t* q = (bf16_t*)(ws + (kind == 0 ? WS_QA : WS_QB)) + ((size_t)h * MTOK + row) * 64 + 4 * fq;
; #pragma unroll
;                     for (int bj = 0; bj < 2; ++bj)
; #pragma unroll
;                         for (int n = 0; n < 2; ++n) *(u32x2*)(q + 32 * bj + 16 * n) = pk4(v[bj][n] * QSCALE);
.LBB0_526:
	s_and_b64 vcc, exec, s[0:1]
	s_cbranch_vccz .LBB0_459
	v_ashrrev_i32_e32 v33, 31, v32
	s_add_u32 s0, s36, s29
	v_lshl_add_u64 v[32:33], s[54:55], 0, v[32:33]
	s_addc_u32 s1, s37, 0
	v_lshlrev_b64 v[32:33], 7, v[32:33]
	v_lshl_add_u64 v[32:33], s[0:1], 0, v[32:33]
	v_lshlrev_b32_e32 v150, 1, v152
	v_pk_mul_f32 v[30:31], v[30:31], s[26:27] op_sel_hi:[1,0]
	v_pk_mul_f32 v[28:29], v[28:29], s[26:27] op_sel_hi:[1,0]
	v_pk_mul_f32 v[26:27], v[26:27], s[26:27] op_sel_hi:[1,0]
	v_pk_mul_f32 v[24:25], v[24:25], s[26:27] op_sel_hi:[1,0]
	v_pk_mul_f32 v[22:23], v[22:23], s[26:27] op_sel_hi:[1,0]
	v_pk_mul_f32 v[20:21], v[20:21], s[26:27] op_sel_hi:[1,0]
	v_pk_mul_f32 v[18:19], v[18:19], s[26:27] op_sel_hi:[1,0]
	v_pk_mul_f32 v[16:17], v[16:17], s[26:27] op_sel_hi:[1,0]
	v_lshl_add_u64 v[32:33], v[32:33], 0, v[150:151]
	v_and_b32_e32 v150, 8, v150
	v_mul_u32_u24_e32 v150, 3, v150
	v_lshl_add_u64 v[32:33], v[32:33], 0, v[150:151]
	v_cvt_pk_bf16_f32 v28, v28, v29
	v_cvt_pk_bf16_f32 v29, v30, v31
	v_cvt_pk_bf16_f32 v30, v24, v25
	v_cvt_pk_bf16_f32 v31, v26, v27
	v_cvt_pk_bf16_f32 v20, v20, v21
	v_cvt_pk_bf16_f32 v21, v22, v23
	v_cvt_pk_bf16_f32 v22, v16, v17
	v_cvt_pk_bf16_f32 v23, v18, v19
	s_nop 1
	v_permlane16_swap_b32_e32 v28, v30
	v_permlane16_swap_b32_e32 v29, v31
	v_permlane16_swap_b32_e32 v20, v22
	v_permlane16_swap_b32_e32 v21, v23
	global_store_dwordx4 v[32:33], v[28:31], off sc1
	global_store_dwordx4 v[32:33], v[20:23], off offset:64 sc1
	s_and_b64 vcc, exec, s[6:7]
	s_cbranch_vccz .LBB0_460

; DI u32x2 pk4(f32x4 v) { u32x2 r; r.x = pk2(v[0], v[1]); r.y = pk2(v[2], v[3]); return r; }
;     DI void operator()(const AccT& acc, const Unit& u, int wr, int wc, int fr, int fq, LAS unsigned char*) const {
;     ...
;                 if (kind == 0 || kind == 3) {
;                     bf16_t* q = (bf16_t*)(ws + (kind == 0 ? WS_QA : WS_QB)) + ((size_t)h * MTOK + row) * 64 + 4 * fq;
; #pragma unroll
;                     for (int bj = 0; bj < 2; ++bj)
; #pragma unroll
;                         for (int n = 0; n < 2; ++n) *(u32x2*)(q + 32 * bj + 16 * n) = pk4(v[bj][n] * QSCALE);
.LBB0_530:
	s_and_b64 vcc, exec, s[0:1]
	s_cbranch_vccz .LBB0_505
	v_ashrrev_i32_e32 v17, 31, v16
	s_add_u32 s0, s36, s29
	v_lshl_add_u64 v[16:17], s[54:55], 0, v[16:17]
	s_addc_u32 s1, s37, 0
	v_lshlrev_b64 v[16:17], 7, v[16:17]
	v_lshl_add_u64 v[16:17], s[0:1], 0, v[16:17]
	v_lshlrev_b32_e32 v150, 1, v152
	v_pk_mul_f32 v[14:15], v[14:15], s[26:27] op_sel_hi:[1,0]
	v_pk_mul_f32 v[12:13], v[12:13], s[26:27] op_sel_hi:[1,0]
	v_pk_mul_f32 v[10:11], v[10:11], s[26:27] op_sel_hi:[1,0]
	v_pk_mul_f32 v[8:9], v[8:9], s[26:27] op_sel_hi:[1,0]
	v_pk_mul_f32 v[6:7], v[6:7], s[26:27] op_sel_hi:[1,0]
	v_pk_mul_f32 v[4:5], v[4:5], s[26:27] op_sel_hi:[1,0]
	v_pk_mul_f32 v[2:3], v[2:3], s[26:27] op_sel_hi:[1,0]
	v_pk_mul_f32 v[0:1], v[0:1], s[26:27] op_sel_hi:[1,0]
	v_lshl_add_u64 v[16:17], v[16:17], 0, v[150:151]
	v_and_b32_e32 v150, 8, v150
	v_mul_u32_u24_e32 v150, 3, v150
	v_lshl_add_u64 v[16:17], v[16:17], 0, v[150:151]
	v_cvt_pk_bf16_f32 v12, v12, v13
	v_cvt_pk_bf16_f32 v13, v14, v15
	v_cvt_pk_bf16_f32 v14, v8, v9
	v_cvt_pk_bf16_f32 v15, v10, v11
	v_cvt_pk_bf16_f32 v4, v4, v5
	v_cvt_pk_bf16_f32 v5, v6, v7
	v_cvt_pk_bf16_f32 v6, v0, v1
	v_cvt_pk_bf16_f32 v7, v2, v3
	s_nop 1
	v_permlane16_swap_b32_e32 v12, v14
	v_permlane16_swap_b32_e32 v13, v15
	v_permlane16_swap_b32_e32 v4, v6
	v_permlane16_swap_b32_e32 v5, v7
	global_store_dwordx4 v[16:17], v[12:15], off sc1
	global_store_dwordx4 v[16:17], v[4:7], off offset:64 sc1
	s_andn2_b64 vcc, exec, s[4:5]
	s_mov_b64 s[0:1], -1
	s_cbranch_vccnz .LBB0_100

; DI void kc_item(const float* src, int past, int nh, int band, int krows, bf16_t* KF, int item, int lane) {
;     const int nrb = past / 32, h = item % nh, rb = (item / nh) % nrb, b = item / (nh * nrb), r = lane & 31, hh = lane >> 5;
;     const float* sp = src + (((size_t)b * past + rb * 32 + r) * nh + h) * 64 + 8 * hh;
;     bf16_t* d = KF + (((size_t)h * (krows >> 5) + ((SEQ + b * band) >> 5) + rb) * 4 * 64 + lane) * 8;
; #pragma unroll
;     for (int ds = 0; ds < 4; ++ds) { const f32x4 v0 = *(const f32x4*)(sp + 16 * ds), v1 = *(const f32x4*)(sp + 16 * ds + 4);
;         u32x4 o; o.x = pk2(v0[0], v0[1]); o.y = pk2(v0[2], v0[3]); o.z = pk2(v1[0], v1[1]); o.w = pk2(v1[2], v1[3]);
;         *(u32x4*)(d + ds * 512) = o; }
; }
; DI void prologue_b(KArgs ap, int gw, int NGW, int lane) {
;     ...
;     for (int it = gw; it < NSTREAM * 16 * 8; it += NGW) kc_item(cak, 512, 8, 576, KA_ROWS, (bf16_t*)(ws + WS_KA), it, lane);
.LBB0_537:
	s_ashr_i32 s11, s10, 31
	s_lshr_b32 s18, s11, 29
	s_lshr_b32 s11, s11, 25
	s_add_i32 s18, s10, s18
	s_add_i32 s11, s10, s11
	s_ashr_i32 s26, s18, 3
	s_and_b32 s19, s18, -8
	s_ashr_i32 s18, s11, 7
	s_lshr_b32 s11, s26, 28
	s_add_i32 s11, s26, s11
	s_and_b32 s11, s11, -16
	s_sub_i32 s20, s10, s19
	s_ashr_i32 s19, s18, 31
	s_sub_i32 s11, s26, s11
	s_ashr_i32 s21, s20, 31
	s_lshl_b64 s[22:23], s[18:19], 20
	s_lshl_b32 s19, s11, 5
	s_lshl_b64 s[24:25], s[20:21], 8
	s_ashr_i32 s21, s19, 31
	v_or_b32_e32 v6, s19, v0
	v_mov_b32_e32 v7, s21
	v_lshlrev_b64 v[6:7], 11, v[6:7]
	v_lshl_add_u64 v[6:7], v[2:3], 0, v[6:7]
	v_lshl_add_u64 v[6:7], v[6:7], 0, s[22:23]
	v_lshl_add_u64 v[14:15], v[6:7], 0, s[24:25]
	global_load_dwordx4 v[6:9], v[14:15], off
	global_load_dwordx4 v[10:13], v[14:15], off offset:16
	global_load_dwordx4 v[44:47], v[14:15], off offset:64
	global_load_dwordx4 v[48:51], v[14:15], off offset:80
	global_load_dwordx4 v[52:55], v[14:15], off offset:128
	global_load_dwordx4 v[56:59], v[14:15], off offset:144
	global_load_dwordx4 v[60:63], v[14:15], off offset:192
	global_load_dwordx4 v[64:67], v[14:15], off offset:208
	s_mulk_i32 s18, 0x240
	s_addk_i32 s18, 0x4000
	s_ashr_i32 s18, s18, 5
	s_mul_hi_i32 s19, s20, 0x440
	s_mulk_i32 s20, 0x440
	s_ashr_i32 s21, s18, 31
	s_ashr_i32 s22, s11, 31
	s_add_u32 s11, s20, s11
	s_addc_u32 s19, s19, s22
	s_add_u32 s18, s11, s18
	s_addc_u32 s19, s19, s21
	s_lshl_b64 s[18:19], s[18:19], 12
	v_lshl_add_u64 v[16:17], v[4:5], 0, s[18:19]
	s_add_i32 s10, s10, s17
	s_cmpk_gt_i32 s10, 0xfff
	s_waitcnt vmcnt(6)
	v_cvt_pk_bf16_f32 v6, v6, v7
	v_cvt_pk_bf16_f32 v7, v8, v9
	v_cvt_pk_bf16_f32 v8, v10, v11
	v_cvt_pk_bf16_f32 v9, v12, v13
	global_store_dwordx4 v[16:17], v[6:9], off sc1
	s_waitcnt vmcnt(5)
	v_cvt_pk_bf16_f32 v44, v44, v45
	v_cvt_pk_bf16_f32 v45, v46, v47
	v_cvt_pk_bf16_f32 v46, v48, v49
	v_cvt_pk_bf16_f32 v47, v50, v51
	global_store_dwordx4 v[16:17], v[44:47], off offset:1024 sc1
	s_waitcnt vmcnt(4)
	v_cvt_pk_bf16_f32 v52, v52, v53
	v_cvt_pk_bf16_f32 v53, v54, v55
	v_cvt_pk_bf16_f32 v54, v56, v57
	v_cvt_pk_bf16_f32 v55, v58, v59
	global_store_dwordx4 v[16:17], v[52:55], off offset:2048 sc1
	s_waitcnt vmcnt(3)
	v_cvt_pk_bf16_f32 v60, v60, v61
	v_cvt_pk_bf16_f32 v61, v62, v63
	v_cvt_pk_bf16_f32 v62, v64, v65
	v_cvt_pk_bf16_f32 v63, v66, v67
	global_store_dwordx4 v[16:17], v[60:63], off offset:3072 sc1
	s_cbranch_scc0 .LBB0_537

; DI void kc_item(const float* src, int past, int nh, int band, int krows, bf16_t* KF, int item, int lane) {
;     const int nrb = past / 32, h = item % nh, rb = (item / nh) % nrb, b = item / (nh * nrb), r = lane & 31, hh = lane >> 5;
;     const float* sp = src + (((size_t)b * past + rb * 32 + r) * nh + h) * 64 + 8 * hh;
;     bf16_t* d = KF + (((size_t)h * (krows >> 5) + ((SEQ + b * band) >> 5) + rb) * 4 * 64 + lane) * 8;
; #pragma unroll
;     for (int ds = 0; ds < 4; ++ds) { const f32x4 v0 = *(const f32x4*)(sp + 16 * ds), v1 = *(const f32x4*)(sp + 16 * ds + 4);
;         u32x4 o; o.x = pk2(v0[0], v0[1]); o.y = pk2(v0[2], v0[3]); o.z = pk2(v1[0], v1[1]); o.w = pk2(v1[2], v1[3]);
;         *(u32x4*)(d + ds * 512) = o; }
; }
; DI void prologue_b(KArgs ap, int gw, int NGW, int lane) {
;     ...
;     for (int it = gw; it < NSTREAM * 4 * 2; it += NGW) kc_item(cbk, 128, 2, 192, KB_ROWS, (bf16_t*)(ws + WS_KB), it, lane);
.LBB0_540:
	s_lshr_b32 s7, s6, 31
	s_ashr_i32 s18, s6, 31
	s_add_i32 s7, s6, s7
	s_lshr_b32 s18, s18, 29
	s_ashr_i32 s26, s7, 1
	s_and_b32 s7, s7, -2
	s_add_i32 s19, s6, s18
	s_sub_i32 s18, s6, s7
	s_lshr_b32 s7, s26, 30
	s_add_i32 s7, s26, s7
	s_and_b32 s7, s7, -4
	s_ashr_i32 s20, s19, 3
	s_ashr_i32 s19, s18, 31
	s_sub_i32 s7, s26, s7
	s_ashr_i32 s21, s20, 31
	s_lshl_b64 s[24:25], s[18:19], 8
	s_lshl_b32 s19, s7, 5
	s_lshl_b64 s[22:23], s[20:21], 16
	s_ashr_i32 s21, s19, 31
	v_or_b32_e32 v6, s19, v0
	v_mov_b32_e32 v7, s21
	v_lshlrev_b64 v[6:7], 9, v[6:7]
	v_lshl_add_u64 v[6:7], v[2:3], 0, v[6:7]
	v_lshl_add_u64 v[6:7], v[6:7], 0, s[22:23]
	v_lshl_add_u64 v[14:15], v[6:7], 0, s[24:25]
	global_load_dwordx4 v[6:9], v[14:15], off
	global_load_dwordx4 v[10:13], v[14:15], off offset:16
	global_load_dwordx4 v[44:47], v[14:15], off offset:64
	global_load_dwordx4 v[48:51], v[14:15], off offset:80
	global_load_dwordx4 v[52:55], v[14:15], off offset:128
	global_load_dwordx4 v[56:59], v[14:15], off offset:144
	global_load_dwordx4 v[60:63], v[14:15], off offset:192
	global_load_dwordx4 v[64:67], v[14:15], off offset:208
	s_mulk_i32 s20, 0xc0
	s_addk_i32 s20, 0x4000
	s_ashr_i32 s20, s20, 5
	s_mul_hi_i32 s19, s18, 0x2c0
	s_mulk_i32 s18, 0x2c0
	s_ashr_i32 s21, s20, 31
	s_ashr_i32 s22, s7, 31
	s_add_u32 s7, s18, s7
	s_addc_u32 s19, s19, s22
	s_add_u32 s18, s7, s20
	s_addc_u32 s19, s19, s21
	s_lshl_b64 s[18:19], s[18:19], 12
	v_lshl_add_u64 v[16:17], v[4:5], 0, s[18:19]
	s_add_i32 s6, s6, s17
	s_cmpk_gt_i32 s6, 0xff
	s_waitcnt vmcnt(6)
	v_cvt_pk_bf16_f32 v6, v6, v7
	v_cvt_pk_bf16_f32 v7, v8, v9
	v_cvt_pk_bf16_f32 v8, v10, v11
	v_cvt_pk_bf16_f32 v9, v12, v13
	global_store_dwordx4 v[16:17], v[6:9], off sc1
	s_waitcnt vmcnt(5)
	v_cvt_pk_bf16_f32 v44, v44, v45
	v_cvt_pk_bf16_f32 v45, v46, v47
	v_cvt_pk_bf16_f32 v46, v48, v49
	v_cvt_pk_bf16_f32 v47, v50, v51
	global_store_dwordx4 v[16:17], v[44:47], off offset:1024 sc1
	s_waitcnt vmcnt(4)
	v_cvt_pk_bf16_f32 v52, v52, v53
	v_cvt_pk_bf16_f32 v53, v54, v55
	v_cvt_pk_bf16_f32 v54, v56, v57
	v_cvt_pk_bf16_f32 v55, v58, v59
	global_store_dwordx4 v[16:17], v[52:55], off offset:2048 sc1
	s_waitcnt vmcnt(3)
	v_cvt_pk_bf16_f32 v60, v60, v61
	v_cvt_pk_bf16_f32 v61, v62, v63
	v_cvt_pk_bf16_f32 v62, v64, v65
	v_cvt_pk_bf16_f32 v63, v66, v67
	global_store_dwordx4 v[16:17], v[60:63], off offset:3072 sc1
	s_cbranch_scc0 .LBB0_540

; DI size_t vf_off(int h, int nblk, int krow, int d) { const int kk = krow & 31; return (((((size_t)h * nblk + (krow >> 5)) * 2 + (d >> 5)) * 2 + (kk >> 4)) * 64 + ((kk >> 2) & 1) * 32 + (d & 31)) * 8 + 4 * ((kk >> 3) & 1) + (kk & 3); }
; DI void vt_item(const float* src, int past, int nh, int band, int krows, bf16_t* VT, int item, int lane) {
;     const int nrb = past / 32, rb = item % nrb, h = (item / nrb) % nh, b = item / (nrb * nh), r0 = rb * 32;
;     float v[32];
; #pragma unroll
;     for (int i = 0; i < 32; ++i) v[i] = src[(((size_t)b * past + r0 + i) * nh + h) * 64 + lane];
;     const int krow = SEQ + b * band + r0;
; #pragma unroll
;     for (int t = 0; t < 2; ++t)
; #pragma unroll
;         for (int hh = 0; hh < 2; ++hh) { const int k0 = 16 * t + 4 * hh; u32x4 o; o.x = pk2(v[k0], v[k0 + 1]); o.y = pk2(v[k0 + 2], v[k0 + 3]); o.z = pk2(v[k0 + 8], v[k0 + 9]); o.w = pk2(v[k0 + 10], v[k0 + 11]);
;             *(u32x4*)(VT + vf_off(h, krows >> 5, krow + k0, lane)) = o; }
; }
; DI void prologue_b(KArgs ap, int gw, int NGW, int lane) {
;     ...
;     for (int it = gw; it < NSTREAM * 8 * 16; it += NGW) vt_item(cav, 512, 8, 576, KA_ROWS, (bf16_t*)(ws + WS_VTA), it, lane);
.LBB0_543:
	s_ashr_i32 s4, s34, 31
	s_lshr_b32 s5, s4, 28
	s_lshr_b32 s4, s4, 25
	s_add_i32 s5, s34, s5
	s_add_i32 s4, s34, s4
	s_ashr_i32 s35, s5, 4
	s_ashr_i32 s4, s4, 7
	s_lshr_b32 s6, s35, 29
	s_lshl_b32 s44, s35, 9
	s_ashr_i32 s5, s4, 31
	s_add_i32 s43, s35, s6
	s_sub_i32 s42, s12, s44
	s_lshl_b64 s[6:7], s[4:5], 20
	s_and_b32 s5, s43, -8
	s_ashr_i32 s43, s42, 31
	v_lshl_add_u64 v[6:7], v[2:3], 0, s[6:7]
	s_sub_i32 s6, s35, s5
	s_lshl_b64 s[42:43], s[42:43], 11
	s_ashr_i32 s7, s6, 31
	v_lshl_add_u64 v[6:7], v[6:7], 0, s[42:43]
	s_lshl_b64 s[42:43], s[6:7], 8
	v_lshl_add_u64 v[6:7], v[6:7], 0, s[42:43]
	v_add_co_u32_e32 v8, vcc, s18, v6
	global_load_dword v1, v[6:7], off
	global_load_dword v36, v[6:7], off offset:2048
	v_addc_co_u32_e32 v9, vcc, 0, v7, vcc
	v_add_co_u32_e32 v10, vcc, s19, v6
	s_mulk_i32 s4, 0x240
	s_nop 0
	v_addc_co_u32_e32 v11, vcc, 0, v7, vcc
	v_add_co_u32_e32 v12, vcc, s20, v6
	s_sub_i32 s4, s4, s44
	s_nop 0
	v_addc_co_u32_e32 v13, vcc, 0, v7, vcc
	v_add_co_u32_e32 v14, vcc, s21, v6
	s_add_i32 s4, s12, s4
	s_nop 0
	v_addc_co_u32_e32 v15, vcc, 0, v7, vcc
	v_add_co_u32_e32 v16, vcc, s22, v6
	s_addk_i32 s4, 0x4000
	s_nop 0
	v_addc_co_u32_e32 v17, vcc, 0, v7, vcc
	v_add_co_u32_e32 v18, vcc, s23, v6
	s_ashr_i32 s4, s4, 5
	s_nop 0
	v_addc_co_u32_e32 v19, vcc, 0, v7, vcc
	v_add_co_u32_e32 v20, vcc, s24, v6
	s_mul_hi_i32 s5, s6, 0x440
	s_nop 0
	v_addc_co_u32_e32 v21, vcc, 0, v7, vcc
	v_add_co_u32_e32 v22, vcc, s25, v6
	s_mulk_i32 s6, 0x440
	s_nop 0
	v_addc_co_u32_e32 v23, vcc, 0, v7, vcc
	v_add_co_u32_e32 v24, vcc, s26, v6
	s_ashr_i32 s7, s4, 31
	s_nop 0
	v_addc_co_u32_e32 v25, vcc, 0, v7, vcc
	v_add_co_u32_e32 v26, vcc, s27, v6
	s_add_u32 s4, s6, s4
	s_nop 0
	v_addc_co_u32_e32 v27, vcc, 0, v7, vcc
	v_add_co_u32_e32 v28, vcc, s28, v6
	s_addc_u32 s5, s5, s7
	s_nop 0
	v_addc_co_u32_e32 v29, vcc, 0, v7, vcc
	v_add_co_u32_e32 v30, vcc, s29, v6
	s_add_i32 s34, s34, s17
	s_nop 0
	v_addc_co_u32_e32 v31, vcc, 0, v7, vcc
	v_add_co_u32_e32 v32, vcc, s30, v6
	s_add_i32 s12, s12, s13
	s_nop 0
	v_addc_co_u32_e32 v33, vcc, 0, v7, vcc
	v_add_co_u32_e32 v34, vcc, s31, v6
	s_lshl_b64 s[4:5], s[4:5], 12
	s_nop 0
	v_addc_co_u32_e32 v35, vcc, 0, v7, vcc
	v_add_co_u32_e32 v6, vcc, s33, v6
	s_cmpk_gt_i32 s34, 0xfff
	s_nop 0
	v_addc_co_u32_e32 v7, vcc, 0, v7, vcc
	global_load_dword v37, v[14:15], off offset:2048
	global_load_dword v38, v[18:19], off offset:-4096
	global_load_dword v39, v[18:19], off
	global_load_dword v40, v[18:19], off offset:2048
	global_load_dword v41, v[22:23], off offset:-4096
	global_load_dword v42, v[22:23], off
	global_load_dword v43, v[22:23], off offset:2048
	global_load_dword v44, v[26:27], off offset:-4096
	global_load_dword v45, v[8:9], off offset:2048
	global_load_dword v46, v[12:13], off offset:2048
	global_load_dword v47, v[16:17], off offset:2048
	global_load_dword v48, v[20:21], off offset:2048
	global_load_dword v49, v[24:25], off offset:2048
	global_load_dword v50, v[28:29], off offset:2048
	global_load_dword v51, v[10:11], off offset:-4096
	global_load_dword v12, v[10:11], off
	global_load_dword v8, v[14:15], off
	global_load_dword v13, v[10:11], off offset:2048
	global_load_dword v16, v[14:15], off offset:-4096
	global_load_dword v17, v[32:33], off offset:2048
	global_load_dword v18, v[26:27], off
	global_load_dword v19, v[26:27], off offset:2048
	global_load_dword v20, v[30:31], off offset:-4096
	global_load_dword v21, v[30:31], off
	global_load_dword v24, v[30:31], off offset:2048
	global_load_dword v25, v[34:35], off offset:-4096
	global_load_dword v28, v[34:35], off
	global_load_dword v29, v[34:35], off offset:2048
	global_load_dword v52, v[6:7], off
	global_load_dword v53, v[6:7], off offset:2048
	v_lshl_add_u64 v[22:23], v[4:5], 0, s[4:5]
	s_waitcnt vmcnt(0)
	v_cvt_pk_bf16_f32 v6, v1, v36
	v_cvt_pk_bf16_f32 v14, v42, v43
	v_cvt_pk_bf16_f32 v9, v38, v47
	v_cvt_pk_bf16_f32 v15, v44, v49
	v_cvt_pk_bf16_f32 v7, v51, v45
	v_cvt_pk_bf16_f32 v8, v8, v37
	v_cvt_pk_bf16_f32 v10, v12, v13
	v_cvt_pk_bf16_f32 v11, v16, v46
	v_cvt_pk_bf16_f32 v12, v39, v40
	v_cvt_pk_bf16_f32 v13, v41, v48
	v_cvt_pk_bf16_f32 v18, v18, v19
	v_cvt_pk_bf16_f32 v19, v20, v50
	v_cvt_pk_bf16_f32 v16, v21, v24
	v_cvt_pk_bf16_f32 v17, v25, v17
	v_cvt_pk_bf16_f32 v20, v28, v29
	v_cvt_pk_bf16_f32 v21, v52, v53
	global_store_dwordx4 v[22:23], v[6:9], off sc1
	global_store_dwordx4 v[22:23], v[10:13], off offset:512 sc1
	global_store_dwordx4 v[22:23], v[14:17], off offset:1024 sc1
	global_store_dwordx4 v[22:23], v[18:21], off offset:1536 sc1
	s_cbranch_scc0 .LBB0_543

; DI size_t vf_off(int h, int nblk, int krow, int d) { const int kk = krow & 31; return (((((size_t)h * nblk + (krow >> 5)) * 2 + (d >> 5)) * 2 + (kk >> 4)) * 64 + ((kk >> 2) & 1) * 32 + (d & 31)) * 8 + 4 * ((kk >> 3) & 1) + (kk & 3); }
; DI void vt_item(const float* src, int past, int nh, int band, int krows, bf16_t* VT, int item, int lane) {
;     const int nrb = past / 32, rb = item % nrb, h = (item / nrb) % nh, b = item / (nrb * nh), r0 = rb * 32;
;     float v[32];
; #pragma unroll
;     for (int i = 0; i < 32; ++i) v[i] = src[(((size_t)b * past + r0 + i) * nh + h) * 64 + lane];
;     const int krow = SEQ + b * band + r0;
; #pragma unroll
;     for (int t = 0; t < 2; ++t)
; #pragma unroll
;         for (int hh = 0; hh < 2; ++hh) { const int k0 = 16 * t + 4 * hh; u32x4 o; o.x = pk2(v[k0], v[k0 + 1]); o.y = pk2(v[k0 + 2], v[k0 + 3]); o.z = pk2(v[k0 + 8], v[k0 + 9]); o.w = pk2(v[k0 + 10], v[k0 + 11]);
;             *(u32x4*)(VT + vf_off(h, krows >> 5, krow + k0, lane)) = o; }
; }
; DI void prologue_b(KArgs ap, int gw, int NGW, int lane) {
;     ...
;     for (int it = gw; it < NSTREAM * 2 * 4; it += NGW) vt_item(cbv, 128, 2, 192, KB_ROWS, (bf16_t*)(ws + WS_VTB), it, lane);
.LBB0_546:
	s_ashr_i32 s7, s16, 31
	s_lshr_b32 s8, s7, 30
	s_lshr_b32 s7, s7, 29
	s_add_i32 s8, s16, s8
	s_add_i32 s7, s16, s7
	s_ashr_i32 s11, s8, 2
	s_lshr_b32 s9, s8, 31
	s_ashr_i32 s8, s7, 3
	s_add_i32 s7, s11, s9
	s_lshl_b32 s20, s11, 7
	s_ashr_i32 s9, s8, 31
	s_and_b32 s7, s7, -2
	s_sub_i32 s10, s0, s20
	s_lshl_b64 s[12:13], s[8:9], 16
	s_sub_i32 s18, s11, s7
	s_ashr_i32 s11, s10, 31
	v_lshl_add_u64 v[4:5], v[2:3], 0, s[12:13]
	s_ashr_i32 s19, s18, 31
	s_lshl_b64 s[10:11], s[10:11], 9
	s_lshl_b64 s[12:13], s[18:19], 8
	v_lshl_add_u64 v[4:5], v[4:5], 0, s[10:11]
	v_lshl_add_u64 v[4:5], v[4:5], 0, s[12:13]
	v_add_co_u32_e32 v6, vcc, s4, v4
	global_load_dword v10, v[4:5], off
	global_load_dword v11, v[4:5], off offset:512
	global_load_dword v12, v[4:5], off offset:1024
	global_load_dword v13, v[4:5], off offset:1536
	global_load_dword v14, v[4:5], off offset:2048
	global_load_dword v15, v[4:5], off offset:2560
	global_load_dword v16, v[4:5], off offset:3072
	global_load_dword v17, v[4:5], off offset:3584
	v_addc_co_u32_e32 v7, vcc, 0, v5, vcc
	v_add_co_u32_e32 v8, vcc, s5, v4
	s_mul_i32 s7, s8, 0xc0
	s_nop 0
	v_addc_co_u32_e32 v9, vcc, 0, v5, vcc
	v_add_co_u32_e32 v4, vcc, s6, v4
	s_sub_i32 s7, s7, s20
	s_nop 0
	v_addc_co_u32_e32 v5, vcc, 0, v5, vcc
	global_load_dword v18, v[8:9], off offset:-4096
	global_load_dword v19, v[8:9], off
	global_load_dword v22, v[8:9], off offset:512
	global_load_dword v23, v[8:9], off offset:1024
	global_load_dword v24, v[8:9], off offset:1536
	global_load_dword v25, v[8:9], off offset:2048
	global_load_dword v26, v[8:9], off offset:2560
	global_load_dword v27, v[8:9], off offset:3072
	global_load_dword v28, v[8:9], off offset:3584
	global_load_dword v29, v[6:7], off offset:512
	global_load_dword v30, v[6:7], off offset:1024
	global_load_dword v31, v[6:7], off offset:1536
	global_load_dword v32, v[6:7], off offset:2048
	global_load_dword v33, v[6:7], off offset:2560
	global_load_dword v34, v[6:7], off offset:3072
	global_load_dword v35, v[6:7], off offset:3584
	global_load_dword v36, v[4:5], off
	global_load_dword v37, v[4:5], off offset:512
	global_load_dword v38, v[4:5], off offset:1024
	global_load_dword v39, v[4:5], off offset:1536
	global_load_dword v40, v[4:5], off offset:2048
	global_load_dword v41, v[4:5], off offset:2560
	global_load_dword v42, v[4:5], off offset:3072
	global_load_dword v43, v[4:5], off offset:3584
	s_add_i32 s7, s0, s7
	s_addk_i32 s7, 0x4000
	s_ashr_i32 s7, s7, 5
	s_mul_i32 s8, s18, 0x2c0
	s_ashr_i32 s10, s7, 31
	s_mul_hi_i32 s9, s18, 0x2c0
	s_add_u32 s8, s8, s7
	s_addc_u32 s9, s9, s10
	s_add_i32 s16, s16, s17
	s_add_i32 s0, s0, s1
	s_lshl_b64 s[8:9], s[8:9], 12
	v_lshl_add_u64 v[20:21], v[0:1], 0, s[8:9]
	s_cmpk_lt_i32 s16, 0x100
	s_waitcnt vmcnt(0)
	v_cvt_pk_bf16_f32 v4, v10, v11
	v_cvt_pk_bf16_f32 v5, v12, v13
	v_cvt_pk_bf16_f32 v12, v19, v22
	v_cvt_pk_bf16_f32 v6, v18, v29
	v_cvt_pk_bf16_f32 v8, v14, v15
	v_cvt_pk_bf16_f32 v7, v30, v31
	v_cvt_pk_bf16_f32 v9, v16, v17
	v_cvt_pk_bf16_f32 v10, v32, v33
	v_cvt_pk_bf16_f32 v13, v23, v24
	v_cvt_pk_bf16_f32 v16, v25, v26
	v_cvt_pk_bf16_f32 v11, v34, v35
	v_cvt_pk_bf16_f32 v17, v27, v28
	v_cvt_pk_bf16_f32 v14, v36, v37
	v_cvt_pk_bf16_f32 v15, v38, v39
	v_cvt_pk_bf16_f32 v18, v40, v41
	v_cvt_pk_bf16_f32 v19, v42, v43
	global_store_dwordx4 v[20:21], v[4:7], off sc1
	global_store_dwordx4 v[20:21], v[8:11], off offset:512 sc1
	global_store_dwordx4 v[20:21], v[12:15], off offset:1024 sc1
	global_store_dwordx4 v[20:21], v[16:19], off offset:1536 sc1
	s_cbranch_scc1 .LBB0_546

; DI void transpose_item(const float* W, int ldw, int k0, int n, bf16_t* WT, int Kd, int dst_row, const float* kscale) {
;     ...
;     bf16_t* d = WT + (size_t)dst_row * Kd + k0;
; #pragma unroll
;     for (int c = 0; c < 8; ++c) { u32x4 o; o.x = pk2(v[8 * c], v[8 * c + 1]); o.y = pk2(v[8 * c + 2], v[8 * c + 3]); o.z = pk2(v[8 * c + 4], v[8 * c + 5]); o.w = pk2(v[8 * c + 6], v[8 * c + 7]);
;         *(u32x4*)(d + 8 * c) = o; }
.LBB0_603:
	v_cvt_pk_bf16_f32 v0, v0, v1
	v_cvt_pk_bf16_f32 v1, v2, v3
	v_cvt_pk_bf16_f32 v2, v4, v5
	v_cvt_pk_bf16_f32 v3, v6, v7
	global_store_dwordx4 v[64:65], v[0:3], off offset:16 sc1
	s_mov_b64 s[0:1], 0
	s_nop 0
	v_cvt_pk_bf16_f32 v0, v8, v9
	v_cvt_pk_bf16_f32 v1, v10, v11
	v_cvt_pk_bf16_f32 v2, v12, v13
	v_cvt_pk_bf16_f32 v3, v14, v15
	global_store_dwordx4 v[64:65], v[0:3], off offset:32 sc1
	s_nop 1
	v_cvt_pk_bf16_f32 v0, v16, v17
	v_cvt_pk_bf16_f32 v1, v18, v19
	v_cvt_pk_bf16_f32 v2, v20, v21
	v_cvt_pk_bf16_f32 v3, v22, v23
	global_store_dwordx4 v[64:65], v[0:3], off offset:48 sc1
	s_nop 1
	v_cvt_pk_bf16_f32 v0, v24, v25
	v_cvt_pk_bf16_f32 v1, v26, v27
	v_cvt_pk_bf16_f32 v2, v28, v29
	v_cvt_pk_bf16_f32 v3, v30, v31
	global_store_dwordx4 v[64:65], v[0:3], off offset:64 sc1
	s_nop 1
	v_cvt_pk_bf16_f32 v0, v32, v33
	v_cvt_pk_bf16_f32 v1, v34, v35
	v_cvt_pk_bf16_f32 v2, v36, v37
	v_cvt_pk_bf16_f32 v3, v38, v39
	global_store_dwordx4 v[64:65], v[0:3], off offset:80 sc1
	s_nop 1
	v_cvt_pk_bf16_f32 v0, v40, v41
	v_cvt_pk_bf16_f32 v1, v42, v43
	v_cvt_pk_bf16_f32 v2, v44, v45
	v_cvt_pk_bf16_f32 v3, v46, v47
	global_store_dwordx4 v[64:65], v[0:3], off offset:96 sc1
	s_nop 1
	v_cvt_pk_bf16_f32 v0, v48, v49
	v_cvt_pk_bf16_f32 v1, v50, v51
	v_cvt_pk_bf16_f32 v2, v52, v53
	v_cvt_pk_bf16_f32 v3, v54, v55
	global_store_dwordx4 v[64:65], v[0:3], off offset:112 sc1

; DI u32x2 pk4(f32x4 v) { u32x2 r; r.x = pk2(v[0], v[1]); r.y = pk2(v[2], v[3]); return r; }
; template <bool ISB>
; DI void attn_unit(int u, int hq, int qoff, int nq, const bf16_t* Qb, const bf16_t* Kb, const bf16_t* Vtb, bf16_t* O, const float* sinks, const LAS float* biasL, LAS unsigned char* ring, int lane) {
;     ...
; #pragma unroll
;     for (int qb = 0; qb < 2; ++qb) {
;         if (qb >= nq) continue;
;         const float l = lrun[qb] + __shfl_xor(lrun[qb], 32), inv = 1.f / l;
;         bf16_t* op = O + (size_t)(64 * u + qoff + 32 * qb + r) * DM + (ISB ? 512 : 0) + hq * 64 + 4 * hh;
; #pragma unroll
;         for (int db = 0; db < 2; ++db)
; #pragma unroll
;             for (int i4 = 0; i4 < 4; ++i4) { f32x4 v = {o[qb][db][4 * i4] * inv, o[qb][db][4 * i4 + 1] * inv, o[qb][db][4 * i4 + 2] * inv, o[qb][db][4 * i4 + 3] * inv};
;                 *(u32x2*)(op + 32 * db + 8 * i4) = pk4(v); }
;     }
.LBB0_641:
	v_cmp_lt_i32_e32 vcc, v156, v157
	s_nop 1
	v_cndmask_b32_e32 v64, v176, v156, vcc
	v_lshlrev_b32_e32 v67, 2, v64
	ds_bpermute_b32 v65, v67, v181
	v_or_b32_e32 v64, s6, v182
	s_waitcnt vmcnt(0) lgkmcnt(0)
	v_add_f32_e32 v66, v181, v65
	v_div_scale_f32 v68, s[0:1], v66, v66, 1.0
	v_rcp_f32_e32 v69, v68
	v_div_scale_f32 v70, vcc, 1.0, v66, 1.0
	v_ashrrev_i32_e32 v65, 31, v64
	v_fma_f32 v71, -v68, v69, 1.0
	v_fmac_f32_e32 v69, v71, v69
	v_mul_f32_e32 v71, v70, v69
	v_fma_f32 v72, -v68, v71, v70
	v_fmac_f32_e32 v71, v72, v69
	v_fma_f32 v68, -v68, v71, v70
	v_div_fmas_f32 v68, v68, v69, v71
	v_div_fixup_f32 v66, v68, v66, 1.0
	ds_bpermute_b32 v77, v67, v179
	v_and_b32_e32 v76, 32, v176
	v_lshrrev_b32_e32 v76, 2, v76
	v_lshlrev_b64 v[68:69], 11, v[64:65]
	v_lshl_add_u64 v[68:69], v[174:175], 0, v[68:69]
	v_add_co_u32_e32 v68, vcc, v76, v68
	s_nop 1
	v_addc_co_u32_e32 v69, vcc, 0, v69, vcc
	v_add_u32_e32 v84, 32, v64
	v_ashrrev_i32_e32 v85, 31, v84
	v_lshlrev_b64 v[84:85], 11, v[84:85]
	v_lshl_add_u64 v[84:85], v[174:175], 0, v[84:85]
	v_add_co_u32_e32 v84, vcc, v76, v84
	s_nop 1
	v_addc_co_u32_e32 v85, vcc, 0, v85, vcc
	s_waitcnt lgkmcnt(0)
	v_add_f32_e32 v77, v179, v77
	v_div_scale_f32 v88, s[0:1], v77, v77, 1.0
	v_rcp_f32_e32 v89, v88
	v_div_scale_f32 v90, vcc, 1.0, v77, 1.0
	v_fma_f32 v91, -v88, v89, 1.0
	v_fmac_f32_e32 v89, v91, v89
	v_mul_f32_e32 v91, v90, v89
	v_fma_f32 v92, -v88, v91, v90
	v_fmac_f32_e32 v91, v92, v89
	v_fma_f32 v88, -v88, v91, v90
	v_div_fmas_f32 v88, v88, v89, v91
	v_div_fixup_f32 v78, v88, v77, 1.0
	v_pk_mul_f32 v[32:33], v[32:33], v[66:67] op_sel_hi:[1,0]
	v_pk_mul_f32 v[34:35], v[34:35], v[66:67] op_sel_hi:[1,0]
	v_pk_mul_f32 v[36:37], v[36:37], v[66:67] op_sel_hi:[1,0]
	v_pk_mul_f32 v[38:39], v[38:39], v[66:67] op_sel_hi:[1,0]
	v_pk_mul_f32 v[40:41], v[40:41], v[66:67] op_sel_hi:[1,0]
	v_pk_mul_f32 v[42:43], v[42:43], v[66:67] op_sel_hi:[1,0]
	v_pk_mul_f32 v[44:45], v[44:45], v[66:67] op_sel_hi:[1,0]
	v_pk_mul_f32 v[46:47], v[46:47], v[66:67] op_sel_hi:[1,0]
	v_cvt_pk_bf16_f32 v32, v32, v33
	v_cvt_pk_bf16_f32 v33, v34, v35
	v_cvt_pk_bf16_f32 v34, v36, v37
	v_cvt_pk_bf16_f32 v35, v38, v39
	v_cvt_pk_bf16_f32 v40, v40, v41
	v_cvt_pk_bf16_f32 v41, v42, v43
	v_cvt_pk_bf16_f32 v42, v44, v45
	v_cvt_pk_bf16_f32 v43, v46, v47
	s_nop 1
	v_permlane32_swap_b32_e32 v32, v34
	v_permlane32_swap_b32_e32 v33, v35
	v_permlane32_swap_b32_e32 v40, v42
	v_permlane32_swap_b32_e32 v41, v43
	global_store_dwordx4 v[68:69], v[32:35], off offset:1024 sc1
	global_store_dwordx4 v[68:69], v[40:43], off offset:1056 sc1
	v_pk_mul_f32 v[0:1], v[0:1], v[66:67] op_sel_hi:[1,0]
	v_pk_mul_f32 v[2:3], v[2:3], v[66:67] op_sel_hi:[1,0]
	v_pk_mul_f32 v[4:5], v[4:5], v[66:67] op_sel_hi:[1,0]
	v_pk_mul_f32 v[6:7], v[6:7], v[66:67] op_sel_hi:[1,0]
	v_pk_mul_f32 v[8:9], v[8:9], v[66:67] op_sel_hi:[1,0]
	v_pk_mul_f32 v[10:11], v[10:11], v[66:67] op_sel_hi:[1,0]
	v_pk_mul_f32 v[12:13], v[12:13], v[66:67] op_sel_hi:[1,0]
	v_pk_mul_f32 v[14:15], v[14:15], v[66:67] op_sel_hi:[1,0]
	v_cvt_pk_bf16_f32 v0, v0, v1
	v_cvt_pk_bf16_f32 v1, v2, v3
	v_cvt_pk_bf16_f32 v2, v4, v5
	v_cvt_pk_bf16_f32 v3, v6, v7
	v_cvt_pk_bf16_f32 v8, v8, v9
	v_cvt_pk_bf16_f32 v9, v10, v11
	v_cvt_pk_bf16_f32 v10, v12, v13
	v_cvt_pk_bf16_f32 v11, v14, v15
	s_nop 1
	v_permlane32_swap_b32_e32 v0, v2
	v_permlane32_swap_b32_e32 v1, v3
	v_permlane32_swap_b32_e32 v8, v10
	v_permlane32_swap_b32_e32 v9, v11
	global_store_dwordx4 v[68:69], v[0:3], off offset:1088 sc1
	global_store_dwordx4 v[68:69], v[8:11], off offset:1120 sc1
	v_pk_mul_f32 v[48:49], v[48:49], v[78:79] op_sel_hi:[1,0]
	v_pk_mul_f32 v[50:51], v[50:51], v[78:79] op_sel_hi:[1,0]
	v_pk_mul_f32 v[52:53], v[52:53], v[78:79] op_sel_hi:[1,0]
	v_pk_mul_f32 v[54:55], v[54:55], v[78:79] op_sel_hi:[1,0]
	v_pk_mul_f32 v[56:57], v[56:57], v[78:79] op_sel_hi:[1,0]
	v_pk_mul_f32 v[58:59], v[58:59], v[78:79] op_sel_hi:[1,0]
	v_pk_mul_f32 v[60:61], v[60:61], v[78:79] op_sel_hi:[1,0]
	v_pk_mul_f32 v[62:63], v[62:63], v[78:79] op_sel_hi:[1,0]
	v_cvt_pk_bf16_f32 v48, v48, v49
	v_cvt_pk_bf16_f32 v49, v50, v51
	v_cvt_pk_bf16_f32 v50, v52, v53
	v_cvt_pk_bf16_f32 v51, v54, v55
	v_cvt_pk_bf16_f32 v56, v56, v57
	v_cvt_pk_bf16_f32 v57, v58, v59
	v_cvt_pk_bf16_f32 v58, v60, v61
	v_cvt_pk_bf16_f32 v59, v62, v63
	s_nop 1
	v_permlane32_swap_b32_e32 v48, v50
	v_permlane32_swap_b32_e32 v49, v51
	v_permlane32_swap_b32_e32 v56, v58
	v_permlane32_swap_b32_e32 v57, v59
	global_store_dwordx4 v[84:85], v[48:51], off offset:1024 sc1
	global_store_dwordx4 v[84:85], v[56:59], off offset:1056 sc1
	v_pk_mul_f32 v[16:17], v[16:17], v[78:79] op_sel_hi:[1,0]
	v_pk_mul_f32 v[18:19], v[18:19], v[78:79] op_sel_hi:[1,0]
	v_pk_mul_f32 v[20:21], v[20:21], v[78:79] op_sel_hi:[1,0]
	v_pk_mul_f32 v[22:23], v[22:23], v[78:79] op_sel_hi:[1,0]
	v_pk_mul_f32 v[24:25], v[24:25], v[78:79] op_sel_hi:[1,0]
	v_pk_mul_f32 v[26:27], v[26:27], v[78:79] op_sel_hi:[1,0]
	v_pk_mul_f32 v[28:29], v[28:29], v[78:79] op_sel_hi:[1,0]
	v_pk_mul_f32 v[30:31], v[30:31], v[78:79] op_sel_hi:[1,0]
	v_cvt_pk_bf16_f32 v16, v16, v17
	v_cvt_pk_bf16_f32 v17, v18, v19
	v_cvt_pk_bf16_f32 v18, v20, v21
	v_cvt_pk_bf16_f32 v19, v22, v23
	v_cvt_pk_bf16_f32 v24, v24, v25
	v_cvt_pk_bf16_f32 v25, v26, v27
	v_cvt_pk_bf16_f32 v26, v28, v29
	v_cvt_pk_bf16_f32 v27, v30, v31
	s_nop 1
	v_permlane32_swap_b32_e32 v16, v18
	v_permlane32_swap_b32_e32 v17, v19
	v_permlane32_swap_b32_e32 v24, v26
	v_permlane32_swap_b32_e32 v25, v27
	global_store_dwordx4 v[84:85], v[16:19], off offset:1088 sc1
	global_store_dwordx4 v[84:85], v[24:27], off offset:1120 sc1
	s_mov_b64 s[0:1], 0

; DI u32x2 pk4(f32x4 v) { u32x2 r; r.x = pk2(v[0], v[1]); r.y = pk2(v[2], v[3]); return r; }
; template <bool ISB>
; DI void attn_unit(int u, int hq, int qoff, int nq, const bf16_t* Qb, const bf16_t* Kb, const bf16_t* Vtb, bf16_t* O, const float* sinks, const LAS float* biasL, LAS unsigned char* ring, int lane) {
;     ...
; #pragma unroll
;     for (int qb = 0; qb < 2; ++qb) {
;         if (qb >= nq) continue;
;         const float l = lrun[qb] + __shfl_xor(lrun[qb], 32), inv = 1.f / l;
;         bf16_t* op = O + (size_t)(64 * u + qoff + 32 * qb + r) * DM + (ISB ? 512 : 0) + hq * 64 + 4 * hh;
; #pragma unroll
;         for (int db = 0; db < 2; ++db)
; #pragma unroll
;             for (int i4 = 0; i4 < 4; ++i4) { f32x4 v = {o[qb][db][4 * i4] * inv, o[qb][db][4 * i4 + 1] * inv, o[qb][db][4 * i4 + 2] * inv, o[qb][db][4 * i4 + 3] * inv};
;                 *(u32x2*)(op + 32 * db + 8 * i4) = pk4(v); }
;     }
.LBB0_696:
	v_cmp_lt_i32_e32 vcc, v192, v193
	s_nop 1
	v_cndmask_b32_e32 v66, v191, v192, vcc
	v_lshlrev_b32_e32 v68, 2, v66
	ds_bpermute_b32 v67, v68, v65
	v_or_b32_e32 v66, s91, v188
	s_waitcnt lgkmcnt(0)
	v_add_f32_e32 v65, v65, v67
	v_div_scale_f32 v69, s[0:1], v65, v65, 1.0
	v_rcp_f32_e32 v70, v69
	v_div_scale_f32 v71, vcc, 1.0, v65, 1.0
	v_ashrrev_i32_e32 v67, 31, v66
	v_fma_f32 v72, -v69, v70, 1.0
	v_fmac_f32_e32 v70, v72, v70
	v_mul_f32_e32 v72, v71, v70
	v_fma_f32 v73, -v69, v72, v71
	v_fmac_f32_e32 v72, v73, v70
	v_fma_f32 v69, -v69, v72, v71
	v_div_fmas_f32 v69, v69, v70, v72
	v_div_fixup_f32 v70, v69, v65, 1.0
	v_and_b32_e32 v100, 32, v191
	v_lshrrev_b32_e32 v100, 2, v100
	v_lshlrev_b64 v[72:73], 11, v[66:67]
	v_lshl_add_u64 v[72:73], v[174:175], 0, v[72:73]
	v_add_co_u32_e32 v72, vcc, v100, v72
	s_nop 1
	v_addc_co_u32_e32 v73, vcc, 0, v73, vcc
	v_pk_mul_f32 v[16:17], v[16:17], v[70:71] op_sel_hi:[1,0]
	v_pk_mul_f32 v[18:19], v[18:19], v[70:71] op_sel_hi:[1,0]
	v_pk_mul_f32 v[20:21], v[20:21], v[70:71] op_sel_hi:[1,0]
	v_pk_mul_f32 v[22:23], v[22:23], v[70:71] op_sel_hi:[1,0]
	v_pk_mul_f32 v[24:25], v[24:25], v[70:71] op_sel_hi:[1,0]
	v_pk_mul_f32 v[26:27], v[26:27], v[70:71] op_sel_hi:[1,0]
	v_pk_mul_f32 v[28:29], v[28:29], v[70:71] op_sel_hi:[1,0]
	v_pk_mul_f32 v[30:31], v[30:31], v[70:71] op_sel_hi:[1,0]
	v_cvt_pk_bf16_f32 v16, v16, v17
	v_cvt_pk_bf16_f32 v17, v18, v19
	v_cvt_pk_bf16_f32 v18, v20, v21
	v_cvt_pk_bf16_f32 v19, v22, v23
	v_cvt_pk_bf16_f32 v24, v24, v25
	v_cvt_pk_bf16_f32 v25, v26, v27
	v_cvt_pk_bf16_f32 v26, v28, v29
	v_cvt_pk_bf16_f32 v27, v30, v31
	s_nop 1
	v_permlane32_swap_b32_e32 v16, v18
	v_permlane32_swap_b32_e32 v17, v19
	v_permlane32_swap_b32_e32 v24, v26
	v_permlane32_swap_b32_e32 v25, v27
	global_store_dwordx4 v[72:73], v[16:19], off sc1
	global_store_dwordx4 v[72:73], v[24:27], off offset:32 sc1
	v_pk_mul_f32 v[0:1], v[0:1], v[70:71] op_sel_hi:[1,0]
	v_pk_mul_f32 v[2:3], v[2:3], v[70:71] op_sel_hi:[1,0]
	v_pk_mul_f32 v[4:5], v[4:5], v[70:71] op_sel_hi:[1,0]
	v_pk_mul_f32 v[6:7], v[6:7], v[70:71] op_sel_hi:[1,0]
	v_pk_mul_f32 v[8:9], v[8:9], v[70:71] op_sel_hi:[1,0]
	v_pk_mul_f32 v[10:11], v[10:11], v[70:71] op_sel_hi:[1,0]
	v_pk_mul_f32 v[12:13], v[12:13], v[70:71] op_sel_hi:[1,0]
	v_pk_mul_f32 v[14:15], v[14:15], v[70:71] op_sel_hi:[1,0]
	v_cvt_pk_bf16_f32 v0, v0, v1
	v_cvt_pk_bf16_f32 v1, v2, v3
	v_cvt_pk_bf16_f32 v2, v4, v5
	v_cvt_pk_bf16_f32 v3, v6, v7
	v_cvt_pk_bf16_f32 v8, v8, v9
	v_cvt_pk_bf16_f32 v9, v10, v11
	v_cvt_pk_bf16_f32 v10, v12, v13
	v_cvt_pk_bf16_f32 v11, v14, v15
	s_nop 1
	v_permlane32_swap_b32_e32 v0, v2
	v_permlane32_swap_b32_e32 v1, v3
	v_permlane32_swap_b32_e32 v8, v10
	v_permlane32_swap_b32_e32 v9, v11
	global_store_dwordx4 v[72:73], v[0:3], off offset:64 sc1
	global_store_dwordx4 v[72:73], v[8:11], off offset:96 sc1
	s_and_b64 vcc, exec, s[26:27]
	s_cbranch_vccz .LBB0_698
	ds_bpermute_b32 v101, v68, v64
	v_add_u32_e32 v102, 32, v66
	v_ashrrev_i32_e32 v103, 31, v102
	v_lshlrev_b64 v[102:103], 11, v[102:103]
	v_lshl_add_u64 v[102:103], v[174:175], 0, v[102:103]
	v_add_co_u32_e32 v102, vcc, v100, v102
	s_nop 1
	v_addc_co_u32_e32 v103, vcc, 0, v103, vcc
	s_waitcnt lgkmcnt(0)
	v_add_f32_e32 v101, v64, v101
	v_div_scale_f32 v106, s[0:1], v101, v101, 1.0
	v_rcp_f32_e32 v107, v106
	v_div_scale_f32 v108, vcc, 1.0, v101, 1.0
	v_fma_f32 v109, -v106, v107, 1.0
	v_fmac_f32_e32 v107, v109, v107
	v_mul_f32_e32 v109, v108, v107
	v_fma_f32 v110, -v106, v109, v108
	v_fmac_f32_e32 v109, v110, v107
	v_fma_f32 v106, -v106, v109, v108
	v_div_fmas_f32 v106, v106, v107, v109
	v_div_fixup_f32 v104, v106, v101, 1.0
	v_pk_mul_f32 v[48:49], v[48:49], v[104:105] op_sel_hi:[1,0]
	v_pk_mul_f32 v[50:51], v[50:51], v[104:105] op_sel_hi:[1,0]
	v_pk_mul_f32 v[52:53], v[52:53], v[104:105] op_sel_hi:[1,0]
	v_pk_mul_f32 v[54:55], v[54:55], v[104:105] op_sel_hi:[1,0]
	v_pk_mul_f32 v[56:57], v[56:57], v[104:105] op_sel_hi:[1,0]
	v_pk_mul_f32 v[58:59], v[58:59], v[104:105] op_sel_hi:[1,0]
	v_pk_mul_f32 v[60:61], v[60:61], v[104:105] op_sel_hi:[1,0]
	v_pk_mul_f32 v[62:63], v[62:63], v[104:105] op_sel_hi:[1,0]
	v_cvt_pk_bf16_f32 v48, v48, v49
	v_cvt_pk_bf16_f32 v49, v50, v51
	v_cvt_pk_bf16_f32 v50, v52, v53
	v_cvt_pk_bf16_f32 v51, v54, v55
	v_cvt_pk_bf16_f32 v56, v56, v57
	v_cvt_pk_bf16_f32 v57, v58, v59
	v_cvt_pk_bf16_f32 v58, v60, v61
	v_cvt_pk_bf16_f32 v59, v62, v63
	s_nop 1
	v_permlane32_swap_b32_e32 v48, v50
	v_permlane32_swap_b32_e32 v49, v51
	v_permlane32_swap_b32_e32 v56, v58
	v_permlane32_swap_b32_e32 v57, v59
	global_store_dwordx4 v[102:103], v[48:51], off sc1
	global_store_dwordx4 v[102:103], v[56:59], off offset:32 sc1
	v_pk_mul_f32 v[32:33], v[32:33], v[104:105] op_sel_hi:[1,0]
	v_pk_mul_f32 v[34:35], v[34:35], v[104:105] op_sel_hi:[1,0]
	v_pk_mul_f32 v[36:37], v[36:37], v[104:105] op_sel_hi:[1,0]
	v_pk_mul_f32 v[38:39], v[38:39], v[104:105] op_sel_hi:[1,0]
	v_pk_mul_f32 v[40:41], v[40:41], v[104:105] op_sel_hi:[1,0]
	v_pk_mul_f32 v[42:43], v[42:43], v[104:105] op_sel_hi:[1,0]
	v_pk_mul_f32 v[44:45], v[44:45], v[104:105] op_sel_hi:[1,0]
	v_pk_mul_f32 v[46:47], v[46:47], v[104:105] op_sel_hi:[1,0]
	v_cvt_pk_bf16_f32 v32, v32, v33
	v_cvt_pk_bf16_f32 v33, v34, v35
	v_cvt_pk_bf16_f32 v34, v36, v37
	v_cvt_pk_bf16_f32 v35, v38, v39
	v_cvt_pk_bf16_f32 v40, v40, v41
	v_cvt_pk_bf16_f32 v41, v42, v43
	v_cvt_pk_bf16_f32 v42, v44, v45
	v_cvt_pk_bf16_f32 v43, v46, v47
	s_nop 1
	v_permlane32_swap_b32_e32 v32, v34
	v_permlane32_swap_b32_e32 v33, v35
	v_permlane32_swap_b32_e32 v40, v42
	v_permlane32_swap_b32_e32 v41, v43
	global_store_dwordx4 v[102:103], v[32:35], off offset:64 sc1
	global_store_dwordx4 v[102:103], v[40:43], off offset:96 sc1
	s_mov_b64 s[0:1], 0
	s_branch .LBB0_699

; #define LAS __attribute__((address_space(3)))
; #define KP() ({ KArgs _p = kp; asm volatile("" : "+s"(_p)); _p; })
; DI void transpose_item(const float* W, int ldw, int k0, int n, bf16_t* WT, int Kd, int dst_row, const float* kscale) {
;     float v[64];
; #pragma unroll
;     for (int i = 0; i < 64; ++i) v[i] = W[(size_t)(k0 + i) * ldw + n];
; DI void weight_item(KArgs ap, int it, int lane) {
;     unsigned char* ws = ap->ws;
;     int r = it;
;     if (r < WI_OUT) { const int kb = r / 16, nb = r % 16; transpose_item(ap->in[15], DM, 64 * kb, 64 * nb + lane, (bf16_t*)(ws + WS_WOUT), DM, 64 * nb + lane, nullptr); return; }
;     r -= WI_OUT;
;     if (r < WI_GU) { const int kb = r / 88, nb = r % 88; const int L = 64 * nb + lane; const int Lp = L < DFF ? L : L - DFF;
;         transpose_item(ap->in[17], NGU, 64 * kb, L, (bf16_t*)(ws + WS_WGU), DM, 256 * (Lp >> 7) + (L < DFF ? 0 : 128) + (Lp & 127), ap->in[16]); return; }
;     r -= WI_GU;
;     { const int kb = r / 16, nb = r % 16; transpose_item(ap->in[20], DM, 64 * kb, 64 * nb + lane, (bf16_t*)(ws + WS_WDN), DFF, 64 * nb + lane, nullptr); }
; __global__ void __launch_bounds__(512, 2) fwd_kernel(Args a_byval) {
;     ...
;         for (;;) {
;             unsigned k = 0; if (lane == 0) k = __hip_atomic_fetch_add((LAS unsigned*)(lds + RING_BYTES + 8192 + 64), 1u, __ATOMIC_RELAXED, __HIP_MEMORY_SCOPE_WORKGROUP);
;             k = __builtin_amdgcn_readfirstlane(k);
;             if (k >= 19u * NREP(2)) {
;                 const int it = bx + 256 * (int)(k - 19u * NREP(2));
;                 if (it >= WI_ALL) break;
;                 weight_item(KP(), it, lane); continue; }
.LBB0_699:
	s_andn2_b64 vcc, exec, s[0:1]
	s_cbranch_vccnz .LBB0_605
	s_lshl_b32 s0, s12, 8
	s_add_i32 s91, s35, s0
	s_cmpk_gt_i32 s91, 0x93f
	s_mov_b64 s[0:1], -1
	s_cbranch_scc1 .LBB0_604
	v_readlane_b32 s28, v253, 1
	v_readlane_b32 s29, v253, 2
	s_waitcnt lgkmcnt(0)
	s_load_dwordx2 s[26:27], s[28:29], 0xb0
	s_cmpk_gt_i32 s91, 0xff
	s_cbranch_scc0 .LBB0_709
	s_cmpk_gt_u32 s91, 0x67f
	s_cbranch_scc0 .LBB0_704
	s_load_dwordx2 s[4:5], s[28:29], 0xa0
	s_lshl_b32 s1, s91, 6
	s_lshl_b32 s0, s91, 2
	s_and_b32 s1, s1, 0x3c0
	s_and_b32 s0, s0, 0x7fffffc0
	v_or_b32_e32 v66, s1, v190
	s_add_i32 s12, s0, 0xffffe600
	v_lshlrev_b32_e32 v0, 2, v66
	v_mov_b32_e32 v1, v161
	s_waitcnt lgkmcnt(0)
	v_lshl_add_u64 v[48:49], s[4:5], 0, v[0:1]
	s_lshl_b64 s[4:5], s[12:13], 12
	v_lshl_add_u64 v[0:1], v[48:49], 0, s[4:5]
	s_add_i32 s4, s0, 0xffffe601
	s_mov_b32 s5, s13
	s_lshl_b64 s[4:5], s[4:5], 12
	v_lshl_add_u64 v[2:3], v[48:49], 0, s[4:5]
	s_add_i32 s4, s0, 0xffffe602
	s_mov_b32 s5, s13
	s_lshl_b64 s[4:5], s[4:5], 12
	v_lshl_add_u64 v[4:5], v[48:49], 0, s[4:5]
	s_add_i32 s4, s0, 0xffffe603
	s_mov_b32 s5, s13
	s_lshl_b64 s[4:5], s[4:5], 12
	v_lshl_add_u64 v[6:7], v[48:49], 0, s[4:5]
	s_add_i32 s4, s0, 0xffffe604
	s_mov_b32 s5, s13
	s_lshl_b64 s[4:5], s[4:5], 12
	v_lshl_add_u64 v[8:9], v[48:49], 0, s[4:5]
	s_add_i32 s4, s0, 0xffffe605
	s_mov_b32 s5, s13
	s_lshl_b64 s[4:5], s[4:5], 12
	v_lshl_add_u64 v[10:11], v[48:49], 0, s[4:5]
	s_add_i32 s4, s0, 0xffffe606
	s_mov_b32 s5, s13
	s_lshl_b64 s[4:5], s[4:5], 12
	v_lshl_add_u64 v[12:13], v[48:49], 0, s[4:5]
	s_add_i32 s4, s0, 0xffffe607
	s_mov_b32 s5, s13
	s_lshl_b64 s[4:5], s[4:5], 12
	v_lshl_add_u64 v[14:15], v[48:49], 0, s[4:5]
	s_add_i32 s4, s0, 0xffffe608
	s_mov_b32 s5, s13
	s_lshl_b64 s[4:5], s[4:5], 12
	global_load_dword v67, v[0:1], off
	global_load_dword v68, v[2:3], off
	global_load_dword v69, v[4:5], off
	global_load_dword v70, v[6:7], off
	global_load_dword v71, v[8:9], off
	global_load_dword v72, v[10:11], off
	global_load_dword v73, v[12:13], off
	global_load_dword v74, v[14:15], off
	v_lshl_add_u64 v[0:1], v[48:49], 0, s[4:5]
	s_add_i32 s4, s0, 0xffffe609
	s_mov_b32 s5, s13
	s_lshl_b64 s[4:5], s[4:5], 12
	v_lshl_add_u64 v[2:3], v[48:49], 0, s[4:5]
	s_add_i32 s4, s0, 0xffffe60a
	s_mov_b32 s5, s13
	s_lshl_b64 s[4:5], s[4:5], 12
	v_lshl_add_u64 v[4:5], v[48:49], 0, s[4:5]
	s_add_i32 s4, s0, 0xffffe60b
	s_mov_b32 s5, s13
	s_lshl_b64 s[4:5], s[4:5], 12
	v_lshl_add_u64 v[6:7], v[48:49], 0, s[4:5]
	s_add_i32 s4, s0, 0xffffe60c
	s_mov_b32 s5, s13
	s_lshl_b64 s[4:5], s[4:5], 12
	v_lshl_add_u64 v[8:9], v[48:49], 0, s[4:5]
	s_add_i32 s4, s0, 0xffffe60d
	s_mov_b32 s5, s13
	s_lshl_b64 s[4:5], s[4:5], 12
	v_lshl_add_u64 v[10:11], v[48:49], 0, s[4:5]
	s_add_i32 s4, s0, 0xffffe60e
	s_mov_b32 s5, s13
	s_lshl_b64 s[4:5], s[4:5], 12
	v_lshl_add_u64 v[12:13], v[48:49], 0, s[4:5]
	s_add_i32 s4, s0, 0xffffe60f
	s_mov_b32 s5, s13
	s_lshl_b64 s[4:5], s[4:5], 12
	v_lshl_add_u64 v[14:15], v[48:49], 0, s[4:5]
	s_add_i32 s4, s0, 0xffffe610
	s_mov_b32 s5, s13
	s_lshl_b64 s[4:5], s[4:5], 12
	global_load_dword v0, v[0:1], off
	s_nop 0
	global_load_dword v1, v[2:3], off
	s_nop 0
	global_load_dword v2, v[4:5], off
	global_load_dword v3, v[6:7], off
	s_nop 0
	global_load_dword v4, v[8:9], off
	global_load_dword v5, v[10:11], off
	global_load_dword v6, v[12:13], off
	global_load_dword v7, v[14:15], off
	v_lshl_add_u64 v[8:9], v[48:49], 0, s[4:5]
	s_add_i32 s4, s0, 0xffffe611
	s_mov_b32 s5, s13
	s_lshl_b64 s[4:5], s[4:5], 12
	v_lshl_add_u64 v[10:11], v[48:49], 0, s[4:5]
	s_add_i32 s4, s0, 0xffffe612
	s_mov_b32 s5, s13
	s_lshl_b64 s[4:5], s[4:5], 12
	v_lshl_add_u64 v[12:13], v[48:49], 0, s[4:5]
	s_add_i32 s4, s0, 0xffffe613
	s_mov_b32 s5, s13
	s_lshl_b64 s[4:5], s[4:5], 12
	v_lshl_add_u64 v[14:15], v[48:49], 0, s[4:5]
	s_add_i32 s4, s0, 0xffffe614
	s_mov_b32 s5, s13
	s_lshl_b64 s[4:5], s[4:5], 12
	v_lshl_add_u64 v[16:17], v[48:49], 0, s[4:5]
	s_add_i32 s4, s0, 0xffffe615
	s_mov_b32 s5, s13
	s_lshl_b64 s[4:5], s[4:5], 12
	v_lshl_add_u64 v[18:19], v[48:49], 0, s[4:5]
	s_add_i32 s4, s0, 0xffffe616
	s_mov_b32 s5, s13
	s_lshl_b64 s[4:5], s[4:5], 12
	v_lshl_add_u64 v[20:21], v[48:49], 0, s[4:5]
	s_add_i32 s4, s0, 0xffffe617
	s_mov_b32 s5, s13
	s_lshl_b64 s[4:5], s[4:5], 12
	v_lshl_add_u64 v[22:23], v[48:49], 0, s[4:5]
	s_add_i32 s4, s0, 0xffffe618
	s_mov_b32 s5, s13
	s_lshl_b64 s[4:5], s[4:5], 12
	global_load_dword v8, v[8:9], off
	s_nop 0
	global_load_dword v9, v[10:11], off
	s_nop 0
	global_load_dword v10, v[12:13], off
	global_load_dword v11, v[14:15], off
	s_nop 0
	global_load_dword v12, v[16:17], off
	global_load_dword v13, v[18:19], off
	global_load_dword v14, v[20:21], off
	global_load_dword v15, v[22:23], off
	v_lshl_add_u64 v[16:17], v[48:49], 0, s[4:5]
	s_add_i32 s4, s0, 0xffffe619
	s_mov_b32 s5, s13
	s_lshl_b64 s[4:5], s[4:5], 12
	v_lshl_add_u64 v[18:19], v[48:49], 0, s[4:5]
	s_add_i32 s4, s0, 0xffffe61a
	s_mov_b32 s5, s13
	s_lshl_b64 s[4:5], s[4:5], 12
	v_lshl_add_u64 v[20:21], v[48:49], 0, s[4:5]
	s_add_i32 s4, s0, 0xffffe61b
	s_mov_b32 s5, s13
	s_lshl_b64 s[4:5], s[4:5], 12
	v_lshl_add_u64 v[22:23], v[48:49], 0, s[4:5]
	s_add_i32 s4, s0, 0xffffe61c
	s_mov_b32 s5, s13
	s_lshl_b64 s[4:5], s[4:5], 12
	v_lshl_add_u64 v[24:25], v[48:49], 0, s[4:5]
	s_add_i32 s4, s0, 0xffffe61d
	s_mov_b32 s5, s13
	s_lshl_b64 s[4:5], s[4:5], 12
	v_lshl_add_u64 v[26:27], v[48:49], 0, s[4:5]
	s_add_i32 s4, s0, 0xffffe61e
	s_mov_b32 s5, s13
	s_lshl_b64 s[4:5], s[4:5], 12
	v_lshl_add_u64 v[28:29], v[48:49], 0, s[4:5]
	s_add_i32 s4, s0, 0xffffe61f
	s_mov_b32 s5, s13
	s_lshl_b64 s[4:5], s[4:5], 12
	v_lshl_add_u64 v[30:31], v[48:49], 0, s[4:5]
; DI void transpose_item(const float* W, int ldw, int k0, int n, bf16_t* WT, int Kd, int dst_row, const float* kscale) {
;     float v[64];
; #pragma unroll
;     for (int i = 0; i < 64; ++i) v[i] = W[(size_t)(k0 + i) * ldw + n];
;     if (kscale) {
; #pragma unroll
;         for (int i = 0; i < 64; ++i) v[i] *= kscale[k0 + i];
;     }
;     bf16_t* d = WT + (size_t)dst_row * Kd + k0;
; #pragma unroll
;     for (int c = 0; c < 8; ++c) { u32x4 o; o.x = pk2(v[8 * c], v[8 * c + 1]); o.y = pk2(v[8 * c + 2], v[8 * c + 3]); o.z = pk2(v[8 * c + 4], v[8 * c + 5]); o.w = pk2(v[8 * c + 6], v[8 * c + 7]);
;         *(u32x4*)(d + 8 * c) = o; }
; DI void weight_item(KArgs ap, int it, int lane) {
;     ...
;     { const int kb = r / 16, nb = r % 16; transpose_item(ap->in[20], DM, 64 * kb, 64 * nb + lane, (bf16_t*)(ws + WS_WDN), DFF, 64 * nb + lane, nullptr); }
	s_add_i32 s4, s0, 0xffffe620
	s_mov_b32 s5, s13
	s_lshl_b64 s[4:5], s[4:5], 12
	global_load_dword v16, v[16:17], off
	s_nop 0
	global_load_dword v17, v[18:19], off
	s_nop 0
	global_load_dword v18, v[20:21], off
	global_load_dword v19, v[22:23], off
	s_nop 0
	global_load_dword v20, v[24:25], off
	global_load_dword v21, v[26:27], off
	global_load_dword v22, v[28:29], off
	global_load_dword v23, v[30:31], off
	v_lshl_add_u64 v[24:25], v[48:49], 0, s[4:5]
	s_add_i32 s4, s0, 0xffffe621
	s_mov_b32 s5, s13
	s_lshl_b64 s[4:5], s[4:5], 12
	v_lshl_add_u64 v[26:27], v[48:49], 0, s[4:5]
	s_add_i32 s4, s0, 0xffffe622
	s_mov_b32 s5, s13
	s_lshl_b64 s[4:5], s[4:5], 12
	v_lshl_add_u64 v[28:29], v[48:49], 0, s[4:5]
	s_add_i32 s4, s0, 0xffffe623
	s_mov_b32 s5, s13
	s_lshl_b64 s[4:5], s[4:5], 12
	v_lshl_add_u64 v[30:31], v[48:49], 0, s[4:5]
	s_add_i32 s4, s0, 0xffffe624
	s_mov_b32 s5, s13
	s_lshl_b64 s[4:5], s[4:5], 12
	v_lshl_add_u64 v[32:33], v[48:49], 0, s[4:5]
	s_add_i32 s4, s0, 0xffffe625
	s_mov_b32 s5, s13
	s_lshl_b64 s[4:5], s[4:5], 12
	v_lshl_add_u64 v[34:35], v[48:49], 0, s[4:5]
	s_add_i32 s4, s0, 0xffffe626
	s_mov_b32 s5, s13
	s_lshl_b64 s[4:5], s[4:5], 12
	v_lshl_add_u64 v[36:37], v[48:49], 0, s[4:5]
	s_add_i32 s4, s0, 0xffffe627
	s_mov_b32 s5, s13
	s_lshl_b64 s[4:5], s[4:5], 12
	v_lshl_add_u64 v[38:39], v[48:49], 0, s[4:5]
	s_add_i32 s4, s0, 0xffffe628
	s_mov_b32 s5, s13
	s_lshl_b64 s[4:5], s[4:5], 12
	global_load_dword v24, v[24:25], off
	s_nop 0
	global_load_dword v25, v[26:27], off
	s_nop 0
	global_load_dword v26, v[28:29], off
	global_load_dword v27, v[30:31], off
	s_nop 0
	global_load_dword v28, v[32:33], off
	global_load_dword v29, v[34:35], off
	global_load_dword v30, v[36:37], off
	global_load_dword v31, v[38:39], off
	v_lshl_add_u64 v[32:33], v[48:49], 0, s[4:5]
	s_add_i32 s4, s0, 0xffffe629
	s_mov_b32 s5, s13
	s_lshl_b64 s[4:5], s[4:5], 12
	v_lshl_add_u64 v[34:35], v[48:49], 0, s[4:5]
	s_add_i32 s4, s0, 0xffffe62a
	s_mov_b32 s5, s13
	s_lshl_b64 s[4:5], s[4:5], 12
	v_lshl_add_u64 v[36:37], v[48:49], 0, s[4:5]
	s_add_i32 s4, s0, 0xffffe62b
	s_mov_b32 s5, s13
	s_lshl_b64 s[4:5], s[4:5], 12
	v_lshl_add_u64 v[38:39], v[48:49], 0, s[4:5]
	s_add_i32 s4, s0, 0xffffe62c
	s_mov_b32 s5, s13
	s_lshl_b64 s[4:5], s[4:5], 12
	v_lshl_add_u64 v[40:41], v[48:49], 0, s[4:5]
	s_add_i32 s4, s0, 0xffffe62d
	s_mov_b32 s5, s13
	s_lshl_b64 s[4:5], s[4:5], 12
	v_lshl_add_u64 v[42:43], v[48:49], 0, s[4:5]
	s_add_i32 s4, s0, 0xffffe62e
	s_mov_b32 s5, s13
	s_lshl_b64 s[4:5], s[4:5], 12
	v_lshl_add_u64 v[44:45], v[48:49], 0, s[4:5]
	s_add_i32 s4, s0, 0xffffe62f
	s_mov_b32 s5, s13
	s_lshl_b64 s[4:5], s[4:5], 12
	v_lshl_add_u64 v[46:47], v[48:49], 0, s[4:5]
	s_add_i32 s4, s0, 0xffffe630
	s_mov_b32 s5, s13
	s_lshl_b64 s[4:5], s[4:5], 12
	global_load_dword v32, v[32:33], off
	s_nop 0
	global_load_dword v33, v[34:35], off
	s_nop 0
	global_load_dword v34, v[36:37], off
	global_load_dword v35, v[38:39], off
	s_nop 0
	global_load_dword v36, v[40:41], off
	global_load_dword v37, v[42:43], off
	global_load_dword v38, v[44:45], off
	global_load_dword v39, v[46:47], off
	v_lshl_add_u64 v[40:41], v[48:49], 0, s[4:5]
	s_add_i32 s4, s0, 0xffffe631
	s_mov_b32 s5, s13
	s_lshl_b64 s[4:5], s[4:5], 12
	v_lshl_add_u64 v[42:43], v[48:49], 0, s[4:5]
	s_add_i32 s4, s0, 0xffffe632
	s_mov_b32 s5, s13
	s_lshl_b64 s[4:5], s[4:5], 12
	v_lshl_add_u64 v[44:45], v[48:49], 0, s[4:5]
	s_add_i32 s4, s0, 0xffffe633
	s_mov_b32 s5, s13
	s_lshl_b64 s[4:5], s[4:5], 12
	v_lshl_add_u64 v[46:47], v[48:49], 0, s[4:5]
	s_add_i32 s4, s0, 0xffffe634
	s_mov_b32 s5, s13
	s_lshl_b64 s[4:5], s[4:5], 12
	v_lshl_add_u64 v[50:51], v[48:49], 0, s[4:5]
	s_add_i32 s4, s0, 0xffffe635
	s_mov_b32 s5, s13
	s_lshl_b64 s[4:5], s[4:5], 12
	v_lshl_add_u64 v[52:53], v[48:49], 0, s[4:5]
	s_add_i32 s4, s0, 0xffffe636
	s_mov_b32 s5, s13
	s_lshl_b64 s[4:5], s[4:5], 12
	v_lshl_add_u64 v[54:55], v[48:49], 0, s[4:5]
	s_add_i32 s4, s0, 0xffffe637
	s_mov_b32 s5, s13
	s_lshl_b64 s[4:5], s[4:5], 12
	v_lshl_add_u64 v[56:57], v[48:49], 0, s[4:5]
	s_add_i32 s4, s0, 0xffffe638
	s_mov_b32 s5, s13
	s_lshl_b64 s[4:5], s[4:5], 12
	global_load_dword v40, v[40:41], off
	s_nop 0
	global_load_dword v41, v[42:43], off
	s_nop 0
	global_load_dword v42, v[44:45], off
	global_load_dword v43, v[46:47], off
	s_nop 0
	global_load_dword v44, v[50:51], off
	global_load_dword v45, v[52:53], off
	global_load_dword v46, v[54:55], off
	global_load_dword v47, v[56:57], off
	v_lshl_add_u64 v[50:51], v[48:49], 0, s[4:5]
	s_add_i32 s4, s0, 0xffffe639
	s_mov_b32 s5, s13
	s_lshl_b64 s[4:5], s[4:5], 12
	v_lshl_add_u64 v[52:53], v[48:49], 0, s[4:5]
	s_add_i32 s4, s0, 0xffffe63a
	s_mov_b32 s5, s13
	s_lshl_b64 s[4:5], s[4:5], 12
	v_lshl_add_u64 v[54:55], v[48:49], 0, s[4:5]
	s_add_i32 s4, s0, 0xffffe63b
	s_mov_b32 s5, s13
	s_lshl_b64 s[4:5], s[4:5], 12
	v_lshl_add_u64 v[56:57], v[48:49], 0, s[4:5]
	s_add_i32 s4, s0, 0xffffe63c
	s_mov_b32 s5, s13
	s_lshl_b64 s[4:5], s[4:5], 12
	v_lshl_add_u64 v[58:59], v[48:49], 0, s[4:5]
	s_add_i32 s4, s0, 0xffffe63d
	s_mov_b32 s5, s13
	s_lshl_b64 s[4:5], s[4:5], 12
	v_lshl_add_u64 v[60:61], v[48:49], 0, s[4:5]
	s_add_i32 s4, s0, 0xffffe63e
	s_mov_b32 s5, s13
	s_addk_i32 s0, 0xe63f
	s_mov_b32 s1, s13
	s_lshl_b64 s[4:5], s[4:5], 12
	s_lshl_b64 s[0:1], s[0:1], 12
	v_lshl_add_u64 v[62:63], v[48:49], 0, s[4:5]
	v_lshl_add_u64 v[64:65], v[48:49], 0, s[0:1]
	global_load_dword v48, v[50:51], off
	global_load_dword v49, v[52:53], off
	s_nop 0
	global_load_dword v50, v[54:55], off
	global_load_dword v51, v[56:57], off
	global_load_dword v52, v[58:59], off
	global_load_dword v53, v[60:61], off
	s_nop 0
	global_load_dword v54, v[62:63], off
	global_load_dword v55, v[64:65], off
	v_mov_b64_e32 v[56:57], s[26:27]
	s_movk_i32 s0, 0x1600
	v_mad_u64_u32 v[56:57], s[0:1], v66, s0, v[56:57]
	v_lshl_add_u64 v[60:61], s[12:13], 1, v[56:57]
	s_mov_b64 s[0:1], 0x1300000
	v_lshl_add_u64 v[64:65], v[60:61], 0, s[0:1]
	s_mov_b32 s0, 0x1300000
	v_add_co_u32_e32 v60, vcc, s0, v60
	s_waitcnt vmcnt(0)
	v_cvt_pk_bf16_f32 v56, v67, v68
	v_cvt_pk_bf16_f32 v57, v69, v70
	v_cvt_pk_bf16_f32 v58, v71, v72
	v_cvt_pk_bf16_f32 v59, v73, v74
	v_addc_co_u32_e32 v61, vcc, 0, v61, vcc
	global_store_dwordx4 v[60:61], v[56:59], off sc1
	s_mov_b64 s[0:1], 0

; DI void transpose_item(const float* W, int ldw, int k0, int n, bf16_t* WT, int Kd, int dst_row, const float* kscale) {
;     ...
;     bf16_t* d = WT + (size_t)dst_row * Kd + k0;
; #pragma unroll
;     for (int c = 0; c < 8; ++c) { u32x4 o; o.x = pk2(v[8 * c], v[8 * c + 1]); o.y = pk2(v[8 * c + 2], v[8 * c + 3]); o.z = pk2(v[8 * c + 4], v[8 * c + 5]); o.w = pk2(v[8 * c + 6], v[8 * c + 7]);
;         *(u32x4*)(d + 8 * c) = o; }
; DI void weight_item(KArgs ap, int it, int lane) {
;     ...
;     if (r < WI_GU) { const int kb = r / 88, nb = r % 88; const int L = 64 * nb + lane; const int Lp = L < DFF ? L : L - DFF;
;         transpose_item(ap->in[17], NGU, 64 * kb, L, (bf16_t*)(ws + WS_WGU), DM, 256 * (Lp >> 7) + (L < DFF ? 0 : 128) + (Lp & 127), ap->in[16]); return; }
.LBB0_707:
	s_and_b32 s1, 0xffff, s1
	s_cmp_lt_u32 s1, 44
	v_add_u32_e32 v64, 0xfffff500, v66
	s_cselect_b64 vcc, -1, 0
	v_cndmask_b32_e32 v64, v64, v66, vcc
	v_lshlrev_b32_e32 v65, 1, v64
	s_and_b64 s[4:5], vcc, exec
	v_and_b32_e32 v65, 0xffffff00, v65
	s_cselect_b32 s1, 0, 0x80
	v_and_b32_e32 v64, 0x7f, v64
	v_or3_b32 v64, v64, s1, v65
	v_ashrrev_i32_e32 v65, 31, v64
	v_lshlrev_b64 v[64:65], 11, v[64:65]
	v_lshl_add_u64 v[64:65], s[26:27], 0, v[64:65]
	s_lshl_b32 s12, s0, 1
	v_lshl_add_u64 v[66:67], v[64:65], 0, s[12:13]
	s_waitcnt vmcnt(0)
	v_cvt_pk_bf16_f32 v56, v56, v57
	v_cvt_pk_bf16_f32 v57, v58, v59
	v_cvt_pk_bf16_f32 v58, v60, v61
	v_add_co_u32_e32 v60, vcc, 0x800000, v66
	v_lshl_add_u64 v[64:65], v[66:67], 0, s[22:23]
	v_cvt_pk_bf16_f32 v59, v62, v63
	v_addc_co_u32_e32 v61, vcc, 0, v67, vcc
	global_store_dwordx4 v[60:61], v[56:59], off sc1

; DI void transpose_item(const float* W, int ldw, int k0, int n, bf16_t* WT, int Kd, int dst_row, const float* kscale) {
;     float v[64];
; #pragma unroll
;     for (int i = 0; i < 64; ++i) v[i] = W[(size_t)(k0 + i) * ldw + n];
; DI void weight_item(KArgs ap, int it, int lane) {
;     ...
;     if (r < WI_OUT) { const int kb = r / 16, nb = r % 16; transpose_item(ap->in[15], DM, 64 * kb, 64 * nb + lane, (bf16_t*)(ws + WS_WOUT), DM, 64 * nb + lane, nullptr); return; }
.LBB0_709:
	s_andn2_b64 vcc, exec, s[0:1]
	s_cbranch_vccnz .LBB0_603
	s_ashr_i32 s0, s91, 31
	s_lshr_b32 s0, s0, 28
	s_add_i32 s0, s91, s0
	s_load_dwordx2 s[4:5], s[28:29], 0x78
	s_and_b32 s1, s0, 0x3fffff0
	s_sub_i32 s1, s91, s1
	s_lshl_b32 s0, s0, 2
	s_andn2_b32 s0, s0, 63
	v_lshl_or_b32 v56, s1, 6, v190
	v_ashrrev_i32_e32 v57, 31, v56
	s_ashr_i32 s1, s0, 31
	s_waitcnt lgkmcnt(0)
	v_lshl_add_u64 v[48:49], v[56:57], 2, s[4:5]
	s_lshl_b64 s[4:5], s[0:1], 12
	v_lshl_add_u64 v[0:1], v[48:49], 0, s[4:5]
	s_or_b32 s4, s0, 1
	s_ashr_i32 s5, s4, 31
	s_lshl_b64 s[4:5], s[4:5], 12
	v_lshl_add_u64 v[2:3], v[48:49], 0, s[4:5]
	s_or_b32 s4, s0, 2
	s_ashr_i32 s5, s4, 31
	s_lshl_b64 s[4:5], s[4:5], 12
	v_lshl_add_u64 v[4:5], v[48:49], 0, s[4:5]
	s_or_b32 s4, s0, 3
	s_ashr_i32 s5, s4, 31
	s_lshl_b64 s[4:5], s[4:5], 12
	v_lshl_add_u64 v[6:7], v[48:49], 0, s[4:5]
	s_or_b32 s4, s0, 4
	s_ashr_i32 s5, s4, 31
	s_lshl_b64 s[4:5], s[4:5], 12
	v_lshl_add_u64 v[8:9], v[48:49], 0, s[4:5]
	s_or_b32 s4, s0, 5
	s_ashr_i32 s5, s4, 31
	s_lshl_b64 s[4:5], s[4:5], 12
	v_lshl_add_u64 v[10:11], v[48:49], 0, s[4:5]
	s_or_b32 s4, s0, 6
	s_ashr_i32 s5, s4, 31
	s_lshl_b64 s[4:5], s[4:5], 12
	v_lshl_add_u64 v[12:13], v[48:49], 0, s[4:5]
	s_or_b32 s4, s0, 7
	s_ashr_i32 s5, s4, 31
	s_lshl_b64 s[4:5], s[4:5], 12
	v_lshl_add_u64 v[14:15], v[48:49], 0, s[4:5]
	s_or_b32 s4, s0, 8
	s_ashr_i32 s5, s4, 31
	s_lshl_b64 s[4:5], s[4:5], 12
	global_load_dword v68, v[0:1], off
	global_load_dword v69, v[2:3], off
	global_load_dword v70, v[4:5], off
	global_load_dword v71, v[6:7], off
	global_load_dword v72, v[8:9], off
	global_load_dword v73, v[10:11], off
	global_load_dword v74, v[12:13], off
	global_load_dword v75, v[14:15], off
	v_lshl_add_u64 v[0:1], v[48:49], 0, s[4:5]
	s_or_b32 s4, s0, 9
	s_ashr_i32 s5, s4, 31
	s_lshl_b64 s[4:5], s[4:5], 12
	v_lshl_add_u64 v[2:3], v[48:49], 0, s[4:5]
	s_or_b32 s4, s0, 10
	s_ashr_i32 s5, s4, 31
	s_lshl_b64 s[4:5], s[4:5], 12
	v_lshl_add_u64 v[4:5], v[48:49], 0, s[4:5]
	s_or_b32 s4, s0, 11
	s_ashr_i32 s5, s4, 31
	s_lshl_b64 s[4:5], s[4:5], 12
	v_lshl_add_u64 v[6:7], v[48:49], 0, s[4:5]
	s_or_b32 s4, s0, 12
	s_ashr_i32 s5, s4, 31
	s_lshl_b64 s[4:5], s[4:5], 12
	v_lshl_add_u64 v[8:9], v[48:49], 0, s[4:5]
	s_or_b32 s4, s0, 13
	s_ashr_i32 s5, s4, 31
	s_lshl_b64 s[4:5], s[4:5], 12
	v_lshl_add_u64 v[10:11], v[48:49], 0, s[4:5]
	s_or_b32 s4, s0, 14
	s_ashr_i32 s5, s4, 31
	s_lshl_b64 s[4:5], s[4:5], 12
	v_lshl_add_u64 v[12:13], v[48:49], 0, s[4:5]
	s_or_b32 s4, s0, 15
	s_ashr_i32 s5, s4, 31
	s_lshl_b64 s[4:5], s[4:5], 12
	v_lshl_add_u64 v[14:15], v[48:49], 0, s[4:5]
	s_or_b32 s4, s0, 16
	s_ashr_i32 s5, s4, 31
	s_lshl_b64 s[4:5], s[4:5], 12
	global_load_dword v0, v[0:1], off
	s_nop 0
	global_load_dword v1, v[2:3], off
	s_nop 0
	global_load_dword v2, v[4:5], off
	global_load_dword v3, v[6:7], off
	s_nop 0
	global_load_dword v4, v[8:9], off
	global_load_dword v5, v[10:11], off
	global_load_dword v6, v[12:13], off
	global_load_dword v7, v[14:15], off
	v_lshl_add_u64 v[8:9], v[48:49], 0, s[4:5]
	s_or_b32 s4, s0, 17
	s_ashr_i32 s5, s4, 31
	s_lshl_b64 s[4:5], s[4:5], 12
	v_lshl_add_u64 v[10:11], v[48:49], 0, s[4:5]
	s_or_b32 s4, s0, 18
	s_ashr_i32 s5, s4, 31
	s_lshl_b64 s[4:5], s[4:5], 12
	v_lshl_add_u64 v[12:13], v[48:49], 0, s[4:5]
	s_or_b32 s4, s0, 19
	s_ashr_i32 s5, s4, 31
	s_lshl_b64 s[4:5], s[4:5], 12
	v_lshl_add_u64 v[14:15], v[48:49], 0, s[4:5]
	s_or_b32 s4, s0, 20
	s_ashr_i32 s5, s4, 31
	s_lshl_b64 s[4:5], s[4:5], 12
	v_lshl_add_u64 v[16:17], v[48:49], 0, s[4:5]
	s_or_b32 s4, s0, 21
	s_ashr_i32 s5, s4, 31
	s_lshl_b64 s[4:5], s[4:5], 12
	v_lshl_add_u64 v[18:19], v[48:49], 0, s[4:5]
	s_or_b32 s4, s0, 22
	s_ashr_i32 s5, s4, 31
	s_lshl_b64 s[4:5], s[4:5], 12
	v_lshl_add_u64 v[20:21], v[48:49], 0, s[4:5]
	s_or_b32 s4, s0, 23
	s_ashr_i32 s5, s4, 31
	s_lshl_b64 s[4:5], s[4:5], 12
	v_lshl_add_u64 v[22:23], v[48:49], 0, s[4:5]
	s_or_b32 s4, s0, 24
	s_ashr_i32 s5, s4, 31
	s_lshl_b64 s[4:5], s[4:5], 12
	global_load_dword v8, v[8:9], off
	s_nop 0
	global_load_dword v9, v[10:11], off
	s_nop 0
	global_load_dword v10, v[12:13], off
	global_load_dword v11, v[14:15], off
	s_nop 0
	global_load_dword v12, v[16:17], off
	global_load_dword v13, v[18:19], off
	global_load_dword v14, v[20:21], off
	global_load_dword v15, v[22:23], off
	v_lshl_add_u64 v[16:17], v[48:49], 0, s[4:5]
	s_or_b32 s4, s0, 25
	s_ashr_i32 s5, s4, 31
	s_lshl_b64 s[4:5], s[4:5], 12
	v_lshl_add_u64 v[18:19], v[48:49], 0, s[4:5]
	s_or_b32 s4, s0, 26
	s_ashr_i32 s5, s4, 31
	s_lshl_b64 s[4:5], s[4:5], 12
	v_lshl_add_u64 v[20:21], v[48:49], 0, s[4:5]
	s_or_b32 s4, s0, 27
	s_ashr_i32 s5, s4, 31
	s_lshl_b64 s[4:5], s[4:5], 12
	v_lshl_add_u64 v[22:23], v[48:49], 0, s[4:5]
	s_or_b32 s4, s0, 28
	s_ashr_i32 s5, s4, 31
	s_lshl_b64 s[4:5], s[4:5], 12
	v_lshl_add_u64 v[24:25], v[48:49], 0, s[4:5]
	s_or_b32 s4, s0, 29
	s_ashr_i32 s5, s4, 31
	s_lshl_b64 s[4:5], s[4:5], 12
	v_lshl_add_u64 v[26:27], v[48:49], 0, s[4:5]
	s_or_b32 s4, s0, 30
	s_ashr_i32 s5, s4, 31
	s_lshl_b64 s[4:5], s[4:5], 12
	v_lshl_add_u64 v[28:29], v[48:49], 0, s[4:5]
	s_or_b32 s4, s0, 31
	s_ashr_i32 s5, s4, 31
	s_lshl_b64 s[4:5], s[4:5], 12
	v_lshl_add_u64 v[30:31], v[48:49], 0, s[4:5]
	s_or_b32 s4, s0, 32
	s_ashr_i32 s5, s4, 31
	s_lshl_b64 s[4:5], s[4:5], 12
	global_load_dword v16, v[16:17], off
	s_nop 0
	global_load_dword v17, v[18:19], off
	s_nop 0
	global_load_dword v18, v[20:21], off
	global_load_dword v19, v[22:23], off
	s_nop 0
	global_load_dword v20, v[24:25], off
	global_load_dword v21, v[26:27], off
	global_load_dword v22, v[28:29], off
	global_load_dword v23, v[30:31], off
; DI void transpose_item(const float* W, int ldw, int k0, int n, bf16_t* WT, int Kd, int dst_row, const float* kscale) {
;     ...
;     for (int i = 0; i < 64; ++i) v[i] = W[(size_t)(k0 + i) * ldw + n];
;     if (kscale) {
; #pragma unroll
;         for (int i = 0; i < 64; ++i) v[i] *= kscale[k0 + i];
;     }
;     bf16_t* d = WT + (size_t)dst_row * Kd + k0;
; #pragma unroll
;     for (int c = 0; c < 8; ++c) { u32x4 o; o.x = pk2(v[8 * c], v[8 * c + 1]); o.y = pk2(v[8 * c + 2], v[8 * c + 3]); o.z = pk2(v[8 * c + 4], v[8 * c + 5]); o.w = pk2(v[8 * c + 6], v[8 * c + 7]);
;         *(u32x4*)(d + 8 * c) = o; }
	v_lshl_add_u64 v[24:25], v[48:49], 0, s[4:5]
	s_or_b32 s4, s0, 33
	s_ashr_i32 s5, s4, 31
	s_lshl_b64 s[4:5], s[4:5], 12
	v_lshl_add_u64 v[26:27], v[48:49], 0, s[4:5]
	s_or_b32 s4, s0, 34
	s_ashr_i32 s5, s4, 31
	s_lshl_b64 s[4:5], s[4:5], 12
	v_lshl_add_u64 v[28:29], v[48:49], 0, s[4:5]
	s_or_b32 s4, s0, 35
	s_ashr_i32 s5, s4, 31
	s_lshl_b64 s[4:5], s[4:5], 12
	v_lshl_add_u64 v[30:31], v[48:49], 0, s[4:5]
	s_or_b32 s4, s0, 36
	s_ashr_i32 s5, s4, 31
	s_lshl_b64 s[4:5], s[4:5], 12
	v_lshl_add_u64 v[32:33], v[48:49], 0, s[4:5]
	s_or_b32 s4, s0, 37
	s_ashr_i32 s5, s4, 31
	s_lshl_b64 s[4:5], s[4:5], 12
	v_lshl_add_u64 v[34:35], v[48:49], 0, s[4:5]
	s_or_b32 s4, s0, 38
	s_ashr_i32 s5, s4, 31
	s_lshl_b64 s[4:5], s[4:5], 12
	v_lshl_add_u64 v[36:37], v[48:49], 0, s[4:5]
	s_or_b32 s4, s0, 39
	s_ashr_i32 s5, s4, 31
	s_lshl_b64 s[4:5], s[4:5], 12
	v_lshl_add_u64 v[38:39], v[48:49], 0, s[4:5]
	s_or_b32 s4, s0, 40
	s_ashr_i32 s5, s4, 31
	s_lshl_b64 s[4:5], s[4:5], 12
	global_load_dword v24, v[24:25], off
	s_nop 0
	global_load_dword v25, v[26:27], off
	s_nop 0
	global_load_dword v26, v[28:29], off
	global_load_dword v27, v[30:31], off
	s_nop 0
	global_load_dword v28, v[32:33], off
	global_load_dword v29, v[34:35], off
	global_load_dword v30, v[36:37], off
	global_load_dword v31, v[38:39], off
	v_lshl_add_u64 v[32:33], v[48:49], 0, s[4:5]
	s_or_b32 s4, s0, 41
	s_ashr_i32 s5, s4, 31
	s_lshl_b64 s[4:5], s[4:5], 12
	v_lshl_add_u64 v[34:35], v[48:49], 0, s[4:5]
	s_or_b32 s4, s0, 42
	s_ashr_i32 s5, s4, 31
	s_lshl_b64 s[4:5], s[4:5], 12
	v_lshl_add_u64 v[36:37], v[48:49], 0, s[4:5]
	s_or_b32 s4, s0, 43
	s_ashr_i32 s5, s4, 31
	s_lshl_b64 s[4:5], s[4:5], 12
	v_lshl_add_u64 v[38:39], v[48:49], 0, s[4:5]
	s_or_b32 s4, s0, 44
	s_ashr_i32 s5, s4, 31
	s_lshl_b64 s[4:5], s[4:5], 12
	v_lshl_add_u64 v[40:41], v[48:49], 0, s[4:5]
	s_or_b32 s4, s0, 45
	s_ashr_i32 s5, s4, 31
	s_lshl_b64 s[4:5], s[4:5], 12
	v_lshl_add_u64 v[42:43], v[48:49], 0, s[4:5]
	s_or_b32 s4, s0, 46
	s_ashr_i32 s5, s4, 31
	s_lshl_b64 s[4:5], s[4:5], 12
	v_lshl_add_u64 v[44:45], v[48:49], 0, s[4:5]
	s_or_b32 s4, s0, 47
	s_ashr_i32 s5, s4, 31
	s_lshl_b64 s[4:5], s[4:5], 12
	v_lshl_add_u64 v[46:47], v[48:49], 0, s[4:5]
	s_or_b32 s4, s0, 48
	s_ashr_i32 s5, s4, 31
	s_lshl_b64 s[4:5], s[4:5], 12
	global_load_dword v32, v[32:33], off
	s_nop 0
	global_load_dword v33, v[34:35], off
	s_nop 0
	global_load_dword v34, v[36:37], off
	global_load_dword v35, v[38:39], off
	s_nop 0
	global_load_dword v36, v[40:41], off
	global_load_dword v37, v[42:43], off
	global_load_dword v38, v[44:45], off
	global_load_dword v39, v[46:47], off
	v_lshl_add_u64 v[40:41], v[48:49], 0, s[4:5]
	s_or_b32 s4, s0, 49
	s_ashr_i32 s5, s4, 31
	s_lshl_b64 s[4:5], s[4:5], 12
	v_lshl_add_u64 v[42:43], v[48:49], 0, s[4:5]
	s_or_b32 s4, s0, 50
	s_ashr_i32 s5, s4, 31
	s_lshl_b64 s[4:5], s[4:5], 12
	v_lshl_add_u64 v[44:45], v[48:49], 0, s[4:5]
	s_or_b32 s4, s0, 51
	s_ashr_i32 s5, s4, 31
	s_lshl_b64 s[4:5], s[4:5], 12
	v_lshl_add_u64 v[46:47], v[48:49], 0, s[4:5]
	s_or_b32 s4, s0, 52
	s_ashr_i32 s5, s4, 31
	s_lshl_b64 s[4:5], s[4:5], 12
	v_lshl_add_u64 v[50:51], v[48:49], 0, s[4:5]
	s_or_b32 s4, s0, 53
	s_ashr_i32 s5, s4, 31
	s_lshl_b64 s[4:5], s[4:5], 12
	v_lshl_add_u64 v[52:53], v[48:49], 0, s[4:5]
	s_or_b32 s4, s0, 54
	s_ashr_i32 s5, s4, 31
	s_lshl_b64 s[4:5], s[4:5], 12
	v_lshl_add_u64 v[54:55], v[48:49], 0, s[4:5]
	s_or_b32 s4, s0, 55
	s_ashr_i32 s5, s4, 31
	s_lshl_b64 s[4:5], s[4:5], 12
	v_lshl_add_u64 v[58:59], v[48:49], 0, s[4:5]
	s_or_b32 s4, s0, 56
	s_ashr_i32 s5, s4, 31
	s_lshl_b64 s[4:5], s[4:5], 12
	global_load_dword v40, v[40:41], off
	s_nop 0
	global_load_dword v41, v[42:43], off
	s_nop 0
	global_load_dword v42, v[44:45], off
	global_load_dword v43, v[46:47], off
	s_nop 0
	global_load_dword v44, v[50:51], off
	global_load_dword v45, v[52:53], off
	global_load_dword v46, v[54:55], off
	global_load_dword v47, v[58:59], off
	v_lshl_add_u64 v[50:51], v[48:49], 0, s[4:5]
	s_or_b32 s4, s0, 57
	s_ashr_i32 s5, s4, 31
	s_lshl_b64 s[4:5], s[4:5], 12
	v_lshl_add_u64 v[52:53], v[48:49], 0, s[4:5]
	s_or_b32 s4, s0, 58
	s_ashr_i32 s5, s4, 31
	s_lshl_b64 s[4:5], s[4:5], 12
	v_lshl_add_u64 v[54:55], v[48:49], 0, s[4:5]
	s_or_b32 s4, s0, 59
	s_ashr_i32 s5, s4, 31
	s_lshl_b64 s[4:5], s[4:5], 12
	v_lshl_add_u64 v[58:59], v[48:49], 0, s[4:5]
	s_or_b32 s4, s0, 60
	s_ashr_i32 s5, s4, 31
	s_lshl_b64 s[4:5], s[4:5], 12
	v_lshl_add_u64 v[60:61], v[48:49], 0, s[4:5]
	s_or_b32 s4, s0, 61
	s_ashr_i32 s5, s4, 31
	s_lshl_b64 s[4:5], s[4:5], 12
	v_lshl_add_u64 v[62:63], v[48:49], 0, s[4:5]
	s_or_b32 s4, s0, 62
	s_ashr_i32 s5, s4, 31
	s_lshl_b64 s[4:5], s[4:5], 12
	v_lshl_add_u64 v[64:65], v[48:49], 0, s[4:5]
	s_or_b32 s4, s0, 63
	s_ashr_i32 s5, s4, 31
	s_lshl_b64 s[4:5], s[4:5], 12
	v_lshl_add_u64 v[66:67], v[48:49], 0, s[4:5]
	global_load_dword v48, v[50:51], off
	global_load_dword v49, v[52:53], off
	s_nop 0
	global_load_dword v50, v[54:55], off
	global_load_dword v51, v[58:59], off
	global_load_dword v52, v[60:61], off
	global_load_dword v53, v[62:63], off
	s_nop 0
	global_load_dword v54, v[64:65], off
	global_load_dword v55, v[66:67], off
	v_lshlrev_b64 v[56:57], 11, v[56:57]
	v_lshl_add_u64 v[56:57], s[26:27], 0, v[56:57]
	v_lshl_add_u64 v[60:61], s[0:1], 1, v[56:57]
	v_lshl_add_u64 v[64:65], v[60:61], 0, s[24:25]
	v_add_co_u32_e32 v60, vcc, s90, v60
	s_waitcnt vmcnt(0)
	v_cvt_pk_bf16_f32 v56, v68, v69
	v_cvt_pk_bf16_f32 v57, v70, v71
	v_cvt_pk_bf16_f32 v58, v72, v73
	v_cvt_pk_bf16_f32 v59, v74, v75
	v_addc_co_u32_e32 v61, vcc, 0, v61, vcc
	global_store_dwordx4 v[60:61], v[56:59], off sc1
	s_branch .LBB0_603

;     DI void operator()(const AccT& acc, const Unit& u, int wr, int wc, int fr, int fq, LAS unsigned char*) const {
;     ...
;             u32x2 xb[4][2][2];
; #pragma unroll
;             for (int m = 0; m < 4; ++m) {
;                 const int row = u.pm * 256 + ai * 128 + wr * 64 + m * 16 + fr;
;                 const bf16_t* brow = X1B + (size_t)(row < SEQ ? row + 2 : row + (X1B_PROMPT_ROWS - SEQ)) * DM + col0;
; #pragma unroll
;                 for (int bj = 0; bj < 2; ++bj)
; #pragma unroll
;                     for (int n = 0; n < 2; ++n) xb[m][bj][n] = *(const u32x2*)(brow + bj * 128 + n * 16);
;             }
;             asm volatile("" ::: "memory");
; #pragma unroll
;             for (int m = 0; m < 4; ++m) {
;                 const int row = u.pm * 256 + ai * 128 + wr * 64 + m * 16 + fr;
;                 float* orow = out + (size_t)row * DM + col0;
; #pragma unroll
;                 for (int bj = 0; bj < 2; ++bj)
; #pragma unroll
;                     for (int n = 0; n < 2; ++n) { const u32x2 b = xb[m][bj][n];
;                         const f32x4 xr = {__uint_as_float(b.x << 16), __uint_as_float(b.x & 0xffff0000u), __uint_as_float(b.y << 16), __uint_as_float(b.y & 0xffff0000u)};
;                         *(f32x4*)(orow + bj * 128 + n * 16) = xr + acc[ai][bj][m][n]; }
.LBB0_794:
	v_lshl_add_u32 v132, s21, 8, v164
	v_lshl_or_b32 v128, s30, 8, v166
	s_cmp_lt_i32 s21, 64
	s_cselect_b32 s43, 1, 64
	s_lshl_b32 s43, s43, 12
	s_add_u32 s16, s56, s43
	s_addc_u32 s17, s57, 0
	v_lshlrev_b32_e32 v129, 11, v132
	v_lshlrev_b32_e32 v133, 12, v132
	v_lshl_add_u32 v129, v128, 1, v129
	v_lshl_add_u32 v133, v128, 2, v133
	v_and_b32_e32 v128, 16, v226
	v_lshrrev_b32_e32 v132, 1, v128
	v_add3_u32 v129, v129, v128, v132
	global_load_dwordx4 v[136:139], v129, s[16:17]
	global_load_dwordx4 v[140:143], v129, s[16:17] offset:256
	s_add_u32 s18, s16, 0x8000
	s_addc_u32 s19, s17, 0
	global_load_dwordx4 v[144:147], v129, s[18:19]
	global_load_dwordx4 v[148:151], v129, s[18:19] offset:256
	s_add_u32 s18, s16, 0x10000
	s_addc_u32 s19, s17, 0
	global_load_dwordx4 v[152:155], v129, s[18:19]
	global_load_dwordx4 v[156:159], v129, s[18:19] offset:256
	s_add_u32 s18, s16, 0x18000
	s_addc_u32 s19, s17, 0
	global_load_dwordx4 v[160:163], v129, s[18:19]
	global_load_dwordx4 v[182:185], v129, s[18:19] offset:256
	s_add_u32 s18, s16, 0x40000
	s_addc_u32 s19, s17, 0
	global_load_dwordx4 v[186:189], v129, s[18:19]
	global_load_dwordx4 v[190:193], v129, s[18:19] offset:256
	s_add_u32 s18, s16, 0x48000
	s_addc_u32 s19, s17, 0
	global_load_dwordx4 v[194:197], v129, s[18:19]
	global_load_dwordx4 v[198:201], v129, s[18:19] offset:256
	s_add_u32 s18, s16, 0x50000
	s_addc_u32 s19, s17, 0
	global_load_dwordx4 v[202:205], v129, s[18:19]
	global_load_dwordx4 v[206:209], v129, s[18:19] offset:256
	s_add_u32 s18, s16, 0x58000
	s_addc_u32 s19, s17, 0
	global_load_dwordx4 v[210:213], v129, s[18:19]
	global_load_dwordx4 v[214:217], v129, s[18:19] offset:256
	s_waitcnt vmcnt(14)
	v_permlane16_swap_b32_e32 v136, v138
	v_permlane16_swap_b32_e32 v137, v139
	v_permlane16_swap_b32_e32 v140, v142
	v_permlane16_swap_b32_e32 v141, v143
	v_lshlrev_b32_e32 v130, 16, v136
	v_and_b32_e32 v131, 0xffff0000, v136
	v_lshlrev_b32_e32 v134, 16, v137
	v_and_b32_e32 v135, 0xffff0000, v137
	v_pk_add_f32 v[124:125], v[124:125], v[130:131]
	v_pk_add_f32 v[126:127], v[126:127], v[134:135]
	v_lshlrev_b32_e32 v130, 16, v138
	v_and_b32_e32 v131, 0xffff0000, v138
	v_lshlrev_b32_e32 v134, 16, v139
	v_and_b32_e32 v135, 0xffff0000, v139
	v_pk_add_f32 v[120:121], v[120:121], v[130:131]
	v_pk_add_f32 v[122:123], v[122:123], v[134:135]
	v_lshlrev_b32_e32 v130, 16, v140
	v_and_b32_e32 v131, 0xffff0000, v140
	v_lshlrev_b32_e32 v134, 16, v141
	v_and_b32_e32 v135, 0xffff0000, v141
	v_pk_add_f32 v[116:117], v[116:117], v[130:131]
	v_pk_add_f32 v[118:119], v[118:119], v[134:135]
	v_lshlrev_b32_e32 v130, 16, v142
	v_and_b32_e32 v131, 0xffff0000, v142
	v_lshlrev_b32_e32 v134, 16, v143
	v_and_b32_e32 v135, 0xffff0000, v143
	v_pk_add_f32 v[112:113], v[112:113], v[130:131]
	v_pk_add_f32 v[114:115], v[114:115], v[134:135]
	global_store_dwordx4 v133, v[124:127], s[6:7] sc1
	global_store_dwordx4 v133, v[120:123], s[6:7] offset:64 sc1
	global_store_dwordx4 v133, v[116:119], s[6:7] offset:512 sc1
	global_store_dwordx4 v133, v[112:115], s[6:7] offset:576 sc1
	s_waitcnt vmcnt(16)
	v_permlane16_swap_b32_e32 v144, v146
	v_permlane16_swap_b32_e32 v145, v147
	v_permlane16_swap_b32_e32 v148, v150
	v_permlane16_swap_b32_e32 v149, v151
	v_lshlrev_b32_e32 v130, 16, v144
	v_and_b32_e32 v131, 0xffff0000, v144
	v_lshlrev_b32_e32 v134, 16, v145
	v_and_b32_e32 v135, 0xffff0000, v145
	v_pk_add_f32 v[108:109], v[108:109], v[130:131]
	v_pk_add_f32 v[110:111], v[110:111], v[134:135]
	v_lshlrev_b32_e32 v130, 16, v146
	v_and_b32_e32 v131, 0xffff0000, v146
	v_lshlrev_b32_e32 v134, 16, v147
	v_and_b32_e32 v135, 0xffff0000, v147
	v_pk_add_f32 v[104:105], v[104:105], v[130:131]
	v_pk_add_f32 v[106:107], v[106:107], v[134:135]
	v_lshlrev_b32_e32 v130, 16, v148
	v_and_b32_e32 v131, 0xffff0000, v148
	v_lshlrev_b32_e32 v134, 16, v149
	v_and_b32_e32 v135, 0xffff0000, v149
	v_pk_add_f32 v[100:101], v[100:101], v[130:131]
	v_pk_add_f32 v[102:103], v[102:103], v[134:135]
	v_lshlrev_b32_e32 v130, 16, v150
	v_and_b32_e32 v131, 0xffff0000, v150
	v_lshlrev_b32_e32 v134, 16, v151
	v_and_b32_e32 v135, 0xffff0000, v151
	v_pk_add_f32 v[92:93], v[92:93], v[130:131]
	v_pk_add_f32 v[94:95], v[94:95], v[134:135]
	s_add_u32 s36, s6, 0x10000
	s_addc_u32 s37, s7, 0
	global_store_dwordx4 v133, v[108:111], s[36:37] sc1
	global_store_dwordx4 v133, v[104:107], s[36:37] offset:64 sc1
	global_store_dwordx4 v133, v[100:103], s[36:37] offset:512 sc1
	global_store_dwordx4 v133, v[92:95], s[36:37] offset:576 sc1
	s_waitcnt vmcnt(18)
	v_permlane16_swap_b32_e32 v152, v154
	v_permlane16_swap_b32_e32 v153, v155
	v_permlane16_swap_b32_e32 v156, v158
	v_permlane16_swap_b32_e32 v157, v159
	v_lshlrev_b32_e32 v130, 16, v152
	v_and_b32_e32 v131, 0xffff0000, v152
	v_lshlrev_b32_e32 v134, 16, v153
	v_and_b32_e32 v135, 0xffff0000, v153
	v_pk_add_f32 v[96:97], v[96:97], v[130:131]
	v_pk_add_f32 v[98:99], v[98:99], v[134:135]
	v_lshlrev_b32_e32 v130, 16, v154
	v_and_b32_e32 v131, 0xffff0000, v154
	v_lshlrev_b32_e32 v134, 16, v155
	v_and_b32_e32 v135, 0xffff0000, v155
	v_pk_add_f32 v[88:89], v[88:89], v[130:131]
	v_pk_add_f32 v[90:91], v[90:91], v[134:135]
	v_lshlrev_b32_e32 v130, 16, v156
	v_and_b32_e32 v131, 0xffff0000, v156
	v_lshlrev_b32_e32 v134, 16, v157
	v_and_b32_e32 v135, 0xffff0000, v157
	v_pk_add_f32 v[84:85], v[84:85], v[130:131]
	v_pk_add_f32 v[86:87], v[86:87], v[134:135]
	v_lshlrev_b32_e32 v130, 16, v158
	v_and_b32_e32 v131, 0xffff0000, v158
	v_lshlrev_b32_e32 v134, 16, v159
	v_and_b32_e32 v135, 0xffff0000, v159
	v_pk_add_f32 v[76:77], v[76:77], v[130:131]
	v_pk_add_f32 v[78:79], v[78:79], v[134:135]
	s_add_u32 s36, s6, 0x20000
	s_addc_u32 s37, s7, 0
	global_store_dwordx4 v133, v[96:99], s[36:37] sc1
	global_store_dwordx4 v133, v[88:91], s[36:37] offset:64 sc1
	global_store_dwordx4 v133, v[84:87], s[36:37] offset:512 sc1
	global_store_dwordx4 v133, v[76:79], s[36:37] offset:576 sc1
	s_waitcnt vmcnt(20)
; template <class Epi, class Sched, bool ALIGN_EPI>
; DI void gemm_phase(LAS unsigned char* lds, const Gemm g, const Sched& S, const Epi& E) {
;     ...
;         if (!has_next) break;
;     DI void operator()(const AccT& acc, const Unit& u, int wr, int wc, int fr, int fq, LAS unsigned char*) const {
;     ...
;             for (int m = 0; m < 4; ++m) {
;                 const int row = u.pm * 256 + ai * 128 + wr * 64 + m * 16 + fr;
;                 float* orow = out + (size_t)row * DM + col0;
; #pragma unroll
;                 for (int bj = 0; bj < 2; ++bj)
; #pragma unroll
;                     for (int n = 0; n < 2; ++n) { const u32x2 b = xb[m][bj][n];
;                         const f32x4 xr = {__uint_as_float(b.x << 16), __uint_as_float(b.x & 0xffff0000u), __uint_as_float(b.y << 16), __uint_as_float(b.y & 0xffff0000u)};
;                         *(f32x4*)(orow + bj * 128 + n * 16) = xr + acc[ai][bj][m][n]; }
	v_permlane16_swap_b32_e32 v160, v162
	v_permlane16_swap_b32_e32 v161, v163
	v_permlane16_swap_b32_e32 v182, v184
	v_permlane16_swap_b32_e32 v183, v185
	v_lshlrev_b32_e32 v130, 16, v160
	v_and_b32_e32 v131, 0xffff0000, v160
	v_lshlrev_b32_e32 v134, 16, v161
	v_and_b32_e32 v135, 0xffff0000, v161
	v_pk_add_f32 v[80:81], v[80:81], v[130:131]
	v_pk_add_f32 v[82:83], v[82:83], v[134:135]
	v_lshlrev_b32_e32 v130, 16, v162
	v_and_b32_e32 v131, 0xffff0000, v162
	v_lshlrev_b32_e32 v134, 16, v163
	v_and_b32_e32 v135, 0xffff0000, v163
	v_pk_add_f32 v[72:73], v[72:73], v[130:131]
	v_pk_add_f32 v[74:75], v[74:75], v[134:135]
	v_lshlrev_b32_e32 v130, 16, v182
	v_and_b32_e32 v131, 0xffff0000, v182
	v_lshlrev_b32_e32 v134, 16, v183
	v_and_b32_e32 v135, 0xffff0000, v183
	v_pk_add_f32 v[68:69], v[68:69], v[130:131]
	v_pk_add_f32 v[70:71], v[70:71], v[134:135]
	v_lshlrev_b32_e32 v130, 16, v184
	v_and_b32_e32 v131, 0xffff0000, v184
	v_lshlrev_b32_e32 v134, 16, v185
	v_and_b32_e32 v135, 0xffff0000, v185
	v_pk_add_f32 v[64:65], v[64:65], v[130:131]
	v_pk_add_f32 v[66:67], v[66:67], v[134:135]
	s_add_u32 s36, s6, 0x30000
	s_addc_u32 s37, s7, 0
	global_store_dwordx4 v133, v[80:83], s[36:37] sc1
	global_store_dwordx4 v133, v[72:75], s[36:37] offset:64 sc1
	global_store_dwordx4 v133, v[68:71], s[36:37] offset:512 sc1
	global_store_dwordx4 v133, v[64:67], s[36:37] offset:576 sc1
	s_waitcnt vmcnt(22)
	v_permlane16_swap_b32_e32 v186, v188
	v_permlane16_swap_b32_e32 v187, v189
	v_permlane16_swap_b32_e32 v190, v192
	v_permlane16_swap_b32_e32 v191, v193
	v_lshlrev_b32_e32 v130, 16, v186
	v_and_b32_e32 v131, 0xffff0000, v186
	v_lshlrev_b32_e32 v134, 16, v187
	v_and_b32_e32 v135, 0xffff0000, v187
	v_pk_add_f32 v[60:61], v[60:61], v[130:131]
	v_pk_add_f32 v[62:63], v[62:63], v[134:135]
	v_lshlrev_b32_e32 v130, 16, v188
	v_and_b32_e32 v131, 0xffff0000, v188
	v_lshlrev_b32_e32 v134, 16, v189
	v_and_b32_e32 v135, 0xffff0000, v189
	v_pk_add_f32 v[56:57], v[56:57], v[130:131]
	v_pk_add_f32 v[58:59], v[58:59], v[134:135]
	v_lshlrev_b32_e32 v130, 16, v190
	v_and_b32_e32 v131, 0xffff0000, v190
	v_lshlrev_b32_e32 v134, 16, v191
	v_and_b32_e32 v135, 0xffff0000, v191
	v_pk_add_f32 v[52:53], v[52:53], v[130:131]
	v_pk_add_f32 v[54:55], v[54:55], v[134:135]
	v_lshlrev_b32_e32 v130, 16, v192
	v_and_b32_e32 v131, 0xffff0000, v192
	v_lshlrev_b32_e32 v134, 16, v193
	v_and_b32_e32 v135, 0xffff0000, v193
	v_pk_add_f32 v[44:45], v[44:45], v[130:131]
	v_pk_add_f32 v[46:47], v[46:47], v[134:135]
	s_add_u32 s36, s6, 0x80000
	s_addc_u32 s37, s7, 0
	global_store_dwordx4 v133, v[60:63], s[36:37] sc1
	global_store_dwordx4 v133, v[56:59], s[36:37] offset:64 sc1
	global_store_dwordx4 v133, v[52:55], s[36:37] offset:512 sc1
	global_store_dwordx4 v133, v[44:47], s[36:37] offset:576 sc1
	s_waitcnt vmcnt(24)
	v_permlane16_swap_b32_e32 v194, v196
	v_permlane16_swap_b32_e32 v195, v197
	v_permlane16_swap_b32_e32 v198, v200
	v_permlane16_swap_b32_e32 v199, v201
	v_lshlrev_b32_e32 v130, 16, v194
	v_and_b32_e32 v131, 0xffff0000, v194
	v_lshlrev_b32_e32 v134, 16, v195
	v_and_b32_e32 v135, 0xffff0000, v195
	v_pk_add_f32 v[48:49], v[48:49], v[130:131]
	v_pk_add_f32 v[50:51], v[50:51], v[134:135]
	v_lshlrev_b32_e32 v130, 16, v196
	v_and_b32_e32 v131, 0xffff0000, v196
	v_lshlrev_b32_e32 v134, 16, v197
	v_and_b32_e32 v135, 0xffff0000, v197
	v_pk_add_f32 v[40:41], v[40:41], v[130:131]
	v_pk_add_f32 v[42:43], v[42:43], v[134:135]
	v_lshlrev_b32_e32 v130, 16, v198
	v_and_b32_e32 v131, 0xffff0000, v198
	v_lshlrev_b32_e32 v134, 16, v199
	v_and_b32_e32 v135, 0xffff0000, v199
	v_pk_add_f32 v[36:37], v[36:37], v[130:131]
	v_pk_add_f32 v[38:39], v[38:39], v[134:135]
	v_lshlrev_b32_e32 v130, 16, v200
	v_and_b32_e32 v131, 0xffff0000, v200
	v_lshlrev_b32_e32 v134, 16, v201
	v_and_b32_e32 v135, 0xffff0000, v201
	v_pk_add_f32 v[28:29], v[28:29], v[130:131]
	v_pk_add_f32 v[30:31], v[30:31], v[134:135]
	s_add_u32 s36, s6, 0x90000
	s_addc_u32 s37, s7, 0
	global_store_dwordx4 v133, v[48:51], s[36:37] sc1
	global_store_dwordx4 v133, v[40:43], s[36:37] offset:64 sc1
	global_store_dwordx4 v133, v[36:39], s[36:37] offset:512 sc1
	global_store_dwordx4 v133, v[28:31], s[36:37] offset:576 sc1
	s_waitcnt vmcnt(26)
	v_permlane16_swap_b32_e32 v202, v204
	v_permlane16_swap_b32_e32 v203, v205
	v_permlane16_swap_b32_e32 v206, v208
	v_permlane16_swap_b32_e32 v207, v209
	v_lshlrev_b32_e32 v130, 16, v202
	v_and_b32_e32 v131, 0xffff0000, v202
	v_lshlrev_b32_e32 v134, 16, v203
	v_and_b32_e32 v135, 0xffff0000, v203
	v_pk_add_f32 v[32:33], v[32:33], v[130:131]
	v_pk_add_f32 v[34:35], v[34:35], v[134:135]
	v_lshlrev_b32_e32 v130, 16, v204
	v_and_b32_e32 v131, 0xffff0000, v204
	v_lshlrev_b32_e32 v134, 16, v205
	v_and_b32_e32 v135, 0xffff0000, v205
	v_pk_add_f32 v[24:25], v[24:25], v[130:131]
	v_pk_add_f32 v[26:27], v[26:27], v[134:135]
	v_lshlrev_b32_e32 v130, 16, v206
	v_and_b32_e32 v131, 0xffff0000, v206
	v_lshlrev_b32_e32 v134, 16, v207
	v_and_b32_e32 v135, 0xffff0000, v207
	v_pk_add_f32 v[20:21], v[20:21], v[130:131]
	v_pk_add_f32 v[22:23], v[22:23], v[134:135]
	v_lshlrev_b32_e32 v130, 16, v208
	v_and_b32_e32 v131, 0xffff0000, v208
	v_lshlrev_b32_e32 v134, 16, v209
	v_and_b32_e32 v135, 0xffff0000, v209
	v_pk_add_f32 v[12:13], v[12:13], v[130:131]
	v_pk_add_f32 v[14:15], v[14:15], v[134:135]
	s_add_u32 s36, s6, 0xa0000
	s_addc_u32 s37, s7, 0
	global_store_dwordx4 v133, v[32:35], s[36:37] sc1
	global_store_dwordx4 v133, v[24:27], s[36:37] offset:64 sc1
	global_store_dwordx4 v133, v[20:23], s[36:37] offset:512 sc1
	global_store_dwordx4 v133, v[12:15], s[36:37] offset:576 sc1
	s_waitcnt vmcnt(28)
	v_permlane16_swap_b32_e32 v210, v212
	v_permlane16_swap_b32_e32 v211, v213
	v_permlane16_swap_b32_e32 v214, v216
	v_permlane16_swap_b32_e32 v215, v217
	v_lshlrev_b32_e32 v130, 16, v210
	v_and_b32_e32 v131, 0xffff0000, v210
	v_lshlrev_b32_e32 v134, 16, v211
	v_and_b32_e32 v135, 0xffff0000, v211
	v_pk_add_f32 v[16:17], v[16:17], v[130:131]
	v_pk_add_f32 v[18:19], v[18:19], v[134:135]
	v_lshlrev_b32_e32 v130, 16, v212
	v_and_b32_e32 v131, 0xffff0000, v212
	v_lshlrev_b32_e32 v134, 16, v213
	v_and_b32_e32 v135, 0xffff0000, v213
	v_pk_add_f32 v[8:9], v[8:9], v[130:131]
	v_pk_add_f32 v[10:11], v[10:11], v[134:135]
	v_lshlrev_b32_e32 v130, 16, v214
	v_and_b32_e32 v131, 0xffff0000, v214
	v_lshlrev_b32_e32 v134, 16, v215
	v_and_b32_e32 v135, 0xffff0000, v215
	v_pk_add_f32 v[4:5], v[4:5], v[130:131]
	v_pk_add_f32 v[6:7], v[6:7], v[134:135]
	v_lshlrev_b32_e32 v130, 16, v216
	v_and_b32_e32 v131, 0xffff0000, v216
	v_lshlrev_b32_e32 v134, 16, v217
	v_and_b32_e32 v135, 0xffff0000, v217
	v_pk_add_f32 v[0:1], v[0:1], v[130:131]
	v_pk_add_f32 v[2:3], v[2:3], v[134:135]
	s_add_u32 s36, s6, 0xb0000
	s_addc_u32 s37, s7, 0
	global_store_dwordx4 v133, v[16:19], s[36:37] sc1
	global_store_dwordx4 v133, v[8:11], s[36:37] offset:64 sc1
	global_store_dwordx4 v133, v[4:7], s[36:37] offset:512 sc1
	global_store_dwordx4 v133, v[0:3], s[36:37] offset:576 sc1
	s_mov_b64 s[0:1], -1
	s_cmp_eq_u32 s33, s29
	s_cbranch_scc1 .LBB0_787
; #define PG8_BAR __builtin_amdgcn_s_barrier()
; template <class Epi, class Sched, bool ALIGN_EPI>
; DI void gemm_phase(LAS unsigned char* lds, const Gemm g, const Sched& S, const Epi& E) {
;     ...
;         if (!has_next) break;
; #pragma unroll
;         for (int a = 0; a < 2; ++a)
; #pragma unroll
;             for (int b = 0; b < 2; ++b)
; #pragma unroll
;                 for (int m = 0; m < 4; ++m)
; #pragma unroll
;                     for (int n = 0; n < 2; ++n) acc[a][b][m][n] = (f32x4){0.f, 0.f, 0.f, 0.f};
;         cur = nxt; cA = nA; cB = nB; ++ui;
;         if constexpr (ALIGN_EPI) { if (wr == 1) PG8_BAR; }
	s_and_b64 s[0:1], s[14:15], exec
	s_cselect_b32 s30, s22, s30
	s_cselect_b32 s21, s34, s21
	s_andn2_b64 vcc, exec, s[8:9]
	s_cbranch_vccnz .LBB0_786
	s_barrier
	s_branch .LBB0_786

; #define LAS __attribute__((address_space(3)))
;     DI void operator()(const AccT& acc, const Unit& u, int wr, int wc, int fr, int fq, LAS unsigned char* ldsx) const {
;     ...
;         for (int n = 0; n < 2; ++n) {
;             const int f = u.pn * 128 + wc * 32 + 16 * n + 4 * fq;
; #pragma unroll
;             for (int ai = 0; ai < 2; ++ai) {
;                 f32x4 hm1 = {0.f, 0.f, 0.f, 0.f}, hm2 = {0.f, 0.f, 0.f, 0.f};
;                 const int sb = 4 * (T - GU_PT) + 2 * ai + wr;
;                 if (prompt) {
;                     if (ai | wr) { const int sai = wr ? ai : ai - 1, swr = wr ^ 1; const LAS float* hp = H + ((sai * 2 + swr) * 4 + wc) * 64 + 16 * n + 4 * fq;
;                         hm2 = *(const LAS f32x4*)hp; hm1 = *(const LAS f32x4*)(hp + 32); }
;                 } else { hm2 = *(const f32x4*)(state + (size_t)(sb * 2) * DFF + f); hm1 = *(const f32x4*)(state + (size_t)(sb * 2 + 1) * DFF + f); }
;                 f32x4 p1 = hm1, p2;
; #pragma unroll
;                 for (int j = 0; j < 4; ++j) p2[j] = fr == 1 ? hm1[j] : hm2[j];
; #pragma unroll
;                 for (int m = 0; m < 4; ++m) {
;                     const f32x4 g = acc[ai][0][m][n] * rs[ai][m];
;                     f32x4 gm1, gm2;
; #pragma unroll
;                     for (int j = 0; j < 4; ++j) {
;                         gm1[j] = __int_as_float(__builtin_amdgcn_update_dpp(__float_as_int(p1[j]), __float_as_int(g[j]), 0x111, 0xf, 0xf, false));
;                         gm2[j] = __int_as_float(__builtin_amdgcn_update_dpp(__float_as_int(p2[j]), __float_as_int(g[j]), 0x112, 0xf, 0xf, false));
;                         if (m < 3) {
;                             p1[j] = __int_as_float(__builtin_amdgcn_update_dpp(0, __float_as_int(g[j]), 0x121, 0xf, 0xf, false));
;                             p2[j] = __int_as_float(__builtin_amdgcn_update_dpp(0, __float_as_int(g[j]), 0x122, 0xf, 0xf, false)); }
;                     }
;                     const f32x4 cv = cb[n] + w0[n] * gm2 + w1[n] * gm1 + w2[n] * g;
;                     const f32x4 up = acc[ai][1][m][n] * rs[ai][m];
;                     f32x4 y;
; #pragma unroll
;                     for (int j = 0; j < 4; ++j) y[j] = cv[j] * __builtin_amdgcn_rcpf(1.f + __builtin_amdgcn_exp2f(-cv[j] * LOG2E)) * up[j];
.Lgu_samp0:
	v_add_u32_e32 v213, 16, v172
	s_add_u32 s46, s54, 0xfffea000
	s_addc_u32 s47, s55, -1
	v_mul_lo_u32 v213, v213, s87
	v_cndmask_b32_e64 v160, 0, v124, s[94:95]
	v_cndmask_b32_e64 v124, v124, 0, s[94:95]
	v_cndmask_b32_e64 v164, 0, v132, s[96:97]
	v_cndmask_b32_e64 v132, v132, 0, s[96:97]
	v_cndmask_b32_e64 v161, 0, v125, s[94:95]
	v_cndmask_b32_e64 v125, v125, 0, s[94:95]
	v_cndmask_b32_e64 v165, 0, v133, s[96:97]
	v_cndmask_b32_e64 v133, v133, 0, s[96:97]
	v_cndmask_b32_e64 v162, 0, v126, s[94:95]
	v_cndmask_b32_e64 v126, v126, 0, s[94:95]
	v_cndmask_b32_e64 v166, 0, v134, s[96:97]
	v_cndmask_b32_e64 v134, v134, 0, s[96:97]
	v_cndmask_b32_e64 v163, 0, v127, s[94:95]
	v_cndmask_b32_e64 v127, v127, 0, s[94:95]
	v_cndmask_b32_e64 v167, 0, v135, s[96:97]
	v_cndmask_b32_e64 v135, v135, 0, s[96:97]
	v_add_lshl_u32 v213, v213, v216, 1
	v_and_b32_e32 v186, 16, v226
	v_lshrrev_b32_e32 v187, 1, v186
	v_add3_u32 v213, v213, v186, v187
	v_pk_mul_f32 v[156:157], v[156:157], v[214:215] op_sel_hi:[1,0]
	v_pk_mul_f32 v[158:159], v[158:159], v[214:215] op_sel_hi:[1,0]
	v_pk_mul_f32 v[152:153], v[152:153], v[214:215] op_sel_hi:[1,0]
	v_pk_mul_f32 v[154:155], v[154:155], v[214:215] op_sel_hi:[1,0]
	v_pk_fma_f32 v[218:219], v[128:129], v[156:157], v[136:137]
	v_pk_fma_f32 v[220:221], v[130:131], v[158:159], v[138:139]
	v_fmac_f32_dpp v218, v156, v124 row_ror:1 row_mask:0xf bank_mask:0xf
	v_fmac_f32_dpp v219, v157, v125 row_ror:1 row_mask:0xf bank_mask:0xf
	v_fmac_f32_dpp v220, v158, v126 row_ror:1 row_mask:0xf bank_mask:0xf
	v_fmac_f32_dpp v221, v159, v127 row_ror:1 row_mask:0xf bank_mask:0xf
	v_fmac_f32_dpp v218, v156, v132 row_ror:2 row_mask:0xf bank_mask:0xf
	v_fmac_f32_dpp v219, v157, v133 row_ror:2 row_mask:0xf bank_mask:0xf
	v_fmac_f32_dpp v220, v158, v134 row_ror:2 row_mask:0xf bank_mask:0xf
	v_fmac_f32_dpp v221, v159, v135 row_ror:2 row_mask:0xf bank_mask:0xf
	s_waitcnt lgkmcnt(0)
	v_fmac_f32_e32 v218, v248, v160
	v_fmac_f32_e32 v219, v249, v161
	v_fmac_f32_e32 v220, v250, v162
	v_fmac_f32_e32 v221, v251, v163
	v_fmac_f32_dpp v218, v248, v164 row_ror:14 row_mask:0xf bank_mask:0xf
	v_fmac_f32_dpp v219, v249, v165 row_ror:14 row_mask:0xf bank_mask:0xf
	v_fmac_f32_dpp v220, v250, v166 row_ror:14 row_mask:0xf bank_mask:0xf
	v_fmac_f32_dpp v221, v251, v167 row_ror:14 row_mask:0xf bank_mask:0xf
	v_pk_mul_f32 v[204:205], v[218:219], v[184:185] op_sel:[0,1] op_sel_hi:[1,1]
	v_pk_mul_f32 v[148:149], v[148:149], v[210:211] op_sel_hi:[1,0]
	v_pk_mul_f32 v[206:207], v[220:221], v[184:185] op_sel:[0,1] op_sel_hi:[1,1]
	v_pk_mul_f32 v[150:151], v[150:151], v[210:211] op_sel_hi:[1,0]
	v_exp_f32_e32 v204, v204
	v_pk_mul_f32 v[144:145], v[144:145], v[210:211] op_sel_hi:[1,0]
	v_exp_f32_e32 v205, v205
	v_pk_mul_f32 v[146:147], v[146:147], v[210:211] op_sel_hi:[1,0]
	v_exp_f32_e32 v206, v206
	v_pk_fma_f32 v[222:223], v[128:129], v[148:149], v[136:137]
	v_exp_f32_e32 v207, v207
	v_pk_fma_f32 v[224:225], v[130:131], v[150:151], v[138:139]
	v_pk_add_f32 v[204:205], v[204:205], 1.0 op_sel_hi:[1,0]
	v_fmac_f32_dpp v222, v148, v124 row_ror:1 row_mask:0xf bank_mask:0xf
	v_pk_add_f32 v[206:207], v[206:207], 1.0 op_sel_hi:[1,0]
	v_fmac_f32_dpp v223, v149, v125 row_ror:1 row_mask:0xf bank_mask:0xf
	v_rcp_f32_e32 v204, v204
	v_fmac_f32_dpp v224, v150, v126 row_ror:1 row_mask:0xf bank_mask:0xf
	v_rcp_f32_e32 v205, v205
	v_fmac_f32_dpp v225, v151, v127 row_ror:1 row_mask:0xf bank_mask:0xf
	v_rcp_f32_e32 v206, v206
	v_fmac_f32_dpp v222, v148, v132 row_ror:2 row_mask:0xf bank_mask:0xf
	v_rcp_f32_e32 v207, v207
	v_fmac_f32_dpp v223, v149, v133 row_ror:2 row_mask:0xf bank_mask:0xf
	v_pk_mul_f32 v[218:219], v[218:219], v[204:205]
	v_fmac_f32_dpp v224, v150, v134 row_ror:2 row_mask:0xf bank_mask:0xf
	v_pk_mul_f32 v[220:221], v[220:221], v[206:207]
	v_fmac_f32_dpp v225, v151, v135 row_ror:2 row_mask:0xf bank_mask:0xf
	v_pk_mul_f32 v[152:153], v[152:153], v[218:219]
	v_fmac_f32_dpp v222, v156, v160 row_ror:1 row_mask:0xf bank_mask:0xf
	v_pk_mul_f32 v[154:155], v[154:155], v[220:221]
	v_fmac_f32_dpp v223, v157, v161 row_ror:1 row_mask:0xf bank_mask:0xf
	v_cvt_pk_bf16_f32 v152, v152, v153
	v_fmac_f32_dpp v224, v158, v162 row_ror:1 row_mask:0xf bank_mask:0xf
	v_cvt_pk_bf16_f32 v153, v154, v155
	v_fmac_f32_dpp v225, v159, v163 row_ror:1 row_mask:0xf bank_mask:0xf
	v_fmac_f32_dpp v222, v156, v164 row_ror:2 row_mask:0xf bank_mask:0xf
	v_fmac_f32_dpp v223, v157, v165 row_ror:2 row_mask:0xf bank_mask:0xf
	v_fmac_f32_dpp v224, v158, v166 row_ror:2 row_mask:0xf bank_mask:0xf
	v_fmac_f32_dpp v225, v159, v167 row_ror:2 row_mask:0xf bank_mask:0xf
	v_pk_mul_f32 v[204:205], v[222:223], v[184:185] op_sel:[0,1] op_sel_hi:[1,1]
	v_pk_mul_f32 v[140:141], v[140:141], v[208:209] op_sel_hi:[1,0]
	v_pk_mul_f32 v[206:207], v[224:225], v[184:185] op_sel:[0,1] op_sel_hi:[1,1]
	v_pk_mul_f32 v[142:143], v[142:143], v[208:209] op_sel_hi:[1,0]
	v_exp_f32_e32 v204, v204
	v_pk_mul_f32 v[120:121], v[120:121], v[208:209] op_sel_hi:[1,0]
	v_exp_f32_e32 v205, v205
	v_pk_mul_f32 v[122:123], v[122:123], v[208:209] op_sel_hi:[1,0]
	v_exp_f32_e32 v206, v206
	v_pk_fma_f32 v[218:219], v[128:129], v[140:141], v[136:137]
	v_exp_f32_e32 v207, v207
	v_pk_fma_f32 v[220:221], v[130:131], v[142:143], v[138:139]
	v_pk_add_f32 v[204:205], v[204:205], 1.0 op_sel_hi:[1,0]
	v_fmac_f32_dpp v218, v140, v124 row_ror:1 row_mask:0xf bank_mask:0xf
	v_pk_add_f32 v[206:207], v[206:207], 1.0 op_sel_hi:[1,0]
	v_fmac_f32_dpp v219, v141, v125 row_ror:1 row_mask:0xf bank_mask:0xf
	v_rcp_f32_e32 v204, v204
	v_fmac_f32_dpp v220, v142, v126 row_ror:1 row_mask:0xf bank_mask:0xf
	v_rcp_f32_e32 v205, v205
	v_fmac_f32_dpp v221, v143, v127 row_ror:1 row_mask:0xf bank_mask:0xf
;     DI void operator()(const AccT& acc, const Unit& u, int wr, int wc, int fr, int fq, LAS unsigned char* ldsx) const {
;     ...
; #pragma unroll
;                 for (int m = 0; m < 4; ++m) {
;                     const f32x4 g = acc[ai][0][m][n] * rs[ai][m];
;                     f32x4 gm1, gm2;
; #pragma unroll
;                     for (int j = 0; j < 4; ++j) {
;                         gm1[j] = __int_as_float(__builtin_amdgcn_update_dpp(__float_as_int(p1[j]), __float_as_int(g[j]), 0x111, 0xf, 0xf, false));
;                         gm2[j] = __int_as_float(__builtin_amdgcn_update_dpp(__float_as_int(p2[j]), __float_as_int(g[j]), 0x112, 0xf, 0xf, false));
;                         if (m < 3) {
;                             p1[j] = __int_as_float(__builtin_amdgcn_update_dpp(0, __float_as_int(g[j]), 0x121, 0xf, 0xf, false));
;                             p2[j] = __int_as_float(__builtin_amdgcn_update_dpp(0, __float_as_int(g[j]), 0x122, 0xf, 0xf, false)); }
;                     }
;                     const f32x4 cv = cb[n] + w0[n] * gm2 + w1[n] * gm1 + w2[n] * g;
;                     const f32x4 up = acc[ai][1][m][n] * rs[ai][m];
;                     f32x4 y;
; #pragma unroll
;                     for (int j = 0; j < 4; ++j) y[j] = cv[j] * __builtin_amdgcn_rcpf(1.f + __builtin_amdgcn_exp2f(-cv[j] * LOG2E)) * up[j];
	v_rcp_f32_e32 v206, v206
	v_fmac_f32_dpp v218, v140, v132 row_ror:2 row_mask:0xf bank_mask:0xf
	v_rcp_f32_e32 v207, v207
	v_fmac_f32_dpp v219, v141, v133 row_ror:2 row_mask:0xf bank_mask:0xf
	v_pk_mul_f32 v[222:223], v[222:223], v[204:205]
	v_fmac_f32_dpp v220, v142, v134 row_ror:2 row_mask:0xf bank_mask:0xf
	v_pk_mul_f32 v[224:225], v[224:225], v[206:207]
	v_fmac_f32_dpp v221, v143, v135 row_ror:2 row_mask:0xf bank_mask:0xf
	v_pk_mul_f32 v[144:145], v[144:145], v[222:223]
	v_fmac_f32_dpp v218, v148, v160 row_ror:1 row_mask:0xf bank_mask:0xf
	v_pk_mul_f32 v[146:147], v[146:147], v[224:225]
	v_fmac_f32_dpp v219, v149, v161 row_ror:1 row_mask:0xf bank_mask:0xf
	v_cvt_pk_bf16_f32 v144, v144, v145
	v_fmac_f32_dpp v220, v150, v162 row_ror:1 row_mask:0xf bank_mask:0xf
	v_cvt_pk_bf16_f32 v145, v146, v147
	v_fmac_f32_dpp v221, v151, v163 row_ror:1 row_mask:0xf bank_mask:0xf
	v_fmac_f32_dpp v218, v148, v164 row_ror:2 row_mask:0xf bank_mask:0xf
	v_fmac_f32_dpp v219, v149, v165 row_ror:2 row_mask:0xf bank_mask:0xf
	v_fmac_f32_dpp v220, v150, v166 row_ror:2 row_mask:0xf bank_mask:0xf
	v_fmac_f32_dpp v221, v151, v167 row_ror:2 row_mask:0xf bank_mask:0xf
	v_pk_mul_f32 v[204:205], v[218:219], v[184:185] op_sel:[0,1] op_sel_hi:[1,1]
	v_pk_mul_f32 v[116:117], v[116:117], v[202:203] op_sel_hi:[1,0]
	v_pk_mul_f32 v[206:207], v[220:221], v[184:185] op_sel:[0,1] op_sel_hi:[1,1]
	v_pk_mul_f32 v[118:119], v[118:119], v[202:203] op_sel_hi:[1,0]
	v_exp_f32_e32 v204, v204
	v_pk_mul_f32 v[112:113], v[112:113], v[202:203] op_sel_hi:[1,0]
	v_exp_f32_e32 v205, v205
	v_pk_mul_f32 v[114:115], v[114:115], v[202:203] op_sel_hi:[1,0]
	v_exp_f32_e32 v206, v206
	v_pk_fma_f32 v[222:223], v[128:129], v[116:117], v[136:137]
	v_exp_f32_e32 v207, v207
	v_pk_fma_f32 v[224:225], v[130:131], v[118:119], v[138:139]
	v_pk_add_f32 v[204:205], v[204:205], 1.0 op_sel_hi:[1,0]
	v_fmac_f32_dpp v222, v116, v124 row_ror:1 row_mask:0xf bank_mask:0xf
	v_pk_add_f32 v[206:207], v[206:207], 1.0 op_sel_hi:[1,0]
	v_fmac_f32_dpp v223, v117, v125 row_ror:1 row_mask:0xf bank_mask:0xf
	v_rcp_f32_e32 v204, v204
	v_fmac_f32_dpp v224, v118, v126 row_ror:1 row_mask:0xf bank_mask:0xf
	v_rcp_f32_e32 v205, v205
	v_fmac_f32_dpp v225, v119, v127 row_ror:1 row_mask:0xf bank_mask:0xf
	v_rcp_f32_e32 v206, v206
	v_fmac_f32_dpp v222, v116, v132 row_ror:2 row_mask:0xf bank_mask:0xf
	v_rcp_f32_e32 v207, v207
	v_fmac_f32_dpp v223, v117, v133 row_ror:2 row_mask:0xf bank_mask:0xf
	v_pk_mul_f32 v[218:219], v[218:219], v[204:205]
	v_fmac_f32_dpp v224, v118, v134 row_ror:2 row_mask:0xf bank_mask:0xf
	v_pk_mul_f32 v[220:221], v[220:221], v[206:207]
	v_fmac_f32_dpp v225, v119, v135 row_ror:2 row_mask:0xf bank_mask:0xf
	v_pk_mul_f32 v[120:121], v[120:121], v[218:219]
	v_fmac_f32_dpp v222, v140, v160 row_ror:1 row_mask:0xf bank_mask:0xf
	v_pk_mul_f32 v[122:123], v[122:123], v[220:221]
	v_fmac_f32_dpp v223, v141, v161 row_ror:1 row_mask:0xf bank_mask:0xf
	v_cvt_pk_bf16_f32 v120, v120, v121
	v_fmac_f32_dpp v224, v142, v162 row_ror:1 row_mask:0xf bank_mask:0xf
	v_cvt_pk_bf16_f32 v121, v122, v123
	v_fmac_f32_dpp v225, v143, v163 row_ror:1 row_mask:0xf bank_mask:0xf
	v_fmac_f32_dpp v222, v140, v164 row_ror:2 row_mask:0xf bank_mask:0xf
	v_fmac_f32_dpp v223, v141, v165 row_ror:2 row_mask:0xf bank_mask:0xf
	v_fmac_f32_dpp v224, v142, v166 row_ror:2 row_mask:0xf bank_mask:0xf
	v_fmac_f32_dpp v225, v143, v167 row_ror:2 row_mask:0xf bank_mask:0xf
	v_pk_mul_f32 v[204:205], v[222:223], v[184:185] op_sel:[0,1] op_sel_hi:[1,1]
	v_pk_mul_f32 v[108:109], v[108:109], v[200:201] op_sel_hi:[1,0]
	v_pk_mul_f32 v[206:207], v[224:225], v[184:185] op_sel:[0,1] op_sel_hi:[1,1]
	v_pk_mul_f32 v[110:111], v[110:111], v[200:201] op_sel_hi:[1,0]
	v_exp_f32_e32 v204, v204
	v_pk_mul_f32 v[104:105], v[104:105], v[200:201] op_sel_hi:[1,0]
	v_exp_f32_e32 v205, v205
	v_pk_mul_f32 v[106:107], v[106:107], v[200:201] op_sel_hi:[1,0]
	v_exp_f32_e32 v206, v206
	v_pk_fma_f32 v[218:219], v[128:129], v[108:109], v[136:137]
	v_exp_f32_e32 v207, v207
	v_pk_fma_f32 v[220:221], v[130:131], v[110:111], v[138:139]
	v_pk_add_f32 v[204:205], v[204:205], 1.0 op_sel_hi:[1,0]
	v_fmac_f32_dpp v218, v108, v124 row_ror:1 row_mask:0xf bank_mask:0xf
	v_pk_add_f32 v[206:207], v[206:207], 1.0 op_sel_hi:[1,0]
	v_fmac_f32_dpp v219, v109, v125 row_ror:1 row_mask:0xf bank_mask:0xf
	v_rcp_f32_e32 v204, v204
	v_fmac_f32_dpp v220, v110, v126 row_ror:1 row_mask:0xf bank_mask:0xf
	v_rcp_f32_e32 v205, v205
	v_fmac_f32_dpp v221, v111, v127 row_ror:1 row_mask:0xf bank_mask:0xf
	v_rcp_f32_e32 v206, v206
	v_fmac_f32_dpp v218, v108, v132 row_ror:2 row_mask:0xf bank_mask:0xf
	v_rcp_f32_e32 v207, v207
	v_fmac_f32_dpp v219, v109, v133 row_ror:2 row_mask:0xf bank_mask:0xf
	v_pk_mul_f32 v[222:223], v[222:223], v[204:205]
	v_fmac_f32_dpp v220, v110, v134 row_ror:2 row_mask:0xf bank_mask:0xf
	v_pk_mul_f32 v[224:225], v[224:225], v[206:207]
	v_fmac_f32_dpp v221, v111, v135 row_ror:2 row_mask:0xf bank_mask:0xf
	v_pk_mul_f32 v[112:113], v[112:113], v[222:223]
	v_fmac_f32_dpp v218, v248, v160 row_ror:12 row_mask:0xf bank_mask:0xf
	v_pk_mul_f32 v[114:115], v[114:115], v[224:225]
	v_fmac_f32_dpp v219, v249, v161 row_ror:12 row_mask:0xf bank_mask:0xf
	v_cvt_pk_bf16_f32 v112, v112, v113
	v_fmac_f32_dpp v220, v250, v162 row_ror:12 row_mask:0xf bank_mask:0xf
	v_cvt_pk_bf16_f32 v113, v114, v115
	v_fmac_f32_dpp v221, v251, v163 row_ror:12 row_mask:0xf bank_mask:0xf
	v_fmac_f32_dpp v218, v248, v164 row_ror:10 row_mask:0xf bank_mask:0xf
	v_fmac_f32_dpp v219, v249, v165 row_ror:10 row_mask:0xf bank_mask:0xf
	v_fmac_f32_dpp v220, v250, v166 row_ror:10 row_mask:0xf bank_mask:0xf
	v_fmac_f32_dpp v221, v251, v167 row_ror:10 row_mask:0xf bank_mask:0xf
;     DI void operator()(const AccT& acc, const Unit& u, int wr, int wc, int fr, int fq, LAS unsigned char* ldsx) const {
;     ...
; #pragma unroll
;                 for (int m = 0; m < 4; ++m) {
;                     const f32x4 g = acc[ai][0][m][n] * rs[ai][m];
;                     f32x4 gm1, gm2;
; #pragma unroll
;                     for (int j = 0; j < 4; ++j) {
;                         gm1[j] = __int_as_float(__builtin_amdgcn_update_dpp(__float_as_int(p1[j]), __float_as_int(g[j]), 0x111, 0xf, 0xf, false));
;                         gm2[j] = __int_as_float(__builtin_amdgcn_update_dpp(__float_as_int(p2[j]), __float_as_int(g[j]), 0x112, 0xf, 0xf, false));
;                         if (m < 3) {
;                             p1[j] = __int_as_float(__builtin_amdgcn_update_dpp(0, __float_as_int(g[j]), 0x121, 0xf, 0xf, false));
;                             p2[j] = __int_as_float(__builtin_amdgcn_update_dpp(0, __float_as_int(g[j]), 0x122, 0xf, 0xf, false)); }
;                     }
;                     const f32x4 cv = cb[n] + w0[n] * gm2 + w1[n] * gm1 + w2[n] * g;
;                     const f32x4 up = acc[ai][1][m][n] * rs[ai][m];
;                     f32x4 y;
; #pragma unroll
;                     for (int j = 0; j < 4; ++j) y[j] = cv[j] * __builtin_amdgcn_rcpf(1.f + __builtin_amdgcn_exp2f(-cv[j] * LOG2E)) * up[j];
	v_pk_mul_f32 v[204:205], v[218:219], v[184:185] op_sel:[0,1] op_sel_hi:[1,1]
	v_pk_mul_f32 v[100:101], v[100:101], v[192:193] op_sel_hi:[1,0]
	v_pk_mul_f32 v[206:207], v[220:221], v[184:185] op_sel:[0,1] op_sel_hi:[1,1]
	v_pk_mul_f32 v[102:103], v[102:103], v[192:193] op_sel_hi:[1,0]
	v_exp_f32_e32 v204, v204
	v_pk_mul_f32 v[96:97], v[96:97], v[192:193] op_sel_hi:[1,0]
	v_exp_f32_e32 v205, v205
	v_pk_mul_f32 v[98:99], v[98:99], v[192:193] op_sel_hi:[1,0]
	v_exp_f32_e32 v206, v206
	v_pk_fma_f32 v[222:223], v[128:129], v[100:101], v[136:137]
	v_exp_f32_e32 v207, v207
	v_pk_fma_f32 v[224:225], v[130:131], v[102:103], v[138:139]
	v_pk_add_f32 v[204:205], v[204:205], 1.0 op_sel_hi:[1,0]
	v_fmac_f32_dpp v222, v100, v124 row_ror:1 row_mask:0xf bank_mask:0xf
	v_pk_add_f32 v[206:207], v[206:207], 1.0 op_sel_hi:[1,0]
	v_fmac_f32_dpp v223, v101, v125 row_ror:1 row_mask:0xf bank_mask:0xf
	v_rcp_f32_e32 v204, v204
	v_fmac_f32_dpp v224, v102, v126 row_ror:1 row_mask:0xf bank_mask:0xf
	v_rcp_f32_e32 v205, v205
	v_fmac_f32_dpp v225, v103, v127 row_ror:1 row_mask:0xf bank_mask:0xf
	v_rcp_f32_e32 v206, v206
	v_fmac_f32_dpp v222, v100, v132 row_ror:2 row_mask:0xf bank_mask:0xf
	v_rcp_f32_e32 v207, v207
	v_fmac_f32_dpp v223, v101, v133 row_ror:2 row_mask:0xf bank_mask:0xf
	v_pk_mul_f32 v[218:219], v[218:219], v[204:205]
	v_fmac_f32_dpp v224, v102, v134 row_ror:2 row_mask:0xf bank_mask:0xf
	v_pk_mul_f32 v[220:221], v[220:221], v[206:207]
	v_fmac_f32_dpp v225, v103, v135 row_ror:2 row_mask:0xf bank_mask:0xf
	v_pk_mul_f32 v[104:105], v[104:105], v[218:219]
	v_fmac_f32_dpp v222, v108, v160 row_ror:1 row_mask:0xf bank_mask:0xf
	v_pk_mul_f32 v[106:107], v[106:107], v[220:221]
	v_fmac_f32_dpp v223, v109, v161 row_ror:1 row_mask:0xf bank_mask:0xf
	v_cvt_pk_bf16_f32 v104, v104, v105
	v_fmac_f32_dpp v224, v110, v162 row_ror:1 row_mask:0xf bank_mask:0xf
	v_cvt_pk_bf16_f32 v105, v106, v107
	v_fmac_f32_dpp v225, v111, v163 row_ror:1 row_mask:0xf bank_mask:0xf
	v_fmac_f32_dpp v222, v108, v164 row_ror:2 row_mask:0xf bank_mask:0xf
	v_fmac_f32_dpp v223, v109, v165 row_ror:2 row_mask:0xf bank_mask:0xf
	v_fmac_f32_dpp v224, v110, v166 row_ror:2 row_mask:0xf bank_mask:0xf
	v_fmac_f32_dpp v225, v111, v167 row_ror:2 row_mask:0xf bank_mask:0xf
	v_pk_mul_f32 v[204:205], v[222:223], v[184:185] op_sel:[0,1] op_sel_hi:[1,1]
	v_pk_mul_f32 v[92:93], v[92:93], v[190:191] op_sel_hi:[1,0]
	v_pk_mul_f32 v[206:207], v[224:225], v[184:185] op_sel:[0,1] op_sel_hi:[1,1]
	v_pk_mul_f32 v[94:95], v[94:95], v[190:191] op_sel_hi:[1,0]
	v_exp_f32_e32 v204, v204
	v_pk_mul_f32 v[88:89], v[88:89], v[190:191] op_sel_hi:[1,0]
	v_exp_f32_e32 v205, v205
	v_pk_mul_f32 v[90:91], v[90:91], v[190:191] op_sel_hi:[1,0]
	v_exp_f32_e32 v206, v206
	v_pk_fma_f32 v[218:219], v[128:129], v[92:93], v[136:137]
	v_exp_f32_e32 v207, v207
	v_pk_fma_f32 v[220:221], v[130:131], v[94:95], v[138:139]
	v_pk_add_f32 v[204:205], v[204:205], 1.0 op_sel_hi:[1,0]
	v_fmac_f32_dpp v218, v92, v124 row_ror:1 row_mask:0xf bank_mask:0xf
	v_pk_add_f32 v[206:207], v[206:207], 1.0 op_sel_hi:[1,0]
	v_fmac_f32_dpp v219, v93, v125 row_ror:1 row_mask:0xf bank_mask:0xf
	v_rcp_f32_e32 v204, v204
	v_fmac_f32_dpp v220, v94, v126 row_ror:1 row_mask:0xf bank_mask:0xf
	v_rcp_f32_e32 v205, v205
	v_fmac_f32_dpp v221, v95, v127 row_ror:1 row_mask:0xf bank_mask:0xf
	v_rcp_f32_e32 v206, v206
	v_fmac_f32_dpp v218, v92, v132 row_ror:2 row_mask:0xf bank_mask:0xf
	v_rcp_f32_e32 v207, v207
	v_fmac_f32_dpp v219, v93, v133 row_ror:2 row_mask:0xf bank_mask:0xf
	v_pk_mul_f32 v[222:223], v[222:223], v[204:205]
	v_fmac_f32_dpp v220, v94, v134 row_ror:2 row_mask:0xf bank_mask:0xf
	v_pk_mul_f32 v[224:225], v[224:225], v[206:207]
	v_fmac_f32_dpp v221, v95, v135 row_ror:2 row_mask:0xf bank_mask:0xf
	v_pk_mul_f32 v[96:97], v[96:97], v[222:223]
	v_fmac_f32_dpp v218, v100, v160 row_ror:1 row_mask:0xf bank_mask:0xf
	v_pk_mul_f32 v[98:99], v[98:99], v[224:225]
	v_fmac_f32_dpp v219, v101, v161 row_ror:1 row_mask:0xf bank_mask:0xf
	v_cvt_pk_bf16_f32 v96, v96, v97
	v_fmac_f32_dpp v220, v102, v162 row_ror:1 row_mask:0xf bank_mask:0xf
	v_cvt_pk_bf16_f32 v97, v98, v99
	v_fmac_f32_dpp v221, v103, v163 row_ror:1 row_mask:0xf bank_mask:0xf
	v_fmac_f32_dpp v218, v100, v164 row_ror:2 row_mask:0xf bank_mask:0xf
	v_fmac_f32_dpp v219, v101, v165 row_ror:2 row_mask:0xf bank_mask:0xf
	v_fmac_f32_dpp v220, v102, v166 row_ror:2 row_mask:0xf bank_mask:0xf
	v_fmac_f32_dpp v221, v103, v167 row_ror:2 row_mask:0xf bank_mask:0xf
	v_pk_mul_f32 v[204:205], v[218:219], v[184:185] op_sel:[0,1] op_sel_hi:[1,1]
	v_pk_mul_f32 v[84:85], v[84:85], v[184:185] op_sel_hi:[1,0]
	v_pk_mul_f32 v[206:207], v[220:221], v[184:185] op_sel:[0,1] op_sel_hi:[1,1]
	v_pk_mul_f32 v[86:87], v[86:87], v[184:185] op_sel_hi:[1,0]
	v_exp_f32_e32 v204, v204
	v_pk_mul_f32 v[80:81], v[80:81], v[184:185] op_sel_hi:[1,0]
	v_exp_f32_e32 v205, v205
	v_pk_mul_f32 v[82:83], v[82:83], v[184:185] op_sel_hi:[1,0]
	v_exp_f32_e32 v206, v206
	v_pk_fma_f32 v[222:223], v[128:129], v[84:85], v[136:137]
	v_exp_f32_e32 v207, v207
	v_pk_fma_f32 v[224:225], v[130:131], v[86:87], v[138:139]
	v_pk_add_f32 v[204:205], v[204:205], 1.0 op_sel_hi:[1,0]
	v_fmac_f32_dpp v222, v84, v124 row_ror:1 row_mask:0xf bank_mask:0xf
	v_pk_add_f32 v[206:207], v[206:207], 1.0 op_sel_hi:[1,0]
	v_fmac_f32_dpp v223, v85, v125 row_ror:1 row_mask:0xf bank_mask:0xf
	v_rcp_f32_e32 v204, v204
	v_fmac_f32_dpp v224, v86, v126 row_ror:1 row_mask:0xf bank_mask:0xf
	v_rcp_f32_e32 v205, v205
	v_fmac_f32_dpp v225, v87, v127 row_ror:1 row_mask:0xf bank_mask:0xf
	v_rcp_f32_e32 v206, v206
	v_fmac_f32_dpp v222, v84, v132 row_ror:2 row_mask:0xf bank_mask:0xf
	v_rcp_f32_e32 v207, v207
;     DI void operator()(const AccT& acc, const Unit& u, int wr, int wc, int fr, int fq, LAS unsigned char* ldsx) const {
;     ...
; #pragma unroll
;                 for (int m = 0; m < 4; ++m) {
;                     const f32x4 g = acc[ai][0][m][n] * rs[ai][m];
;                     f32x4 gm1, gm2;
; #pragma unroll
;                     for (int j = 0; j < 4; ++j) {
;                         gm1[j] = __int_as_float(__builtin_amdgcn_update_dpp(__float_as_int(p1[j]), __float_as_int(g[j]), 0x111, 0xf, 0xf, false));
;                         gm2[j] = __int_as_float(__builtin_amdgcn_update_dpp(__float_as_int(p2[j]), __float_as_int(g[j]), 0x112, 0xf, 0xf, false));
;                         if (m < 3) {
;                             p1[j] = __int_as_float(__builtin_amdgcn_update_dpp(0, __float_as_int(g[j]), 0x121, 0xf, 0xf, false));
;                             p2[j] = __int_as_float(__builtin_amdgcn_update_dpp(0, __float_as_int(g[j]), 0x122, 0xf, 0xf, false)); }
;                     }
;                     const f32x4 cv = cb[n] + w0[n] * gm2 + w1[n] * gm1 + w2[n] * g;
;                     const f32x4 up = acc[ai][1][m][n] * rs[ai][m];
;                     f32x4 y;
; #pragma unroll
;                     for (int j = 0; j < 4; ++j) y[j] = cv[j] * __builtin_amdgcn_rcpf(1.f + __builtin_amdgcn_exp2f(-cv[j] * LOG2E)) * up[j];
	v_fmac_f32_dpp v223, v85, v133 row_ror:2 row_mask:0xf bank_mask:0xf
	v_pk_mul_f32 v[218:219], v[218:219], v[204:205]
	v_fmac_f32_dpp v224, v86, v134 row_ror:2 row_mask:0xf bank_mask:0xf
	v_pk_mul_f32 v[220:221], v[220:221], v[206:207]
	v_fmac_f32_dpp v225, v87, v135 row_ror:2 row_mask:0xf bank_mask:0xf
	v_pk_mul_f32 v[88:89], v[88:89], v[218:219]
	v_fmac_f32_dpp v222, v92, v160 row_ror:1 row_mask:0xf bank_mask:0xf
	v_pk_mul_f32 v[90:91], v[90:91], v[220:221]
	v_fmac_f32_dpp v223, v93, v161 row_ror:1 row_mask:0xf bank_mask:0xf
	v_cvt_pk_bf16_f32 v88, v88, v89
	v_fmac_f32_dpp v224, v94, v162 row_ror:1 row_mask:0xf bank_mask:0xf
	v_cvt_pk_bf16_f32 v89, v90, v91
	v_fmac_f32_dpp v225, v95, v163 row_ror:1 row_mask:0xf bank_mask:0xf
	v_fmac_f32_dpp v222, v92, v164 row_ror:2 row_mask:0xf bank_mask:0xf
	v_fmac_f32_dpp v223, v93, v165 row_ror:2 row_mask:0xf bank_mask:0xf
	v_fmac_f32_dpp v224, v94, v166 row_ror:2 row_mask:0xf bank_mask:0xf
	v_fmac_f32_dpp v225, v95, v167 row_ror:2 row_mask:0xf bank_mask:0xf
	v_cndmask_b32_e64 v160, 0, v48, s[94:95]
	v_cndmask_b32_e64 v48, v48, 0, s[94:95]
	v_cndmask_b32_e64 v164, 0, v44, s[96:97]
	v_cndmask_b32_e64 v44, v44, 0, s[96:97]
	v_cndmask_b32_e64 v161, 0, v49, s[94:95]
	v_cndmask_b32_e64 v49, v49, 0, s[94:95]
	v_cndmask_b32_e64 v165, 0, v45, s[96:97]
	v_cndmask_b32_e64 v45, v45, 0, s[96:97]
	v_cndmask_b32_e64 v162, 0, v50, s[94:95]
	v_cndmask_b32_e64 v50, v50, 0, s[94:95]
	v_cndmask_b32_e64 v166, 0, v46, s[96:97]
	v_cndmask_b32_e64 v46, v46, 0, s[96:97]
	v_cndmask_b32_e64 v163, 0, v51, s[94:95]
	v_cndmask_b32_e64 v51, v51, 0, s[94:95]
	v_cndmask_b32_e64 v167, 0, v47, s[96:97]
	v_cndmask_b32_e64 v47, v47, 0, s[96:97]
	v_pk_mul_f32 v[204:205], v[222:223], v[184:185] op_sel:[0,1] op_sel_hi:[1,1]
	v_pk_mul_f32 v[76:77], v[76:77], v[214:215] op_sel_hi:[1,0]
	v_pk_mul_f32 v[206:207], v[224:225], v[184:185] op_sel:[0,1] op_sel_hi:[1,1]
	v_pk_mul_f32 v[78:79], v[78:79], v[214:215] op_sel_hi:[1,0]
	v_exp_f32_e32 v204, v204
	v_pk_mul_f32 v[72:73], v[72:73], v[214:215] op_sel_hi:[1,0]
	v_exp_f32_e32 v205, v205
	v_pk_mul_f32 v[74:75], v[74:75], v[214:215] op_sel_hi:[1,0]
	v_exp_f32_e32 v206, v206
	v_pk_fma_f32 v[218:219], v[52:53], v[76:77], v[56:57]
	v_exp_f32_e32 v207, v207
	v_pk_fma_f32 v[220:221], v[54:55], v[78:79], v[58:59]
	v_pk_add_f32 v[204:205], v[204:205], 1.0 op_sel_hi:[1,0]
	v_fmac_f32_dpp v218, v76, v48 row_ror:1 row_mask:0xf bank_mask:0xf
	v_pk_add_f32 v[206:207], v[206:207], 1.0 op_sel_hi:[1,0]
	v_fmac_f32_dpp v219, v77, v49 row_ror:1 row_mask:0xf bank_mask:0xf
	v_rcp_f32_e32 v204, v204
	v_fmac_f32_dpp v220, v78, v50 row_ror:1 row_mask:0xf bank_mask:0xf
	v_rcp_f32_e32 v205, v205
	v_fmac_f32_dpp v221, v79, v51 row_ror:1 row_mask:0xf bank_mask:0xf
	v_rcp_f32_e32 v206, v206
	v_fmac_f32_dpp v218, v76, v44 row_ror:2 row_mask:0xf bank_mask:0xf
	v_rcp_f32_e32 v207, v207
	v_fmac_f32_dpp v219, v77, v45 row_ror:2 row_mask:0xf bank_mask:0xf
	v_pk_mul_f32 v[222:223], v[222:223], v[204:205]
	v_fmac_f32_dpp v220, v78, v46 row_ror:2 row_mask:0xf bank_mask:0xf
	v_pk_mul_f32 v[224:225], v[224:225], v[206:207]
	v_fmac_f32_dpp v221, v79, v47 row_ror:2 row_mask:0xf bank_mask:0xf
	v_pk_mul_f32 v[80:81], v[80:81], v[222:223]
	v_fmac_f32_dpp v218, v248, v160 row_ror:8 row_mask:0xf bank_mask:0xf
	v_pk_mul_f32 v[82:83], v[82:83], v[224:225]
	v_fmac_f32_dpp v219, v249, v161 row_ror:8 row_mask:0xf bank_mask:0xf
	v_cvt_pk_bf16_f32 v80, v80, v81
	v_fmac_f32_dpp v220, v250, v162 row_ror:8 row_mask:0xf bank_mask:0xf
	v_cvt_pk_bf16_f32 v81, v82, v83
	v_fmac_f32_dpp v221, v251, v163 row_ror:8 row_mask:0xf bank_mask:0xf
	v_fmac_f32_dpp v218, v248, v164 row_ror:6 row_mask:0xf bank_mask:0xf
	v_fmac_f32_dpp v219, v249, v165 row_ror:6 row_mask:0xf bank_mask:0xf
	v_fmac_f32_dpp v220, v250, v166 row_ror:6 row_mask:0xf bank_mask:0xf
	v_fmac_f32_dpp v221, v251, v167 row_ror:6 row_mask:0xf bank_mask:0xf
	v_pk_mul_f32 v[204:205], v[218:219], v[184:185] op_sel:[0,1] op_sel_hi:[1,1]
	v_pk_mul_f32 v[68:69], v[68:69], v[210:211] op_sel_hi:[1,0]
	v_pk_mul_f32 v[206:207], v[220:221], v[184:185] op_sel:[0,1] op_sel_hi:[1,1]
	v_pk_mul_f32 v[70:71], v[70:71], v[210:211] op_sel_hi:[1,0]
	v_exp_f32_e32 v204, v204
	v_pk_mul_f32 v[64:65], v[64:65], v[210:211] op_sel_hi:[1,0]
	v_exp_f32_e32 v205, v205
	v_pk_mul_f32 v[66:67], v[66:67], v[210:211] op_sel_hi:[1,0]
	v_exp_f32_e32 v206, v206
	v_pk_fma_f32 v[222:223], v[52:53], v[68:69], v[56:57]
	v_exp_f32_e32 v207, v207
	v_pk_fma_f32 v[224:225], v[54:55], v[70:71], v[58:59]
	v_pk_add_f32 v[204:205], v[204:205], 1.0 op_sel_hi:[1,0]
	v_fmac_f32_dpp v222, v68, v48 row_ror:1 row_mask:0xf bank_mask:0xf
	v_pk_add_f32 v[206:207], v[206:207], 1.0 op_sel_hi:[1,0]
	v_fmac_f32_dpp v223, v69, v49 row_ror:1 row_mask:0xf bank_mask:0xf
	v_rcp_f32_e32 v204, v204
	v_fmac_f32_dpp v224, v70, v50 row_ror:1 row_mask:0xf bank_mask:0xf
	v_rcp_f32_e32 v205, v205
	v_fmac_f32_dpp v225, v71, v51 row_ror:1 row_mask:0xf bank_mask:0xf
	v_rcp_f32_e32 v206, v206
	v_fmac_f32_dpp v222, v68, v44 row_ror:2 row_mask:0xf bank_mask:0xf
	v_rcp_f32_e32 v207, v207
	v_fmac_f32_dpp v223, v69, v45 row_ror:2 row_mask:0xf bank_mask:0xf
	v_pk_mul_f32 v[218:219], v[218:219], v[204:205]
	v_fmac_f32_dpp v224, v70, v46 row_ror:2 row_mask:0xf bank_mask:0xf
	v_pk_mul_f32 v[220:221], v[220:221], v[206:207]
	v_fmac_f32_dpp v225, v71, v47 row_ror:2 row_mask:0xf bank_mask:0xf
	v_pk_mul_f32 v[72:73], v[72:73], v[218:219]
	v_fmac_f32_dpp v222, v76, v160 row_ror:1 row_mask:0xf bank_mask:0xf
	v_pk_mul_f32 v[74:75], v[74:75], v[220:221]
	v_fmac_f32_dpp v223, v77, v161 row_ror:1 row_mask:0xf bank_mask:0xf
	v_cvt_pk_bf16_f32 v154, v72, v73
; DI u32x2 pk4(f32x4 v) { u32x2 r; r.x = pk2(v[0], v[1]); r.y = pk2(v[2], v[3]); return r; }
;     DI void operator()(const AccT& acc, const Unit& u, int wr, int wc, int fr, int fq, LAS unsigned char* ldsx) const {
;     ...
;                     const f32x4 cv = cb[n] + w0[n] * gm2 + w1[n] * gm1 + w2[n] * g;
;                     const f32x4 up = acc[ai][1][m][n] * rs[ai][m];
;                     f32x4 y;
; #pragma unroll
;                     for (int j = 0; j < 4; ++j) y[j] = cv[j] * __builtin_amdgcn_rcpf(1.f + __builtin_amdgcn_exp2f(-cv[j] * LOG2E)) * up[j];
;                     const int tok = tok0 + 128 * ai + 16 * m;
;                     bool ok = true;
;                     if (prompt && ai == 0 && m == 0) ok = (64 * wr + fr) >= 2;
;                     if (lastT) ok = ok && tok < SEQ;
;                     if (ok) *(u32x2*)(Y + ((unsigned)tok * (unsigned)DFF + (unsigned)f)) = pk4(y);
	v_fmac_f32_dpp v224, v78, v162 row_ror:1 row_mask:0xf bank_mask:0xf
	v_cvt_pk_bf16_f32 v155, v74, v75
	v_fmac_f32_dpp v225, v79, v163 row_ror:1 row_mask:0xf bank_mask:0xf
	v_fmac_f32_dpp v222, v76, v164 row_ror:2 row_mask:0xf bank_mask:0xf
	v_fmac_f32_dpp v223, v77, v165 row_ror:2 row_mask:0xf bank_mask:0xf
	v_fmac_f32_dpp v224, v78, v166 row_ror:2 row_mask:0xf bank_mask:0xf
	v_fmac_f32_dpp v225, v79, v167 row_ror:2 row_mask:0xf bank_mask:0xf
	s_nop 1
	v_permlane16_swap_b32_e32 v152, v154
	v_permlane16_swap_b32_e32 v153, v155
	s_and_saveexec_b64 s[28:29], s[60:61]
	global_store_dwordx4 v213, v[152:155], s[46:47] sc1
	s_mov_b64 exec, s[28:29]
	s_add_u32 s46, s46, 0x16000
	s_addc_u32 s47, s47, 0
	v_pk_mul_f32 v[204:205], v[222:223], v[184:185] op_sel:[0,1] op_sel_hi:[1,1]
	v_pk_mul_f32 v[60:61], v[60:61], v[208:209] op_sel_hi:[1,0]
	v_pk_mul_f32 v[206:207], v[224:225], v[184:185] op_sel:[0,1] op_sel_hi:[1,1]
	v_pk_mul_f32 v[62:63], v[62:63], v[208:209] op_sel_hi:[1,0]
	v_exp_f32_e32 v204, v204
	v_pk_mul_f32 v[40:41], v[40:41], v[208:209] op_sel_hi:[1,0]
	v_exp_f32_e32 v205, v205
	v_pk_mul_f32 v[42:43], v[42:43], v[208:209] op_sel_hi:[1,0]
	v_exp_f32_e32 v206, v206
	v_pk_fma_f32 v[218:219], v[52:53], v[60:61], v[56:57]
	v_exp_f32_e32 v207, v207
	v_pk_fma_f32 v[220:221], v[54:55], v[62:63], v[58:59]
	v_pk_add_f32 v[204:205], v[204:205], 1.0 op_sel_hi:[1,0]
	v_fmac_f32_dpp v218, v60, v48 row_ror:1 row_mask:0xf bank_mask:0xf
	v_pk_add_f32 v[206:207], v[206:207], 1.0 op_sel_hi:[1,0]
	v_fmac_f32_dpp v219, v61, v49 row_ror:1 row_mask:0xf bank_mask:0xf
	v_rcp_f32_e32 v204, v204
	v_fmac_f32_dpp v220, v62, v50 row_ror:1 row_mask:0xf bank_mask:0xf
	v_rcp_f32_e32 v205, v205
	v_fmac_f32_dpp v221, v63, v51 row_ror:1 row_mask:0xf bank_mask:0xf
	v_rcp_f32_e32 v206, v206
	v_fmac_f32_dpp v218, v60, v44 row_ror:2 row_mask:0xf bank_mask:0xf
	v_rcp_f32_e32 v207, v207
	v_fmac_f32_dpp v219, v61, v45 row_ror:2 row_mask:0xf bank_mask:0xf
	v_pk_mul_f32 v[222:223], v[222:223], v[204:205]
	v_fmac_f32_dpp v220, v62, v46 row_ror:2 row_mask:0xf bank_mask:0xf
	v_pk_mul_f32 v[224:225], v[224:225], v[206:207]
	v_fmac_f32_dpp v221, v63, v47 row_ror:2 row_mask:0xf bank_mask:0xf
	v_pk_mul_f32 v[64:65], v[64:65], v[222:223]
	v_fmac_f32_dpp v218, v68, v160 row_ror:1 row_mask:0xf bank_mask:0xf
	v_pk_mul_f32 v[66:67], v[66:67], v[224:225]
	v_fmac_f32_dpp v219, v69, v161 row_ror:1 row_mask:0xf bank_mask:0xf
	v_cvt_pk_bf16_f32 v146, v64, v65
	v_fmac_f32_dpp v220, v70, v162 row_ror:1 row_mask:0xf bank_mask:0xf
	v_cvt_pk_bf16_f32 v147, v66, v67
	v_fmac_f32_dpp v221, v71, v163 row_ror:1 row_mask:0xf bank_mask:0xf
	v_fmac_f32_dpp v218, v68, v164 row_ror:2 row_mask:0xf bank_mask:0xf
	v_fmac_f32_dpp v219, v69, v165 row_ror:2 row_mask:0xf bank_mask:0xf
	v_fmac_f32_dpp v220, v70, v166 row_ror:2 row_mask:0xf bank_mask:0xf
	v_fmac_f32_dpp v221, v71, v167 row_ror:2 row_mask:0xf bank_mask:0xf
	s_nop 1
	v_permlane16_swap_b32_e32 v144, v146
	v_permlane16_swap_b32_e32 v145, v147
	s_and_saveexec_b64 s[28:29], s[62:63]
	global_store_dwordx4 v213, v[144:147], s[46:47] sc1
	s_mov_b64 exec, s[28:29]
	s_add_u32 s46, s46, 0x16000
	s_addc_u32 s47, s47, 0
	v_pk_mul_f32 v[204:205], v[218:219], v[184:185] op_sel:[0,1] op_sel_hi:[1,1]
	v_pk_mul_f32 v[36:37], v[36:37], v[202:203] op_sel_hi:[1,0]
	v_pk_mul_f32 v[206:207], v[220:221], v[184:185] op_sel:[0,1] op_sel_hi:[1,1]
	v_pk_mul_f32 v[38:39], v[38:39], v[202:203] op_sel_hi:[1,0]
	v_exp_f32_e32 v204, v204
	v_pk_mul_f32 v[32:33], v[32:33], v[202:203] op_sel_hi:[1,0]
	v_exp_f32_e32 v205, v205
	v_pk_mul_f32 v[34:35], v[34:35], v[202:203] op_sel_hi:[1,0]
	v_exp_f32_e32 v206, v206
	v_pk_fma_f32 v[222:223], v[52:53], v[36:37], v[56:57]
	v_exp_f32_e32 v207, v207
	v_pk_fma_f32 v[224:225], v[54:55], v[38:39], v[58:59]
	v_pk_add_f32 v[204:205], v[204:205], 1.0 op_sel_hi:[1,0]
	v_fmac_f32_dpp v222, v36, v48 row_ror:1 row_mask:0xf bank_mask:0xf
	v_pk_add_f32 v[206:207], v[206:207], 1.0 op_sel_hi:[1,0]
	v_fmac_f32_dpp v223, v37, v49 row_ror:1 row_mask:0xf bank_mask:0xf
	v_rcp_f32_e32 v204, v204
	v_fmac_f32_dpp v224, v38, v50 row_ror:1 row_mask:0xf bank_mask:0xf
	v_rcp_f32_e32 v205, v205
	v_fmac_f32_dpp v225, v39, v51 row_ror:1 row_mask:0xf bank_mask:0xf
	v_rcp_f32_e32 v206, v206
	v_fmac_f32_dpp v222, v36, v44 row_ror:2 row_mask:0xf bank_mask:0xf
	v_rcp_f32_e32 v207, v207
	v_fmac_f32_dpp v223, v37, v45 row_ror:2 row_mask:0xf bank_mask:0xf
	v_pk_mul_f32 v[218:219], v[218:219], v[204:205]
	v_fmac_f32_dpp v224, v38, v46 row_ror:2 row_mask:0xf bank_mask:0xf
	v_pk_mul_f32 v[220:221], v[220:221], v[206:207]
	v_fmac_f32_dpp v225, v39, v47 row_ror:2 row_mask:0xf bank_mask:0xf
	v_pk_mul_f32 v[40:41], v[40:41], v[218:219]
	v_fmac_f32_dpp v222, v60, v160 row_ror:1 row_mask:0xf bank_mask:0xf
	v_pk_mul_f32 v[42:43], v[42:43], v[220:221]
	v_fmac_f32_dpp v223, v61, v161 row_ror:1 row_mask:0xf bank_mask:0xf
	v_cvt_pk_bf16_f32 v122, v40, v41
	v_fmac_f32_dpp v224, v62, v162 row_ror:1 row_mask:0xf bank_mask:0xf
	v_cvt_pk_bf16_f32 v123, v42, v43
	v_fmac_f32_dpp v225, v63, v163 row_ror:1 row_mask:0xf bank_mask:0xf
	v_fmac_f32_dpp v222, v60, v164 row_ror:2 row_mask:0xf bank_mask:0xf
	v_fmac_f32_dpp v223, v61, v165 row_ror:2 row_mask:0xf bank_mask:0xf
	v_fmac_f32_dpp v224, v62, v166 row_ror:2 row_mask:0xf bank_mask:0xf
	v_fmac_f32_dpp v225, v63, v167 row_ror:2 row_mask:0xf bank_mask:0xf
	s_nop 1
	v_permlane16_swap_b32_e32 v120, v122
	v_permlane16_swap_b32_e32 v121, v123
	s_and_saveexec_b64 s[28:29], s[64:65]
	global_store_dwordx4 v213, v[120:123], s[46:47] sc1
	s_mov_b64 exec, s[28:29]
	s_add_u32 s46, s46, 0x16000
	s_addc_u32 s47, s47, 0
	v_pk_mul_f32 v[204:205], v[222:223], v[184:185] op_sel:[0,1] op_sel_hi:[1,1]
; DI u32x2 pk4(f32x4 v) { u32x2 r; r.x = pk2(v[0], v[1]); r.y = pk2(v[2], v[3]); return r; }
;     DI void operator()(const AccT& acc, const Unit& u, int wr, int wc, int fr, int fq, LAS unsigned char* ldsx) const {
;     ...
;                     const f32x4 cv = cb[n] + w0[n] * gm2 + w1[n] * gm1 + w2[n] * g;
;                     const f32x4 up = acc[ai][1][m][n] * rs[ai][m];
;                     f32x4 y;
; #pragma unroll
;                     for (int j = 0; j < 4; ++j) y[j] = cv[j] * __builtin_amdgcn_rcpf(1.f + __builtin_amdgcn_exp2f(-cv[j] * LOG2E)) * up[j];
;                     const int tok = tok0 + 128 * ai + 16 * m;
;                     bool ok = true;
;                     if (prompt && ai == 0 && m == 0) ok = (64 * wr + fr) >= 2;
;                     if (lastT) ok = ok && tok < SEQ;
;                     if (ok) *(u32x2*)(Y + ((unsigned)tok * (unsigned)DFF + (unsigned)f)) = pk4(y);
	v_pk_mul_f32 v[28:29], v[28:29], v[200:201] op_sel_hi:[1,0]
	v_pk_mul_f32 v[206:207], v[224:225], v[184:185] op_sel:[0,1] op_sel_hi:[1,1]
	v_pk_mul_f32 v[30:31], v[30:31], v[200:201] op_sel_hi:[1,0]
	v_exp_f32_e32 v204, v204
	v_pk_mul_f32 v[24:25], v[24:25], v[200:201] op_sel_hi:[1,0]
	v_exp_f32_e32 v205, v205
	v_pk_mul_f32 v[26:27], v[26:27], v[200:201] op_sel_hi:[1,0]
	v_exp_f32_e32 v206, v206
	v_pk_fma_f32 v[218:219], v[52:53], v[28:29], v[56:57]
	v_exp_f32_e32 v207, v207
	v_pk_fma_f32 v[220:221], v[54:55], v[30:31], v[58:59]
	v_pk_add_f32 v[204:205], v[204:205], 1.0 op_sel_hi:[1,0]
	v_fmac_f32_dpp v218, v28, v48 row_ror:1 row_mask:0xf bank_mask:0xf
	v_pk_add_f32 v[206:207], v[206:207], 1.0 op_sel_hi:[1,0]
	v_fmac_f32_dpp v219, v29, v49 row_ror:1 row_mask:0xf bank_mask:0xf
	v_rcp_f32_e32 v204, v204
	v_fmac_f32_dpp v220, v30, v50 row_ror:1 row_mask:0xf bank_mask:0xf
	v_rcp_f32_e32 v205, v205
	v_fmac_f32_dpp v221, v31, v51 row_ror:1 row_mask:0xf bank_mask:0xf
	v_rcp_f32_e32 v206, v206
	v_fmac_f32_dpp v218, v28, v44 row_ror:2 row_mask:0xf bank_mask:0xf
	v_rcp_f32_e32 v207, v207
	v_fmac_f32_dpp v219, v29, v45 row_ror:2 row_mask:0xf bank_mask:0xf
	v_pk_mul_f32 v[222:223], v[222:223], v[204:205]
	v_fmac_f32_dpp v220, v30, v46 row_ror:2 row_mask:0xf bank_mask:0xf
	v_pk_mul_f32 v[224:225], v[224:225], v[206:207]
	v_fmac_f32_dpp v221, v31, v47 row_ror:2 row_mask:0xf bank_mask:0xf
	v_pk_mul_f32 v[32:33], v[32:33], v[222:223]
	v_fmac_f32_dpp v218, v248, v160 row_ror:4 row_mask:0xf bank_mask:0xf
	v_pk_mul_f32 v[34:35], v[34:35], v[224:225]
	v_fmac_f32_dpp v219, v249, v161 row_ror:4 row_mask:0xf bank_mask:0xf
	v_cvt_pk_bf16_f32 v114, v32, v33
	v_fmac_f32_dpp v220, v250, v162 row_ror:4 row_mask:0xf bank_mask:0xf
	v_cvt_pk_bf16_f32 v115, v34, v35
	v_fmac_f32_dpp v221, v251, v163 row_ror:4 row_mask:0xf bank_mask:0xf
	v_fmac_f32_dpp v218, v248, v164 row_ror:2 row_mask:0xf bank_mask:0xf
	v_fmac_f32_dpp v219, v249, v165 row_ror:2 row_mask:0xf bank_mask:0xf
	v_fmac_f32_dpp v220, v250, v166 row_ror:2 row_mask:0xf bank_mask:0xf
	v_fmac_f32_dpp v221, v251, v167 row_ror:2 row_mask:0xf bank_mask:0xf
	s_nop 1
	v_permlane16_swap_b32_e32 v112, v114
	v_permlane16_swap_b32_e32 v113, v115
	s_and_saveexec_b64 s[28:29], s[66:67]
	global_store_dwordx4 v213, v[112:115], s[46:47] sc1
	s_mov_b64 exec, s[28:29]
	s_add_u32 s46, s46, 0x6e000
	s_addc_u32 s47, s47, 0
	v_pk_mul_f32 v[204:205], v[218:219], v[184:185] op_sel:[0,1] op_sel_hi:[1,1]
	v_pk_mul_f32 v[20:21], v[20:21], v[192:193] op_sel_hi:[1,0]
	v_pk_mul_f32 v[206:207], v[220:221], v[184:185] op_sel:[0,1] op_sel_hi:[1,1]
	v_pk_mul_f32 v[22:23], v[22:23], v[192:193] op_sel_hi:[1,0]
	v_exp_f32_e32 v204, v204
	v_pk_mul_f32 v[16:17], v[16:17], v[192:193] op_sel_hi:[1,0]
	v_exp_f32_e32 v205, v205
	v_pk_mul_f32 v[18:19], v[18:19], v[192:193] op_sel_hi:[1,0]
	v_exp_f32_e32 v206, v206
	v_pk_fma_f32 v[222:223], v[52:53], v[20:21], v[56:57]
	v_exp_f32_e32 v207, v207
	v_pk_fma_f32 v[224:225], v[54:55], v[22:23], v[58:59]
	v_pk_add_f32 v[204:205], v[204:205], 1.0 op_sel_hi:[1,0]
	v_fmac_f32_dpp v222, v20, v48 row_ror:1 row_mask:0xf bank_mask:0xf
	v_pk_add_f32 v[206:207], v[206:207], 1.0 op_sel_hi:[1,0]
	v_fmac_f32_dpp v223, v21, v49 row_ror:1 row_mask:0xf bank_mask:0xf
	v_rcp_f32_e32 v204, v204
	v_fmac_f32_dpp v224, v22, v50 row_ror:1 row_mask:0xf bank_mask:0xf
	v_rcp_f32_e32 v205, v205
	v_fmac_f32_dpp v225, v23, v51 row_ror:1 row_mask:0xf bank_mask:0xf
	v_rcp_f32_e32 v206, v206
	v_fmac_f32_dpp v222, v20, v44 row_ror:2 row_mask:0xf bank_mask:0xf
	v_rcp_f32_e32 v207, v207
	v_fmac_f32_dpp v223, v21, v45 row_ror:2 row_mask:0xf bank_mask:0xf
	v_pk_mul_f32 v[218:219], v[218:219], v[204:205]
	v_fmac_f32_dpp v224, v22, v46 row_ror:2 row_mask:0xf bank_mask:0xf
	v_pk_mul_f32 v[220:221], v[220:221], v[206:207]
	v_fmac_f32_dpp v225, v23, v47 row_ror:2 row_mask:0xf bank_mask:0xf
	v_pk_mul_f32 v[24:25], v[24:25], v[218:219]
	v_fmac_f32_dpp v222, v28, v160 row_ror:1 row_mask:0xf bank_mask:0xf
	v_pk_mul_f32 v[26:27], v[26:27], v[220:221]
	v_fmac_f32_dpp v223, v29, v161 row_ror:1 row_mask:0xf bank_mask:0xf
	v_cvt_pk_bf16_f32 v106, v24, v25
	v_fmac_f32_dpp v224, v30, v162 row_ror:1 row_mask:0xf bank_mask:0xf
	v_cvt_pk_bf16_f32 v107, v26, v27
	v_fmac_f32_dpp v225, v31, v163 row_ror:1 row_mask:0xf bank_mask:0xf
	v_fmac_f32_dpp v222, v28, v164 row_ror:2 row_mask:0xf bank_mask:0xf
	v_fmac_f32_dpp v223, v29, v165 row_ror:2 row_mask:0xf bank_mask:0xf
	v_fmac_f32_dpp v224, v30, v166 row_ror:2 row_mask:0xf bank_mask:0xf
	v_fmac_f32_dpp v225, v31, v167 row_ror:2 row_mask:0xf bank_mask:0xf
	s_nop 1
	v_permlane16_swap_b32_e32 v104, v106
	v_permlane16_swap_b32_e32 v105, v107
	s_and_saveexec_b64 s[28:29], s[68:69]
	global_store_dwordx4 v213, v[104:107], s[46:47] sc1
	s_mov_b64 exec, s[28:29]
	s_add_u32 s46, s46, 0x16000
	s_addc_u32 s47, s47, 0
	v_pk_mul_f32 v[204:205], v[222:223], v[184:185] op_sel:[0,1] op_sel_hi:[1,1]
	v_pk_mul_f32 v[12:13], v[12:13], v[190:191] op_sel_hi:[1,0]
	v_pk_mul_f32 v[206:207], v[224:225], v[184:185] op_sel:[0,1] op_sel_hi:[1,1]
	v_pk_mul_f32 v[14:15], v[14:15], v[190:191] op_sel_hi:[1,0]
	v_exp_f32_e32 v204, v204
	v_pk_mul_f32 v[8:9], v[8:9], v[190:191] op_sel_hi:[1,0]
	v_exp_f32_e32 v205, v205
	v_pk_mul_f32 v[10:11], v[10:11], v[190:191] op_sel_hi:[1,0]
	v_exp_f32_e32 v206, v206
	v_pk_fma_f32 v[218:219], v[52:53], v[12:13], v[56:57]
	v_exp_f32_e32 v207, v207
	v_pk_fma_f32 v[220:221], v[54:55], v[14:15], v[58:59]
	v_pk_add_f32 v[204:205], v[204:205], 1.0 op_sel_hi:[1,0]
	v_fmac_f32_dpp v218, v12, v48 row_ror:1 row_mask:0xf bank_mask:0xf
	v_pk_add_f32 v[206:207], v[206:207], 1.0 op_sel_hi:[1,0]
; DI u32x2 pk4(f32x4 v) { u32x2 r; r.x = pk2(v[0], v[1]); r.y = pk2(v[2], v[3]); return r; }
;     DI void operator()(const AccT& acc, const Unit& u, int wr, int wc, int fr, int fq, LAS unsigned char* ldsx) const {
;     ...
;                     for (int j = 0; j < 4; ++j) y[j] = cv[j] * __builtin_amdgcn_rcpf(1.f + __builtin_amdgcn_exp2f(-cv[j] * LOG2E)) * up[j];
;                     const int tok = tok0 + 128 * ai + 16 * m;
;                     bool ok = true;
;                     if (prompt && ai == 0 && m == 0) ok = (64 * wr + fr) >= 2;
;                     if (lastT) ok = ok && tok < SEQ;
;                     if (ok) *(u32x2*)(Y + ((unsigned)tok * (unsigned)DFF + (unsigned)f)) = pk4(y);
;                     if (lastT) { if (tok == SEQ - 2 || tok == SEQ - 1) *(f32x4*)(out + OFF_CVP + (size_t)(tok - (SEQ - 2)) * DFF + f) = g; }
;                     if (!prompt && m == 3 && fr >= 14) *(f32x4*)(out + OFF_CVS + (size_t)(sb * 2 + (fr - 14)) * DFF + f) = g;
	v_fmac_f32_dpp v219, v13, v49 row_ror:1 row_mask:0xf bank_mask:0xf
	v_rcp_f32_e32 v204, v204
	v_fmac_f32_dpp v220, v14, v50 row_ror:1 row_mask:0xf bank_mask:0xf
	v_rcp_f32_e32 v205, v205
	v_fmac_f32_dpp v221, v15, v51 row_ror:1 row_mask:0xf bank_mask:0xf
	v_rcp_f32_e32 v206, v206
	v_fmac_f32_dpp v218, v12, v44 row_ror:2 row_mask:0xf bank_mask:0xf
	v_rcp_f32_e32 v207, v207
	v_fmac_f32_dpp v219, v13, v45 row_ror:2 row_mask:0xf bank_mask:0xf
	v_pk_mul_f32 v[222:223], v[222:223], v[204:205]
	v_fmac_f32_dpp v220, v14, v46 row_ror:2 row_mask:0xf bank_mask:0xf
	v_pk_mul_f32 v[224:225], v[224:225], v[206:207]
	v_fmac_f32_dpp v221, v15, v47 row_ror:2 row_mask:0xf bank_mask:0xf
	v_pk_mul_f32 v[16:17], v[16:17], v[222:223]
	v_fmac_f32_dpp v218, v20, v160 row_ror:1 row_mask:0xf bank_mask:0xf
	v_pk_mul_f32 v[18:19], v[18:19], v[224:225]
	v_fmac_f32_dpp v219, v21, v161 row_ror:1 row_mask:0xf bank_mask:0xf
	v_cvt_pk_bf16_f32 v98, v16, v17
	v_fmac_f32_dpp v220, v22, v162 row_ror:1 row_mask:0xf bank_mask:0xf
	v_cvt_pk_bf16_f32 v99, v18, v19
	v_fmac_f32_dpp v221, v23, v163 row_ror:1 row_mask:0xf bank_mask:0xf
	v_fmac_f32_dpp v218, v20, v164 row_ror:2 row_mask:0xf bank_mask:0xf
	v_fmac_f32_dpp v219, v21, v165 row_ror:2 row_mask:0xf bank_mask:0xf
	v_fmac_f32_dpp v220, v22, v166 row_ror:2 row_mask:0xf bank_mask:0xf
	v_fmac_f32_dpp v221, v23, v167 row_ror:2 row_mask:0xf bank_mask:0xf
	s_nop 1
	v_permlane16_swap_b32_e32 v96, v98
	v_permlane16_swap_b32_e32 v97, v99
	s_and_saveexec_b64 s[28:29], s[70:71]
	global_store_dwordx4 v213, v[96:99], s[46:47] sc1
	s_mov_b64 exec, s[28:29]
	s_add_u32 s46, s46, 0x16000
	s_addc_u32 s47, s47, 0
	v_pk_mul_f32 v[204:205], v[218:219], v[184:185] op_sel:[0,1] op_sel_hi:[1,1]
	v_pk_mul_f32 v[4:5], v[4:5], v[184:185] op_sel_hi:[1,0]
	v_pk_mul_f32 v[206:207], v[220:221], v[184:185] op_sel:[0,1] op_sel_hi:[1,1]
	v_pk_mul_f32 v[6:7], v[6:7], v[184:185] op_sel_hi:[1,0]
	v_exp_f32_e32 v204, v204
	v_pk_mul_f32 v[0:1], v[0:1], v[184:185] op_sel_hi:[1,0]
	v_exp_f32_e32 v205, v205
	v_pk_mul_f32 v[2:3], v[2:3], v[184:185] op_sel_hi:[1,0]
	v_exp_f32_e32 v206, v206
	v_pk_fma_f32 v[222:223], v[52:53], v[4:5], v[56:57]
	v_exp_f32_e32 v207, v207
	v_pk_fma_f32 v[224:225], v[54:55], v[6:7], v[58:59]
	v_pk_add_f32 v[204:205], v[204:205], 1.0 op_sel_hi:[1,0]
	v_fmac_f32_dpp v222, v4, v48 row_ror:1 row_mask:0xf bank_mask:0xf
	v_pk_add_f32 v[206:207], v[206:207], 1.0 op_sel_hi:[1,0]
	v_fmac_f32_dpp v223, v5, v49 row_ror:1 row_mask:0xf bank_mask:0xf
	v_rcp_f32_e32 v204, v204
	v_fmac_f32_dpp v224, v6, v50 row_ror:1 row_mask:0xf bank_mask:0xf
	v_rcp_f32_e32 v205, v205
	v_fmac_f32_dpp v225, v7, v51 row_ror:1 row_mask:0xf bank_mask:0xf
	v_rcp_f32_e32 v206, v206
	v_fmac_f32_dpp v222, v4, v44 row_ror:2 row_mask:0xf bank_mask:0xf
	v_rcp_f32_e32 v207, v207
	v_fmac_f32_dpp v223, v5, v45 row_ror:2 row_mask:0xf bank_mask:0xf
	v_pk_mul_f32 v[218:219], v[218:219], v[204:205]
	v_fmac_f32_dpp v224, v6, v46 row_ror:2 row_mask:0xf bank_mask:0xf
	v_pk_mul_f32 v[220:221], v[220:221], v[206:207]
	v_fmac_f32_dpp v225, v7, v47 row_ror:2 row_mask:0xf bank_mask:0xf
	v_pk_mul_f32 v[8:9], v[8:9], v[218:219]
	v_fmac_f32_dpp v222, v12, v160 row_ror:1 row_mask:0xf bank_mask:0xf
	v_pk_mul_f32 v[10:11], v[10:11], v[220:221]
	v_fmac_f32_dpp v223, v13, v161 row_ror:1 row_mask:0xf bank_mask:0xf
	v_cvt_pk_bf16_f32 v90, v8, v9
	v_fmac_f32_dpp v224, v14, v162 row_ror:1 row_mask:0xf bank_mask:0xf
	v_cvt_pk_bf16_f32 v91, v10, v11
	v_fmac_f32_dpp v225, v15, v163 row_ror:1 row_mask:0xf bank_mask:0xf
	v_fmac_f32_dpp v222, v12, v164 row_ror:2 row_mask:0xf bank_mask:0xf
	v_fmac_f32_dpp v223, v13, v165 row_ror:2 row_mask:0xf bank_mask:0xf
	v_fmac_f32_dpp v224, v14, v166 row_ror:2 row_mask:0xf bank_mask:0xf
	v_fmac_f32_dpp v225, v15, v167 row_ror:2 row_mask:0xf bank_mask:0xf
	s_nop 1
	v_permlane16_swap_b32_e32 v88, v90
	v_permlane16_swap_b32_e32 v89, v91
	s_and_saveexec_b64 s[28:29], s[72:73]
	global_store_dwordx4 v213, v[88:91], s[46:47] sc1
	s_mov_b64 exec, s[28:29]
	s_add_u32 s46, s46, 0x16000
	s_addc_u32 s47, s47, 0
	v_pk_mul_f32 v[204:205], v[222:223], v[184:185] op_sel:[0,1] op_sel_hi:[1,1]
	v_pk_mul_f32 v[206:207], v[224:225], v[184:185] op_sel:[0,1] op_sel_hi:[1,1]
	v_exp_f32_e32 v204, v204
	v_exp_f32_e32 v205, v205
	v_exp_f32_e32 v206, v206
	v_exp_f32_e32 v207, v207
	v_pk_add_f32 v[204:205], v[204:205], 1.0 op_sel_hi:[1,0]
	v_pk_add_f32 v[206:207], v[206:207], 1.0 op_sel_hi:[1,0]
	v_rcp_f32_e32 v204, v204
	v_rcp_f32_e32 v205, v205
	v_rcp_f32_e32 v206, v206
	v_rcp_f32_e32 v207, v207
	v_pk_mul_f32 v[222:223], v[222:223], v[204:205]
	v_pk_mul_f32 v[224:225], v[224:225], v[206:207]
	v_pk_mul_f32 v[0:1], v[0:1], v[222:223]
	v_pk_mul_f32 v[2:3], v[2:3], v[224:225]
	v_cvt_pk_bf16_f32 v82, v0, v1
	v_cvt_pk_bf16_f32 v83, v2, v3
	s_nop 1
	v_permlane16_swap_b32_e32 v80, v82
	v_permlane16_swap_b32_e32 v81, v83
	s_and_saveexec_b64 s[28:29], s[74:75]
	global_store_dwordx4 v213, v[80:83], s[46:47] sc1
	s_mov_b64 exec, s[28:29]
	s_cmp_gt_i32 s42, 64
	s_cbranch_scc0 .Lgu_nocvs
	v_readlane_b32 s30, v252, 0
	v_readlane_b32 s31, v252, 1
	s_lshl_b32 s23, s42, 2
	s_add_i32 s23, s36, s23
	s_lshl_b32 s23, s23, 1
	s_movk_i32 s76, 0x2c00
	v_add_u32_e32 v186, s23, v233
	v_mad_i64_i32 v[186:187], s[34:35], v186, s76, 0
	v_lshl_add_u64 v[186:187], s[14:15], 0, v[186:187]
	v_lshl_add_u64 v[186:187], v[216:217], 2, v[186:187]
	s_and_saveexec_b64 s[28:29], s[30:31]
	global_store_dwordx4 v[186:187], v[116:119], off sc1
	global_store_dwordx4 v[186:187], v[36:39], off offset:64 sc1
	s_mov_b64 exec, s[28:29]
	s_add_i32 s23, s23, 4
	v_add_u32_e32 v186, s23, v233
	v_mad_i64_i32 v[186:187], s[34:35], v186, s76, 0
	v_lshl_add_u64 v[186:187], s[14:15], 0, v[186:187]
	v_lshl_add_u64 v[186:187], v[216:217], 2, v[186:187]
	s_and_saveexec_b64 s[28:29], s[30:31]
	global_store_dwordx4 v[186:187], v[84:87], off sc1
	global_store_dwordx4 v[186:187], v[4:7], off offset:64 sc1
	s_mov_b64 exec, s[28:29]
;     DI void operator()(const AccT& acc, const Unit& u, int wr, int wc, int fr, int fq, LAS unsigned char* ldsx) const {
;     ...
;                     if (lastT) { if (tok == SEQ - 2 || tok == SEQ - 1) *(f32x4*)(out + OFF_CVP + (size_t)(tok - (SEQ - 2)) * DFF + f) = g; }
.Lgu_nocvs:
	s_cmp_eq_u32 s42, 64
	s_cbranch_scc0 .Lgu_nocvp
	v_mov_b32_e32 v186, v172
	v_and_b32_e32 v187, -2, v186
	v_cmp_eq_u32_e32 vcc, s88, v187
	s_and_saveexec_b64 s[28:29], vcc
	v_mul_lo_u32 v186, v186, s87
	v_mov_b32_e32 v187, v173
	v_lshl_add_u64 v[188:189], v[186:187], 2, s[6:7]
	v_lshl_add_u64 v[188:189], v[216:217], 2, v[188:189]
	v_add_co_u32_e32 v188, vcc, 0xf9a26000, v188
	s_nop 1
	v_addc_co_u32_e32 v189, vcc, -1, v189, vcc
	global_store_dwordx4 v[188:189], v[156:159], off offset:-2048 sc1
	s_mov_b64 exec, s[28:29]
	v_add_u32_e32 v186, 0x10, v172
	v_and_b32_e32 v187, -2, v186
	v_cmp_eq_u32_e32 vcc, s88, v187
	s_and_saveexec_b64 s[28:29], vcc
	v_mul_lo_u32 v186, v186, s87
	v_mov_b32_e32 v187, v173
	v_lshl_add_u64 v[188:189], v[186:187], 2, s[6:7]
	v_lshl_add_u64 v[188:189], v[216:217], 2, v[188:189]
	v_add_co_u32_e32 v188, vcc, 0xf9a26000, v188
	s_nop 1
	v_addc_co_u32_e32 v189, vcc, -1, v189, vcc
	global_store_dwordx4 v[188:189], v[148:151], off offset:-2048 sc1
	s_mov_b64 exec, s[28:29]
	v_add_u32_e32 v186, 0x20, v172
	v_and_b32_e32 v187, -2, v186
	v_cmp_eq_u32_e32 vcc, s88, v187
	s_and_saveexec_b64 s[28:29], vcc
	v_mul_lo_u32 v186, v186, s87
	v_mov_b32_e32 v187, v173
	v_lshl_add_u64 v[188:189], v[186:187], 2, s[6:7]
	v_lshl_add_u64 v[188:189], v[216:217], 2, v[188:189]
	v_add_co_u32_e32 v188, vcc, 0xf9a26000, v188
	s_nop 1
	v_addc_co_u32_e32 v189, vcc, -1, v189, vcc
	global_store_dwordx4 v[188:189], v[140:143], off offset:-2048 sc1
	s_mov_b64 exec, s[28:29]
	v_add_u32_e32 v186, 0x30, v172
	v_and_b32_e32 v187, -2, v186
	v_cmp_eq_u32_e32 vcc, s88, v187
	s_and_saveexec_b64 s[28:29], vcc
	v_mul_lo_u32 v186, v186, s87
	v_mov_b32_e32 v187, v173
	v_lshl_add_u64 v[188:189], v[186:187], 2, s[6:7]
	v_lshl_add_u64 v[188:189], v[216:217], 2, v[188:189]
	v_add_co_u32_e32 v188, vcc, 0xf9a26000, v188
	s_nop 1
	v_addc_co_u32_e32 v189, vcc, -1, v189, vcc
	global_store_dwordx4 v[188:189], v[116:119], off offset:-2048 sc1
	s_mov_b64 exec, s[28:29]
	v_add_u32_e32 v186, 0x80, v172
	v_and_b32_e32 v187, -2, v186
	v_cmp_eq_u32_e32 vcc, s88, v187
	s_and_saveexec_b64 s[28:29], vcc
	v_mul_lo_u32 v186, v186, s87
	v_mov_b32_e32 v187, v173
	v_lshl_add_u64 v[188:189], v[186:187], 2, s[6:7]
	v_lshl_add_u64 v[188:189], v[216:217], 2, v[188:189]
	v_add_co_u32_e32 v188, vcc, 0xf9a26000, v188
	s_nop 1
	v_addc_co_u32_e32 v189, vcc, -1, v189, vcc
	global_store_dwordx4 v[188:189], v[108:111], off offset:-2048 sc1
	s_mov_b64 exec, s[28:29]
	v_add_u32_e32 v186, 0x90, v172
	v_and_b32_e32 v187, -2, v186
	v_cmp_eq_u32_e32 vcc, s88, v187
	s_and_saveexec_b64 s[28:29], vcc
	v_mul_lo_u32 v186, v186, s87
	v_mov_b32_e32 v187, v173
	v_lshl_add_u64 v[188:189], v[186:187], 2, s[6:7]
	v_lshl_add_u64 v[188:189], v[216:217], 2, v[188:189]
	v_add_co_u32_e32 v188, vcc, 0xf9a26000, v188
	s_nop 1
	v_addc_co_u32_e32 v189, vcc, -1, v189, vcc
	global_store_dwordx4 v[188:189], v[100:103], off offset:-2048 sc1
	s_mov_b64 exec, s[28:29]
	v_add_u32_e32 v186, 0xa0, v172
	v_and_b32_e32 v187, -2, v186
	v_cmp_eq_u32_e32 vcc, s88, v187
	s_and_saveexec_b64 s[28:29], vcc
	v_mul_lo_u32 v186, v186, s87
	v_mov_b32_e32 v187, v173
	v_lshl_add_u64 v[188:189], v[186:187], 2, s[6:7]
	v_lshl_add_u64 v[188:189], v[216:217], 2, v[188:189]
	v_add_co_u32_e32 v188, vcc, 0xf9a26000, v188
	s_nop 1
	v_addc_co_u32_e32 v189, vcc, -1, v189, vcc
	global_store_dwordx4 v[188:189], v[92:95], off offset:-2048 sc1
	s_mov_b64 exec, s[28:29]
	v_add_u32_e32 v186, 0xb0, v172
	v_and_b32_e32 v187, -2, v186
	v_cmp_eq_u32_e32 vcc, s88, v187
	s_and_saveexec_b64 s[28:29], vcc
	v_mul_lo_u32 v186, v186, s87
	v_mov_b32_e32 v187, v173
	v_lshl_add_u64 v[188:189], v[186:187], 2, s[6:7]
	v_lshl_add_u64 v[188:189], v[216:217], 2, v[188:189]
	v_add_co_u32_e32 v188, vcc, 0xf9a26000, v188
	s_nop 1
	v_addc_co_u32_e32 v189, vcc, -1, v189, vcc
	global_store_dwordx4 v[188:189], v[84:87], off offset:-2048 sc1
;     DI void operator()(const AccT& acc, const Unit& u, int wr, int wc, int fr, int fq, LAS unsigned char* ldsx) const {
;     ...
;                     if (lastT) { if (tok == SEQ - 2 || tok == SEQ - 1) *(f32x4*)(out + OFF_CVP + (size_t)(tok - (SEQ - 2)) * DFF + f) = g; }
	s_mov_b64 exec, s[28:29]
	v_mov_b32_e32 v186, v172
	v_and_b32_e32 v187, -2, v186
	v_cmp_eq_u32_e32 vcc, s88, v187
	s_and_saveexec_b64 s[28:29], vcc
	v_mul_lo_u32 v186, v186, s87
	v_mov_b32_e32 v187, v173
	v_lshl_add_u64 v[188:189], v[186:187], 2, s[6:7]
	v_lshl_add_u64 v[188:189], v[182:183], 2, v[188:189]
	v_add_co_u32_e32 v188, vcc, 0xf9a26000, v188
	s_nop 1
	v_addc_co_u32_e32 v189, vcc, -1, v189, vcc
	global_store_dwordx4 v[188:189], v[76:79], off offset:-2048 sc1
	s_mov_b64 exec, s[28:29]
	v_add_u32_e32 v186, 0x10, v172
	v_and_b32_e32 v187, -2, v186
	v_cmp_eq_u32_e32 vcc, s88, v187
	s_and_saveexec_b64 s[28:29], vcc
	v_mul_lo_u32 v186, v186, s87
	v_mov_b32_e32 v187, v173
	v_lshl_add_u64 v[188:189], v[186:187], 2, s[6:7]
	v_lshl_add_u64 v[188:189], v[182:183], 2, v[188:189]
	v_add_co_u32_e32 v188, vcc, 0xf9a26000, v188
	s_nop 1
	v_addc_co_u32_e32 v189, vcc, -1, v189, vcc
	global_store_dwordx4 v[188:189], v[68:71], off offset:-2048 sc1
	s_mov_b64 exec, s[28:29]
	v_add_u32_e32 v186, 0x20, v172
	v_and_b32_e32 v187, -2, v186
	v_cmp_eq_u32_e32 vcc, s88, v187
	s_and_saveexec_b64 s[28:29], vcc
	v_mul_lo_u32 v186, v186, s87
	v_mov_b32_e32 v187, v173
	v_lshl_add_u64 v[188:189], v[186:187], 2, s[6:7]
	v_lshl_add_u64 v[188:189], v[182:183], 2, v[188:189]
	v_add_co_u32_e32 v188, vcc, 0xf9a26000, v188
	s_nop 1
	v_addc_co_u32_e32 v189, vcc, -1, v189, vcc
	global_store_dwordx4 v[188:189], v[60:63], off offset:-2048 sc1
	s_mov_b64 exec, s[28:29]
	v_add_u32_e32 v186, 0x30, v172
	v_and_b32_e32 v187, -2, v186
	v_cmp_eq_u32_e32 vcc, s88, v187
	s_and_saveexec_b64 s[28:29], vcc
	v_mul_lo_u32 v186, v186, s87
	v_mov_b32_e32 v187, v173
	v_lshl_add_u64 v[188:189], v[186:187], 2, s[6:7]
	v_lshl_add_u64 v[188:189], v[182:183], 2, v[188:189]
	v_add_co_u32_e32 v188, vcc, 0xf9a26000, v188
	s_nop 1
	v_addc_co_u32_e32 v189, vcc, -1, v189, vcc
	global_store_dwordx4 v[188:189], v[36:39], off offset:-2048 sc1
	s_mov_b64 exec, s[28:29]
	v_add_u32_e32 v186, 0x80, v172
	v_and_b32_e32 v187, -2, v186
	v_cmp_eq_u32_e32 vcc, s88, v187
	s_and_saveexec_b64 s[28:29], vcc
	v_mul_lo_u32 v186, v186, s87
	v_mov_b32_e32 v187, v173
	v_lshl_add_u64 v[188:189], v[186:187], 2, s[6:7]
	v_lshl_add_u64 v[188:189], v[182:183], 2, v[188:189]
	v_add_co_u32_e32 v188, vcc, 0xf9a26000, v188
	s_nop 1
	v_addc_co_u32_e32 v189, vcc, -1, v189, vcc
	global_store_dwordx4 v[188:189], v[28:31], off offset:-2048 sc1
	s_mov_b64 exec, s[28:29]
	v_add_u32_e32 v186, 0x90, v172
	v_and_b32_e32 v187, -2, v186
	v_cmp_eq_u32_e32 vcc, s88, v187
	s_and_saveexec_b64 s[28:29], vcc
	v_mul_lo_u32 v186, v186, s87
	v_mov_b32_e32 v187, v173
	v_lshl_add_u64 v[188:189], v[186:187], 2, s[6:7]
	v_lshl_add_u64 v[188:189], v[182:183], 2, v[188:189]
	v_add_co_u32_e32 v188, vcc, 0xf9a26000, v188
	s_nop 1
	v_addc_co_u32_e32 v189, vcc, -1, v189, vcc
	global_store_dwordx4 v[188:189], v[20:23], off offset:-2048 sc1
	s_mov_b64 exec, s[28:29]
	v_add_u32_e32 v186, 0xa0, v172
	v_and_b32_e32 v187, -2, v186
	v_cmp_eq_u32_e32 vcc, s88, v187
	s_and_saveexec_b64 s[28:29], vcc
	v_mul_lo_u32 v186, v186, s87
	v_mov_b32_e32 v187, v173
	v_lshl_add_u64 v[188:189], v[186:187], 2, s[6:7]
	v_lshl_add_u64 v[188:189], v[182:183], 2, v[188:189]
	v_add_co_u32_e32 v188, vcc, 0xf9a26000, v188
	s_nop 1
	v_addc_co_u32_e32 v189, vcc, -1, v189, vcc
	global_store_dwordx4 v[188:189], v[12:15], off offset:-2048 sc1
	s_mov_b64 exec, s[28:29]
	v_add_u32_e32 v186, 0xb0, v172
	v_and_b32_e32 v187, -2, v186
	v_cmp_eq_u32_e32 vcc, s88, v187
	s_and_saveexec_b64 s[28:29], vcc
	v_mul_lo_u32 v186, v186, s87
	v_mov_b32_e32 v187, v173
	v_lshl_add_u64 v[188:189], v[186:187], 2, s[6:7]
	v_lshl_add_u64 v[188:189], v[182:183], 2, v[188:189]
	v_add_co_u32_e32 v188, vcc, 0xf9a26000, v188
	s_nop 1
	v_addc_co_u32_e32 v189, vcc, -1, v189, vcc
	global_store_dwordx4 v[188:189], v[4:7], off offset:-2048 sc1
	s_mov_b64 exec, s[28:29]

; DI u32x2 pk4(f32x4 v) { u32x2 r; r.x = pk2(v[0], v[1]); r.y = pk2(v[2], v[3]); return r; }
;     DI void operator()(const AccT& acc, const Unit& u, int wr, int wc, int fr, int fq, LAS unsigned char*) const {
;         const int col0 = u.pn * 256 + wc * 32 + 4 * fq;
; #pragma unroll
;         for (int ai = 0; ai < 2; ++ai)
; #pragma unroll
;             for (int m = 0; m < 4; ++m) {
;                 const int row = u.pm * 256 + ai * 128 + wr * 64 + m * 16 + fr;
;                 const float* xr = (row < SEQ ? xp + (size_t)row * DM : xs + (size_t)(row - SEQ) * DM) + col0;
;                 bf16_t* brow = X1B + (size_t)(row < SEQ ? row + 2 : row + (X1B_PROMPT_ROWS - SEQ)) * DM + col0;
;                 float ss = 0.f;
; #pragma unroll
;                 for (int bj = 0; bj < 2; ++bj)
; #pragma unroll
;                     for (int n = 0; n < 2; ++n) {
;                         const int c = bj * 128 + n * 16;
;                         const f32x4 o = *(const f32x4*)(xr + c) + acc[ai][bj][m][n];
;                         *(u32x2*)(brow + c) = pk4(o);
;                         ss += (o[0] * o[0] + o[1] * o[1]) + (o[2] * o[2] + o[3] * o[3]);
;                     }
.LBB0_960:
	v_lshl_add_u32 v130, s31, 8, v132
	v_lshl_or_b32 v128, s33, 8, v134
	s_cmp_lt_i32 s31, 64
	s_cselect_b32 s16, s44, s46
	s_cselect_b32 s17, s45, s47
	s_cselect_b32 s42, 0, 0x4000000
	s_cselect_b32 s43, 1, 64
	s_lshl_b32 s43, s43, 12
	s_sub_u32 s16, s16, s42
	s_subb_u32 s17, s17, 0
	s_add_u32 s18, s56, s43
	s_addc_u32 s19, s57, 0
	v_lshlrev_b32_e32 v129, 12, v130
	v_lshlrev_b32_e32 v131, 11, v130
	v_lshl_add_u32 v129, v128, 2, v129
	v_lshl_add_u32 v131, v128, 1, v131
	v_lshlrev_b32_e32 v130, 2, v130
	v_and_b32_e32 v128, 16, v226
	v_lshrrev_b32_e32 v144, 1, v128
	v_add3_u32 v131, v131, v128, v144
	global_load_dwordx4 v[146:149], v129, s[16:17]
	global_load_dwordx4 v[150:153], v129, s[16:17] offset:64
	global_load_dwordx4 v[154:157], v129, s[16:17] offset:512
	global_load_dwordx4 v[158:161], v129, s[16:17] offset:576
	s_add_u32 s36, s16, 0x10000
	s_addc_u32 s37, s17, 0
	global_load_dwordx4 v[182:185], v129, s[36:37]
	global_load_dwordx4 v[186:189], v129, s[36:37] offset:64
	global_load_dwordx4 v[190:193], v129, s[36:37] offset:512
	global_load_dwordx4 v[194:197], v129, s[36:37] offset:576
	s_add_u32 s36, s16, 0x20000
	s_addc_u32 s37, s17, 0
	global_load_dwordx4 v[198:201], v129, s[36:37]
	global_load_dwordx4 v[202:205], v129, s[36:37] offset:64
	global_load_dwordx4 v[206:209], v129, s[36:37] offset:512
	global_load_dwordx4 v[210:213], v129, s[36:37] offset:576
	s_add_u32 s36, s16, 0x30000
	s_addc_u32 s37, s17, 0
	global_load_dwordx4 v[162:165], v129, s[36:37]
	global_load_dwordx4 v[214:217], v129, s[36:37] offset:64
	global_load_dwordx4 v[136:139], v129, s[36:37] offset:512
	global_load_dwordx4 v[140:143], v129, s[36:37] offset:576
	s_waitcnt vmcnt(12)
	v_pk_add_f32 v[146:147], v[124:125], v[146:147]
	v_pk_add_f32 v[148:149], v[126:127], v[148:149]
	v_pk_add_f32 v[150:151], v[120:121], v[150:151]
	v_pk_add_f32 v[152:153], v[122:123], v[152:153]
	v_pk_add_f32 v[154:155], v[116:117], v[154:155]
	v_pk_add_f32 v[156:157], v[118:119], v[156:157]
	v_pk_add_f32 v[158:159], v[112:113], v[158:159]
	v_pk_add_f32 v[160:161], v[114:115], v[160:161]
	s_add_u32 s36, s16, 0x80000
	s_addc_u32 s37, s17, 0
	global_load_dwordx4 v[124:127], v129, s[36:37]
	global_load_dwordx4 v[120:123], v129, s[36:37] offset:64
	global_load_dwordx4 v[116:119], v129, s[36:37] offset:512
	global_load_dwordx4 v[112:115], v129, s[36:37] offset:576
	s_waitcnt vmcnt(12)
	v_pk_add_f32 v[182:183], v[108:109], v[182:183]
	v_pk_add_f32 v[184:185], v[110:111], v[184:185]
	v_pk_add_f32 v[186:187], v[104:105], v[186:187]
	v_pk_add_f32 v[188:189], v[106:107], v[188:189]
	v_pk_add_f32 v[190:191], v[100:101], v[190:191]
	v_pk_add_f32 v[192:193], v[102:103], v[192:193]
	v_pk_add_f32 v[194:195], v[96:97], v[194:195]
	v_pk_add_f32 v[196:197], v[98:99], v[196:197]
	s_add_u32 s36, s16, 0x90000
	s_addc_u32 s37, s17, 0
	global_load_dwordx4 v[108:111], v129, s[36:37]
	global_load_dwordx4 v[104:107], v129, s[36:37] offset:64
	global_load_dwordx4 v[100:103], v129, s[36:37] offset:512
	global_load_dwordx4 v[96:99], v129, s[36:37] offset:576
	s_waitcnt vmcnt(12)
	v_pk_add_f32 v[198:199], v[92:93], v[198:199]
	v_pk_add_f32 v[200:201], v[94:95], v[200:201]
	v_pk_add_f32 v[202:203], v[88:89], v[202:203]
	v_pk_add_f32 v[204:205], v[90:91], v[204:205]
	v_pk_add_f32 v[206:207], v[84:85], v[206:207]
	v_pk_add_f32 v[208:209], v[86:87], v[208:209]
	v_pk_add_f32 v[210:211], v[80:81], v[210:211]
	v_pk_add_f32 v[212:213], v[82:83], v[212:213]
	s_add_u32 s36, s16, 0xa0000
	s_addc_u32 s37, s17, 0
	global_load_dwordx4 v[92:95], v129, s[36:37]
	global_load_dwordx4 v[88:91], v129, s[36:37] offset:64
	global_load_dwordx4 v[84:87], v129, s[36:37] offset:512
	global_load_dwordx4 v[80:83], v129, s[36:37] offset:576
	s_waitcnt vmcnt(12)
	v_pk_add_f32 v[162:163], v[76:77], v[162:163]
	v_pk_add_f32 v[164:165], v[78:79], v[164:165]
	v_pk_add_f32 v[214:215], v[72:73], v[214:215]
	v_pk_add_f32 v[216:217], v[74:75], v[216:217]
	v_pk_add_f32 v[136:137], v[68:69], v[136:137]
	v_pk_add_f32 v[138:139], v[70:71], v[138:139]
	v_pk_add_f32 v[140:141], v[64:65], v[140:141]
	v_pk_add_f32 v[142:143], v[66:67], v[142:143]
	s_add_u32 s36, s16, 0xb0000
	s_addc_u32 s37, s17, 0
	global_load_dwordx4 v[76:79], v129, s[36:37]
	global_load_dwordx4 v[72:75], v129, s[36:37] offset:64
	global_load_dwordx4 v[68:71], v129, s[36:37] offset:512
	global_load_dwordx4 v[64:67], v129, s[36:37] offset:576
	v_pk_mul_f32 v[166:167], v[146:147], v[146:147]
	v_pk_mul_f32 v[144:145], v[148:149], v[148:149]
	v_pk_fma_f32 v[166:167], v[150:151], v[150:151], v[166:167]
	v_pk_fma_f32 v[144:145], v[152:153], v[152:153], v[144:145]
	v_pk_fma_f32 v[166:167], v[154:155], v[154:155], v[166:167]
	v_pk_fma_f32 v[144:145], v[156:157], v[156:157], v[144:145]
	v_pk_fma_f32 v[166:167], v[158:159], v[158:159], v[166:167]
	v_pk_fma_f32 v[144:145], v[160:161], v[160:161], v[144:145]
	s_nop 0
	v_pk_add_f32 v[166:167], v[166:167], v[144:145]
	v_cvt_pk_bf16_f32 v146, v146, v147
	v_cvt_pk_bf16_f32 v147, v148, v149
	v_cvt_pk_bf16_f32 v148, v150, v151
	v_cvt_pk_bf16_f32 v149, v152, v153
	v_cvt_pk_bf16_f32 v154, v154, v155
	v_cvt_pk_bf16_f32 v155, v156, v157
	v_cvt_pk_bf16_f32 v156, v158, v159
	v_cvt_pk_bf16_f32 v157, v160, v161
	v_add_f32_e32 v218, v166, v167
	s_nop 0
	v_permlane16_swap_b32_e32 v146, v148
	v_permlane16_swap_b32_e32 v147, v149
	v_permlane16_swap_b32_e32 v154, v156
	v_permlane16_swap_b32_e32 v155, v157
	global_store_dwordx4 v131, v[146:149], s[18:19] sc1
	global_store_dwordx4 v131, v[154:157], s[18:19] offset:256 sc1
	v_mov_b32_e32 v219, v218
	s_nop 1
	v_permlane16_swap_b32_e32 v219, v218
	v_add_f32_e32 v218, v218, v219
	v_mov_b32_e32 v219, v218
	s_nop 1
; DI u32x2 pk4(f32x4 v) { u32x2 r; r.x = pk2(v[0], v[1]); r.y = pk2(v[2], v[3]); return r; }
;     DI void operator()(const AccT& acc, const Unit& u, int wr, int wc, int fr, int fq, LAS unsigned char*) const {
;     ...
;                 for (int bj = 0; bj < 2; ++bj)
; #pragma unroll
;                     for (int n = 0; n < 2; ++n) {
;                         const int c = bj * 128 + n * 16;
;                         const f32x4 o = *(const f32x4*)(xr + c) + acc[ai][bj][m][n];
;                         *(u32x2*)(brow + c) = pk4(o);
;                         ss += (o[0] * o[0] + o[1] * o[1]) + (o[2] * o[2] + o[3] * o[3]);
;                     }
;                 ss += __shfl_xor(ss, 16); ss += __shfl_xor(ss, 32);
;                 if (fq == 0) unsafeAtomicAdd(sumsq + row, ss);
	v_permlane32_swap_b32_e32 v219, v218
	v_add_f32_e32 v218, v218, v219
	s_and_saveexec_b64 s[0:1], s[40:41]
	global_atomic_add_f32 v130, v218, s[58:59]
	s_mov_b64 exec, s[0:1]
	v_pk_mul_f32 v[166:167], v[182:183], v[182:183]
	v_pk_mul_f32 v[144:145], v[184:185], v[184:185]
	v_pk_fma_f32 v[166:167], v[186:187], v[186:187], v[166:167]
	v_pk_fma_f32 v[144:145], v[188:189], v[188:189], v[144:145]
	v_pk_fma_f32 v[166:167], v[190:191], v[190:191], v[166:167]
	v_pk_fma_f32 v[144:145], v[192:193], v[192:193], v[144:145]
	v_pk_fma_f32 v[166:167], v[194:195], v[194:195], v[166:167]
	v_pk_fma_f32 v[144:145], v[196:197], v[196:197], v[144:145]
	s_nop 0
	v_pk_add_f32 v[166:167], v[166:167], v[144:145]
	s_add_u32 s48, s18, 0x8000
	s_addc_u32 s49, s19, 0
	v_cvt_pk_bf16_f32 v182, v182, v183
	v_cvt_pk_bf16_f32 v183, v184, v185
	v_cvt_pk_bf16_f32 v184, v186, v187
	v_cvt_pk_bf16_f32 v185, v188, v189
	v_cvt_pk_bf16_f32 v190, v190, v191
	v_cvt_pk_bf16_f32 v191, v192, v193
	v_cvt_pk_bf16_f32 v192, v194, v195
	v_cvt_pk_bf16_f32 v193, v196, v197
	v_add_f32_e32 v218, v166, v167
	s_nop 0
	v_permlane16_swap_b32_e32 v182, v184
	v_permlane16_swap_b32_e32 v183, v185
	v_permlane16_swap_b32_e32 v190, v192
	v_permlane16_swap_b32_e32 v191, v193
	global_store_dwordx4 v131, v[182:185], s[48:49] sc1
	global_store_dwordx4 v131, v[190:193], s[48:49] offset:256 sc1
	v_mov_b32_e32 v219, v218
	s_nop 1
	v_permlane16_swap_b32_e32 v219, v218
	v_add_f32_e32 v218, v218, v219
	v_mov_b32_e32 v219, v218
	s_nop 1
	v_permlane32_swap_b32_e32 v219, v218
	v_add_f32_e32 v218, v218, v219
	s_and_saveexec_b64 s[0:1], s[40:41]
	global_atomic_add_f32 v130, v218, s[58:59] offset:64
	s_mov_b64 exec, s[0:1]
	v_pk_mul_f32 v[166:167], v[198:199], v[198:199]
	v_pk_mul_f32 v[144:145], v[200:201], v[200:201]
	v_pk_fma_f32 v[166:167], v[202:203], v[202:203], v[166:167]
	v_pk_fma_f32 v[144:145], v[204:205], v[204:205], v[144:145]
	v_pk_fma_f32 v[166:167], v[206:207], v[206:207], v[166:167]
	v_pk_fma_f32 v[144:145], v[208:209], v[208:209], v[144:145]
	v_pk_fma_f32 v[166:167], v[210:211], v[210:211], v[166:167]
	v_pk_fma_f32 v[144:145], v[212:213], v[212:213], v[144:145]
	s_nop 0
	v_pk_add_f32 v[166:167], v[166:167], v[144:145]
	s_add_u32 s48, s18, 0x10000
	s_addc_u32 s49, s19, 0
	v_cvt_pk_bf16_f32 v198, v198, v199
	v_cvt_pk_bf16_f32 v199, v200, v201
	v_cvt_pk_bf16_f32 v200, v202, v203
	v_cvt_pk_bf16_f32 v201, v204, v205
	v_cvt_pk_bf16_f32 v206, v206, v207
	v_cvt_pk_bf16_f32 v207, v208, v209
	v_cvt_pk_bf16_f32 v208, v210, v211
	v_cvt_pk_bf16_f32 v209, v212, v213
	v_add_f32_e32 v218, v166, v167
	s_nop 0
	v_permlane16_swap_b32_e32 v198, v200
	v_permlane16_swap_b32_e32 v199, v201
	v_permlane16_swap_b32_e32 v206, v208
	v_permlane16_swap_b32_e32 v207, v209
	global_store_dwordx4 v131, v[198:201], s[48:49] sc1
	global_store_dwordx4 v131, v[206:209], s[48:49] offset:256 sc1
	v_mov_b32_e32 v219, v218
	s_nop 1
	v_permlane16_swap_b32_e32 v219, v218
	v_add_f32_e32 v218, v218, v219
	v_mov_b32_e32 v219, v218
	s_nop 1
	v_permlane32_swap_b32_e32 v219, v218
	v_add_f32_e32 v218, v218, v219
	s_and_saveexec_b64 s[0:1], s[40:41]
	global_atomic_add_f32 v130, v218, s[58:59] offset:128
	s_mov_b64 exec, s[0:1]
	v_pk_mul_f32 v[166:167], v[162:163], v[162:163]
	v_pk_mul_f32 v[144:145], v[164:165], v[164:165]
	v_pk_fma_f32 v[166:167], v[214:215], v[214:215], v[166:167]
	v_pk_fma_f32 v[144:145], v[216:217], v[216:217], v[144:145]
	v_pk_fma_f32 v[166:167], v[136:137], v[136:137], v[166:167]
	v_pk_fma_f32 v[144:145], v[138:139], v[138:139], v[144:145]
	v_pk_fma_f32 v[166:167], v[140:141], v[140:141], v[166:167]
	v_pk_fma_f32 v[144:145], v[142:143], v[142:143], v[144:145]
	s_nop 0
	v_pk_add_f32 v[166:167], v[166:167], v[144:145]
	s_add_u32 s48, s18, 0x18000
	s_addc_u32 s49, s19, 0
	v_cvt_pk_bf16_f32 v162, v162, v163
	v_cvt_pk_bf16_f32 v163, v164, v165
	v_cvt_pk_bf16_f32 v164, v214, v215
	v_cvt_pk_bf16_f32 v165, v216, v217
	v_cvt_pk_bf16_f32 v136, v136, v137
	v_cvt_pk_bf16_f32 v137, v138, v139
	v_cvt_pk_bf16_f32 v138, v140, v141
	v_cvt_pk_bf16_f32 v139, v142, v143
	v_add_f32_e32 v218, v166, v167
	s_nop 0
	v_permlane16_swap_b32_e32 v162, v164
	v_permlane16_swap_b32_e32 v163, v165
	v_permlane16_swap_b32_e32 v136, v138
	v_permlane16_swap_b32_e32 v137, v139
	global_store_dwordx4 v131, v[162:165], s[48:49] sc1
	global_store_dwordx4 v131, v[136:139], s[48:49] offset:256 sc1
	v_mov_b32_e32 v219, v218
	s_nop 1
	v_permlane16_swap_b32_e32 v219, v218
	v_add_f32_e32 v218, v218, v219
	v_mov_b32_e32 v219, v218
	s_nop 1
	v_permlane32_swap_b32_e32 v219, v218
	v_add_f32_e32 v218, v218, v219
	s_and_saveexec_b64 s[0:1], s[40:41]
	global_atomic_add_f32 v130, v218, s[58:59] offset:192
	s_mov_b64 exec, s[0:1]
	s_waitcnt vmcnt(24)
	v_pk_add_f32 v[124:125], v[60:61], v[124:125]
	v_pk_add_f32 v[126:127], v[62:63], v[126:127]
	v_pk_add_f32 v[120:121], v[56:57], v[120:121]
	v_pk_add_f32 v[122:123], v[58:59], v[122:123]
	v_pk_add_f32 v[116:117], v[52:53], v[116:117]
	v_pk_add_f32 v[118:119], v[54:55], v[118:119]
	v_pk_add_f32 v[112:113], v[48:49], v[112:113]
	v_pk_add_f32 v[114:115], v[50:51], v[114:115]
	v_pk_mul_f32 v[166:167], v[124:125], v[124:125]
	v_pk_mul_f32 v[144:145], v[126:127], v[126:127]
	v_pk_fma_f32 v[166:167], v[120:121], v[120:121], v[166:167]
	v_pk_fma_f32 v[144:145], v[122:123], v[122:123], v[144:145]
	v_pk_fma_f32 v[166:167], v[116:117], v[116:117], v[166:167]
	v_pk_fma_f32 v[144:145], v[118:119], v[118:119], v[144:145]
	v_pk_fma_f32 v[166:167], v[112:113], v[112:113], v[166:167]
	v_pk_fma_f32 v[144:145], v[114:115], v[114:115], v[144:145]
	s_nop 0
	v_pk_add_f32 v[166:167], v[166:167], v[144:145]
	s_add_u32 s48, s18, 0x40000
	s_addc_u32 s49, s19, 0
	v_cvt_pk_bf16_f32 v124, v124, v125
	v_cvt_pk_bf16_f32 v125, v126, v127
	v_cvt_pk_bf16_f32 v126, v120, v121
	v_cvt_pk_bf16_f32 v127, v122, v123
	v_cvt_pk_bf16_f32 v116, v116, v117
	v_cvt_pk_bf16_f32 v117, v118, v119
	v_cvt_pk_bf16_f32 v118, v112, v113
	v_cvt_pk_bf16_f32 v119, v114, v115
	v_add_f32_e32 v218, v166, v167
	s_nop 0
	v_permlane16_swap_b32_e32 v124, v126
	v_permlane16_swap_b32_e32 v125, v127
	v_permlane16_swap_b32_e32 v116, v118
	v_permlane16_swap_b32_e32 v117, v119
	global_store_dwordx4 v131, v[124:127], s[48:49] sc1
	global_store_dwordx4 v131, v[116:119], s[48:49] offset:256 sc1
	v_mov_b32_e32 v219, v218
	s_nop 1
	v_permlane16_swap_b32_e32 v219, v218
	v_add_f32_e32 v218, v218, v219
	v_mov_b32_e32 v219, v218
	s_nop 1
	v_permlane32_swap_b32_e32 v219, v218
	v_add_f32_e32 v218, v218, v219
	s_and_saveexec_b64 s[0:1], s[40:41]
	global_atomic_add_f32 v130, v218, s[58:59] offset:512
	s_mov_b64 exec, s[0:1]
	s_waitcnt vmcnt(23)
; DI u32x2 pk4(f32x4 v) { u32x2 r; r.x = pk2(v[0], v[1]); r.y = pk2(v[2], v[3]); return r; }
;     DI void operator()(const AccT& acc, const Unit& u, int wr, int wc, int fr, int fq, LAS unsigned char*) const {
;     ...
;                 for (int bj = 0; bj < 2; ++bj)
; #pragma unroll
;                     for (int n = 0; n < 2; ++n) {
;                         const int c = bj * 128 + n * 16;
;                         const f32x4 o = *(const f32x4*)(xr + c) + acc[ai][bj][m][n];
;                         *(u32x2*)(brow + c) = pk4(o);
;                         ss += (o[0] * o[0] + o[1] * o[1]) + (o[2] * o[2] + o[3] * o[3]);
;                     }
;                 ss += __shfl_xor(ss, 16); ss += __shfl_xor(ss, 32);
;                 if (fq == 0) unsafeAtomicAdd(sumsq + row, ss);
	v_pk_add_f32 v[108:109], v[44:45], v[108:109]
	v_pk_add_f32 v[110:111], v[46:47], v[110:111]
	v_pk_add_f32 v[104:105], v[40:41], v[104:105]
	v_pk_add_f32 v[106:107], v[42:43], v[106:107]
	v_pk_add_f32 v[100:101], v[36:37], v[100:101]
	v_pk_add_f32 v[102:103], v[38:39], v[102:103]
	v_pk_add_f32 v[96:97], v[32:33], v[96:97]
	v_pk_add_f32 v[98:99], v[34:35], v[98:99]
	v_pk_mul_f32 v[166:167], v[108:109], v[108:109]
	v_pk_mul_f32 v[144:145], v[110:111], v[110:111]
	v_pk_fma_f32 v[166:167], v[104:105], v[104:105], v[166:167]
	v_pk_fma_f32 v[144:145], v[106:107], v[106:107], v[144:145]
	v_pk_fma_f32 v[166:167], v[100:101], v[100:101], v[166:167]
	v_pk_fma_f32 v[144:145], v[102:103], v[102:103], v[144:145]
	v_pk_fma_f32 v[166:167], v[96:97], v[96:97], v[166:167]
	v_pk_fma_f32 v[144:145], v[98:99], v[98:99], v[144:145]
	s_nop 0
	v_pk_add_f32 v[166:167], v[166:167], v[144:145]
	s_add_u32 s48, s18, 0x48000
	s_addc_u32 s49, s19, 0
	v_cvt_pk_bf16_f32 v108, v108, v109
	v_cvt_pk_bf16_f32 v109, v110, v111
	v_cvt_pk_bf16_f32 v110, v104, v105
	v_cvt_pk_bf16_f32 v111, v106, v107
	v_cvt_pk_bf16_f32 v100, v100, v101
	v_cvt_pk_bf16_f32 v101, v102, v103
	v_cvt_pk_bf16_f32 v102, v96, v97
	v_cvt_pk_bf16_f32 v103, v98, v99
	v_add_f32_e32 v218, v166, v167
	s_nop 0
	v_permlane16_swap_b32_e32 v108, v110
	v_permlane16_swap_b32_e32 v109, v111
	v_permlane16_swap_b32_e32 v100, v102
	v_permlane16_swap_b32_e32 v101, v103
	global_store_dwordx4 v131, v[108:111], s[48:49] sc1
	global_store_dwordx4 v131, v[100:103], s[48:49] offset:256 sc1
	v_mov_b32_e32 v219, v218
	s_nop 1
	v_permlane16_swap_b32_e32 v219, v218
	v_add_f32_e32 v218, v218, v219
	v_mov_b32_e32 v219, v218
	s_nop 1
	v_permlane32_swap_b32_e32 v219, v218
	v_add_f32_e32 v218, v218, v219
	s_and_saveexec_b64 s[0:1], s[40:41]
	global_atomic_add_f32 v130, v218, s[58:59] offset:576
	s_mov_b64 exec, s[0:1]
	s_waitcnt vmcnt(22)
	v_pk_add_f32 v[92:93], v[28:29], v[92:93]
	v_pk_add_f32 v[94:95], v[30:31], v[94:95]
	v_pk_add_f32 v[88:89], v[24:25], v[88:89]
	v_pk_add_f32 v[90:91], v[26:27], v[90:91]
	v_pk_add_f32 v[84:85], v[20:21], v[84:85]
	v_pk_add_f32 v[86:87], v[22:23], v[86:87]
	v_pk_add_f32 v[80:81], v[16:17], v[80:81]
	v_pk_add_f32 v[82:83], v[18:19], v[82:83]
	v_pk_mul_f32 v[166:167], v[92:93], v[92:93]
	v_pk_mul_f32 v[144:145], v[94:95], v[94:95]
	v_pk_fma_f32 v[166:167], v[88:89], v[88:89], v[166:167]
	v_pk_fma_f32 v[144:145], v[90:91], v[90:91], v[144:145]
	v_pk_fma_f32 v[166:167], v[84:85], v[84:85], v[166:167]
	v_pk_fma_f32 v[144:145], v[86:87], v[86:87], v[144:145]
	v_pk_fma_f32 v[166:167], v[80:81], v[80:81], v[166:167]
	v_pk_fma_f32 v[144:145], v[82:83], v[82:83], v[144:145]
	s_nop 0
	v_pk_add_f32 v[166:167], v[166:167], v[144:145]
	s_add_u32 s48, s18, 0x50000
	s_addc_u32 s49, s19, 0
	v_cvt_pk_bf16_f32 v92, v92, v93
	v_cvt_pk_bf16_f32 v93, v94, v95
	v_cvt_pk_bf16_f32 v94, v88, v89
	v_cvt_pk_bf16_f32 v95, v90, v91
	v_cvt_pk_bf16_f32 v84, v84, v85
	v_cvt_pk_bf16_f32 v85, v86, v87
	v_cvt_pk_bf16_f32 v86, v80, v81
	v_cvt_pk_bf16_f32 v87, v82, v83
	v_add_f32_e32 v218, v166, v167
	s_nop 0
	v_permlane16_swap_b32_e32 v92, v94
	v_permlane16_swap_b32_e32 v93, v95
	v_permlane16_swap_b32_e32 v84, v86
	v_permlane16_swap_b32_e32 v85, v87
	global_store_dwordx4 v131, v[92:95], s[48:49] sc1
	global_store_dwordx4 v131, v[84:87], s[48:49] offset:256 sc1
	v_mov_b32_e32 v219, v218
	s_nop 1
	v_permlane16_swap_b32_e32 v219, v218
	v_add_f32_e32 v218, v218, v219
	v_mov_b32_e32 v219, v218
	s_nop 1
	v_permlane32_swap_b32_e32 v219, v218
	v_add_f32_e32 v218, v218, v219
	s_and_saveexec_b64 s[0:1], s[40:41]
	global_atomic_add_f32 v130, v218, s[58:59] offset:640
	s_mov_b64 exec, s[0:1]
	s_waitcnt vmcnt(21)
	v_pk_add_f32 v[76:77], v[12:13], v[76:77]
	v_pk_add_f32 v[78:79], v[14:15], v[78:79]
	v_pk_add_f32 v[72:73], v[8:9], v[72:73]
	v_pk_add_f32 v[74:75], v[10:11], v[74:75]
	v_pk_add_f32 v[68:69], v[4:5], v[68:69]
	v_pk_add_f32 v[70:71], v[6:7], v[70:71]
	v_pk_add_f32 v[64:65], v[0:1], v[64:65]
	v_pk_add_f32 v[66:67], v[2:3], v[66:67]
	v_pk_mul_f32 v[166:167], v[76:77], v[76:77]
	v_pk_mul_f32 v[144:145], v[78:79], v[78:79]
	v_pk_fma_f32 v[166:167], v[72:73], v[72:73], v[166:167]
	v_pk_fma_f32 v[144:145], v[74:75], v[74:75], v[144:145]
	v_pk_fma_f32 v[166:167], v[68:69], v[68:69], v[166:167]
	v_pk_fma_f32 v[144:145], v[70:71], v[70:71], v[144:145]
	v_pk_fma_f32 v[166:167], v[64:65], v[64:65], v[166:167]
	v_pk_fma_f32 v[144:145], v[66:67], v[66:67], v[144:145]
	s_nop 0
	v_pk_add_f32 v[166:167], v[166:167], v[144:145]
	s_add_u32 s48, s18, 0x58000
	s_addc_u32 s49, s19, 0
	v_cvt_pk_bf16_f32 v76, v76, v77
	v_cvt_pk_bf16_f32 v77, v78, v79
	v_cvt_pk_bf16_f32 v78, v72, v73
	v_cvt_pk_bf16_f32 v79, v74, v75
	v_cvt_pk_bf16_f32 v68, v68, v69
	v_cvt_pk_bf16_f32 v69, v70, v71
	v_cvt_pk_bf16_f32 v70, v64, v65
	v_cvt_pk_bf16_f32 v71, v66, v67
	v_add_f32_e32 v218, v166, v167
	s_nop 0
	v_permlane16_swap_b32_e32 v76, v78
	v_permlane16_swap_b32_e32 v77, v79
	v_permlane16_swap_b32_e32 v68, v70
	v_permlane16_swap_b32_e32 v69, v71
	global_store_dwordx4 v131, v[76:79], s[48:49] sc1
	global_store_dwordx4 v131, v[68:71], s[48:49] offset:256 sc1
	v_mov_b32_e32 v219, v218
	s_nop 1
	v_permlane16_swap_b32_e32 v219, v218
	v_add_f32_e32 v218, v218, v219
	v_mov_b32_e32 v219, v218
	s_nop 1
	v_permlane32_swap_b32_e32 v219, v218
	v_add_f32_e32 v218, v218, v219
	s_and_saveexec_b64 s[0:1], s[40:41]
	global_atomic_add_f32 v130, v218, s[58:59] offset:704
	s_mov_b64 exec, s[0:1]
	s_cmp_eq_u32 s30, s28
	s_mov_b64 s[0:1], -1
	s_cbranch_scc1 .LBB0_955
